# mLSTM prompt loops: gate-prefix block moved before the chunk's first barrier, sfp/sip double buffered by chunk parity, second per-chunk barrier removed
# speedup vs baseline: 1.0126x; 1.0126x over previous
.LBB0_1143:
	s_or_b64 exec, exec, s[8:9]
	s_and_saveexec_b64 s[8:9], s[46:47]
	s_cbranch_execz .LBB0_1154
	v_mov_b32_e32 v65, 0
	v_mov_b32_e32 v64, 0xf149f2ca
	s_and_saveexec_b64 s[64:65], s[42:43]
	v_add_u32_e32 v64, 0x4000, v145
	ds_read2_b32 v[64:65], v64 offset0:128 offset1:144
	s_or_b64 exec, exec, s[64:65]
	s_waitcnt lgkmcnt(0)
	v_add_f32_dpp v66, v64, v65 row_shr:1 row_mask:0xf bank_mask:0xf bound_ctrl:1
	v_max_f32_e32 v67, v64, v64
	v_max_f32_e32 v66, v66, v67
	v_cndmask_b32_e64 v66, v64, v66, s[48:49]
	v_add_f32_dpp v67, v65, v65 row_shr:1 row_mask:0xf bank_mask:0xf bound_ctrl:1
	v_cndmask_b32_e64 v67, v65, v67, s[48:49]
	v_max_f32_e32 v69, v66, v66
	s_nop 0
	v_add_f32_dpp v68, v66, v67 row_shr:2 row_mask:0xf bank_mask:0xf bound_ctrl:1
	v_max_f32_e32 v68, v68, v69
	v_add_f32_dpp v69, v67, v67 row_shr:2 row_mask:0xf bank_mask:0xf bound_ctrl:1
	v_cndmask_b32_e64 v66, v66, v68, s[50:51]
	v_cndmask_b32_e64 v67, v67, v69, s[50:51]
	v_max_f32_e32 v69, v66, v66
	s_nop 0
	v_add_f32_dpp v68, v66, v67 row_shr:4 row_mask:0xf bank_mask:0xf bound_ctrl:1
	v_max_f32_e32 v68, v68, v69
	v_cndmask_b32_e64 v66, v66, v68, s[52:53]
	ds_read_b32 v68, v140 offset:35328
	v_add_f32_dpp v69, v67, v67 row_shr:4 row_mask:0xf bank_mask:0xf bound_ctrl:1
	v_cndmask_b32_e64 v67, v67, v69, s[52:53]
	v_max_f32_e32 v66, v66, v66
	s_waitcnt lgkmcnt(0)
	v_add_f32_e32 v67, v68, v67
	v_max_f32_e32 v66, v67, v66
	v_mov_b32_e32 v67, 0
	v_sub_f32_e32 v64, v64, v66
	v_mul_f32_e32 v64, 0x3fb8aa3b, v64
	v_mov_b32_dpp v67, v66 row_shr:1 row_mask:0xf bank_mask:0xf
	v_cndmask_b32_e64 v67, v67, v68, s[38:39]
	v_add_f32_e32 v65, v65, v67
	v_sub_f32_e32 v65, v65, v66
	v_mul_f32_e32 v65, 0x3fb8aa3b, v65
	v_exp_f32_e32 v65, v65
	v_exp_f32_e32 v64, v64
	v_add_u32_e32 v67, 0x8800, v145
	ds_write2_b32 v67, v65, v64 offset0:64 offset1:80
	ds_write_b32 v145, v66 offset:35200
	s_and_b64 exec, exec, s[54:55]
	ds_write_b32 v140, v66 offset:35328

.LBB0_1149:
	s_cmp_lg_u32 s85, 0
	s_cselect_b64 s[8:9], -1, 0
	s_and_b64 s[22:23], s[56:57], s[8:9]
	s_and_saveexec_b64 s[8:9], s[22:23]
	s_cbranch_execz .LBB0_1156
	ds_read_b32 v66, v145 offset:34560
	v_add3_u32 v64, v149, s85, -8
	v_ashrrev_i32_e32 v65, 31, v64
	v_lshlrev_b64 v[64:65], 12, v[64:65]
	v_lshl_add_u64 v[64:65], v[152:153], 0, v[64:65]
	s_waitcnt lgkmcnt(0)
	global_store_dword v[64:65], v66, off
.LBB0_1156:
	s_or_b64 exec, exec, s[8:9]
	s_waitcnt lgkmcnt(0)
	v_mov_b32_e32 v196, v88
	v_mov_b32_e32 v197, v89
	v_mov_b32_e32 v198, v90
	v_mov_b32_e32 v199, v100
	v_mov_b32_e32 v200, v91
	v_mov_b32_e32 v201, v101
	v_mov_b32_e32 v202, v102
	v_mov_b32_e32 v203, v104
	v_mov_b32_e32 v204, v103
	v_mov_b32_e32 v205, v105
	v_mov_b32_e32 v206, v106
	v_mov_b32_e32 v207, v109
	v_mov_b32_e32 v208, v107
	v_mov_b32_e32 v209, v110
	v_mov_b32_e32 v210, v108
	v_mov_b32_e32 v211, v111
	v_mov_b32_e32 v214, 0
	v_mov_b32_e32 v215, 0
	ds_read_b128 v[80:83], v194 offset:8192
	ds_read_b128 v[84:87], v194 offset:8448
	ds_read_b128 v[88:91], v194 offset:8704
	ds_read_b128 v[92:95], v194 offset:8960
	ds_read_b32 v134, v140 offset:35136
	ds_read_b32 v135, v190 offset:16384
	ds_read_b32 v132, v140 offset:35072
	ds_read_b128 v[64:67], v194
	ds_read_b128 v[68:71], v194 offset:256
	ds_read_b128 v[72:75], v194 offset:512
	ds_read_b128 v[76:79], v194 offset:768
	ds_read_b128 v[112:115], v194 offset:9216
	ds_read_b128 v[116:119], v194 offset:9472
	ds_read_b128 v[120:123], v194 offset:9728
	ds_read_b128 v[124:127], v194 offset:9984
	ds_read_b32 v156, v140 offset:35140
	ds_read_b32 v157, v190 offset:16448
	ds_read_b32 v154, v140 offset:35076
	ds_read_b128 v[96:99], v194 offset:1024
	ds_read_b128 v[100:103], v194 offset:1280
	ds_read_b128 v[104:107], v194 offset:1536
	ds_read_b128 v[108:111], v194 offset:1792
	s_waitcnt lgkmcnt(15)
	v_mul_f32_e32 v133, v134, v135
	v_pk_mul_f32 v[80:81], v[80:81], v[132:133] op_sel:[0,1] op_sel_hi:[1,1]
	v_pk_mul_f32 v[82:83], v[82:83], v[132:133] op_sel:[0,1] op_sel_hi:[1,1]
	v_pk_mul_f32 v[84:85], v[84:85], v[132:133] op_sel:[0,1] op_sel_hi:[1,1]
	v_pk_mul_f32 v[86:87], v[86:87], v[132:133] op_sel:[0,1] op_sel_hi:[1,1]
	v_pk_mul_f32 v[88:89], v[88:89], v[132:133] op_sel:[0,1] op_sel_hi:[1,1]
	v_pk_mul_f32 v[90:91], v[90:91], v[132:133] op_sel:[0,1] op_sel_hi:[1,1]
	v_pk_mul_f32 v[92:93], v[92:93], v[132:133] op_sel:[0,1] op_sel_hi:[1,1]
	v_pk_mul_f32 v[94:95], v[94:95], v[132:133] op_sel:[0,1] op_sel_hi:[1,1]
	v_pk_fma_f32 v[196:197], v[132:133], v[196:197], v[80:81] op_sel_hi:[0,1,1]
	v_pk_fma_f32 v[198:199], v[132:133], v[198:199], v[82:83] op_sel_hi:[0,1,1]
	v_pk_fma_f32 v[200:201], v[132:133], v[200:201], v[84:85] op_sel_hi:[0,1,1]
	v_pk_fma_f32 v[202:203], v[132:133], v[202:203], v[86:87] op_sel_hi:[0,1,1]
	v_pk_fma_f32 v[204:205], v[132:133], v[204:205], v[88:89] op_sel_hi:[0,1,1]
	v_pk_fma_f32 v[206:207], v[132:133], v[206:207], v[90:91] op_sel_hi:[0,1,1]
	v_pk_fma_f32 v[208:209], v[132:133], v[208:209], v[92:93] op_sel_hi:[0,1,1]
	v_pk_fma_f32 v[210:211], v[132:133], v[210:211], v[94:95] op_sel_hi:[0,1,1]
	s_waitcnt lgkmcnt(14)
	v_pk_fma_f32 v[128:129], v[64:65], v[196:197], v[214:215]
	v_pk_fma_f32 v[130:131], v[66:67], v[198:199], v[214:215]
	s_waitcnt lgkmcnt(13)
	v_pk_fma_f32 v[128:129], v[68:69], v[200:201], v[128:129]
	v_pk_fma_f32 v[130:131], v[70:71], v[202:203], v[130:131]
	s_waitcnt lgkmcnt(12)
	v_pk_fma_f32 v[128:129], v[72:73], v[204:205], v[128:129]
	v_pk_fma_f32 v[130:131], v[74:75], v[206:207], v[130:131]
	s_waitcnt lgkmcnt(11)
	v_pk_fma_f32 v[128:129], v[76:77], v[208:209], v[128:129]
	v_pk_fma_f32 v[130:131], v[78:79], v[210:211], v[130:131]
	v_add_f32_e32 v128, v128, v129
	v_add_f32_e32 v130, v130, v131
	v_add_f32_e32 v212, v128, v130
	ds_read_b128 v[80:83], v194 offset:10240
	ds_read_b128 v[84:87], v194 offset:10496
	ds_read_b128 v[88:91], v194 offset:10752
	ds_read_b128 v[92:95], v194 offset:11008
	ds_read_b32 v134, v140 offset:35144
	ds_read_b32 v135, v190 offset:16512
	ds_read_b32 v132, v140 offset:35080
	ds_read_b128 v[64:67], v194 offset:2048
	ds_read_b128 v[68:71], v194 offset:2304
	ds_read_b128 v[72:75], v194 offset:2560
	ds_read_b128 v[76:79], v194 offset:2816
	s_waitcnt lgkmcnt(15)
	v_mul_f32_e32 v155, v156, v157
	v_pk_mul_f32 v[112:113], v[112:113], v[154:155] op_sel:[0,1] op_sel_hi:[1,1]
	v_add_f32_dpp v212, v212, v212 row_ror:8 row_mask:0xf bank_mask:0xf bound_ctrl:1
	v_pk_mul_f32 v[114:115], v[114:115], v[154:155] op_sel:[0,1] op_sel_hi:[1,1]
	v_pk_mul_f32 v[116:117], v[116:117], v[154:155] op_sel:[0,1] op_sel_hi:[1,1]
	v_add_f32_dpp v212, v212, v212 row_ror:4 row_mask:0xf bank_mask:0xf bound_ctrl:1
	v_pk_mul_f32 v[118:119], v[118:119], v[154:155] op_sel:[0,1] op_sel_hi:[1,1]
	v_pk_mul_f32 v[120:121], v[120:121], v[154:155] op_sel:[0,1] op_sel_hi:[1,1]
	v_add_f32_dpp v212, v212, v212 row_ror:2 row_mask:0xf bank_mask:0xf bound_ctrl:1
	v_pk_mul_f32 v[122:123], v[122:123], v[154:155] op_sel:[0,1] op_sel_hi:[1,1]
	v_pk_mul_f32 v[124:125], v[124:125], v[154:155] op_sel:[0,1] op_sel_hi:[1,1]
	v_add_f32_dpp v212, v212, v212 row_ror:1 row_mask:0xf bank_mask:0xf bound_ctrl:1
	v_pk_mul_f32 v[126:127], v[126:127], v[154:155] op_sel:[0,1] op_sel_hi:[1,1]
	v_pk_fma_f32 v[196:197], v[154:155], v[196:197], v[112:113] op_sel_hi:[0,1,1]
	s_and_saveexec_b64 s[8:9], s[44:45]
	ds_write_b32 v190, v212 offset:34048
	s_mov_b64 exec, s[8:9]
	v_pk_fma_f32 v[198:199], v[154:155], v[198:199], v[114:115] op_sel_hi:[0,1,1]
	v_pk_fma_f32 v[200:201], v[154:155], v[200:201], v[116:117] op_sel_hi:[0,1,1]
	v_pk_fma_f32 v[202:203], v[154:155], v[202:203], v[118:119] op_sel_hi:[0,1,1]
	v_pk_fma_f32 v[204:205], v[154:155], v[204:205], v[120:121] op_sel_hi:[0,1,1]
	v_pk_fma_f32 v[206:207], v[154:155], v[206:207], v[122:123] op_sel_hi:[0,1,1]
	v_pk_fma_f32 v[208:209], v[154:155], v[208:209], v[124:125] op_sel_hi:[0,1,1]
	v_pk_fma_f32 v[210:211], v[154:155], v[210:211], v[126:127] op_sel_hi:[0,1,1]
	s_waitcnt lgkmcnt(15)
	v_pk_fma_f32 v[128:129], v[96:97], v[196:197], v[214:215]
	v_pk_fma_f32 v[130:131], v[98:99], v[198:199], v[214:215]
	s_waitcnt lgkmcnt(14)
	v_pk_fma_f32 v[128:129], v[100:101], v[200:201], v[128:129]
	v_pk_fma_f32 v[130:131], v[102:103], v[202:203], v[130:131]
	s_waitcnt lgkmcnt(13)
	v_pk_fma_f32 v[128:129], v[104:105], v[204:205], v[128:129]
	v_pk_fma_f32 v[130:131], v[106:107], v[206:207], v[130:131]
	s_waitcnt lgkmcnt(12)
	v_pk_fma_f32 v[128:129], v[108:109], v[208:209], v[128:129]
	v_pk_fma_f32 v[130:131], v[110:111], v[210:211], v[130:131]
	v_add_f32_e32 v128, v128, v129
	v_add_f32_e32 v130, v130, v131
	v_add_f32_e32 v213, v128, v130
	ds_read_b128 v[112:115], v194 offset:11264
	ds_read_b128 v[116:119], v194 offset:11520
	ds_read_b128 v[120:123], v194 offset:11776
	ds_read_b128 v[124:127], v194 offset:12032
	ds_read_b32 v156, v140 offset:35148
	ds_read_b32 v157, v190 offset:16576
	ds_read_b32 v154, v140 offset:35084
	ds_read_b128 v[96:99], v194 offset:3072
	ds_read_b128 v[100:103], v194 offset:3328
	ds_read_b128 v[104:107], v194 offset:3584
	ds_read_b128 v[108:111], v194 offset:3840
	s_waitcnt lgkmcnt(15)
	v_mul_f32_e32 v133, v134, v135
	v_pk_mul_f32 v[80:81], v[80:81], v[132:133] op_sel:[0,1] op_sel_hi:[1,1]
	v_add_f32_dpp v213, v213, v213 row_ror:8 row_mask:0xf bank_mask:0xf bound_ctrl:1
	v_pk_mul_f32 v[82:83], v[82:83], v[132:133] op_sel:[0,1] op_sel_hi:[1,1]
	v_pk_mul_f32 v[84:85], v[84:85], v[132:133] op_sel:[0,1] op_sel_hi:[1,1]
	v_add_f32_dpp v213, v213, v213 row_ror:4 row_mask:0xf bank_mask:0xf bound_ctrl:1
	v_pk_mul_f32 v[86:87], v[86:87], v[132:133] op_sel:[0,1] op_sel_hi:[1,1]
	v_pk_mul_f32 v[88:89], v[88:89], v[132:133] op_sel:[0,1] op_sel_hi:[1,1]
	v_add_f32_dpp v213, v213, v213 row_ror:2 row_mask:0xf bank_mask:0xf bound_ctrl:1
	v_pk_mul_f32 v[90:91], v[90:91], v[132:133] op_sel:[0,1] op_sel_hi:[1,1]
	v_pk_mul_f32 v[92:93], v[92:93], v[132:133] op_sel:[0,1] op_sel_hi:[1,1]
	v_add_f32_dpp v213, v213, v213 row_ror:1 row_mask:0xf bank_mask:0xf bound_ctrl:1
	v_pk_mul_f32 v[94:95], v[94:95], v[132:133] op_sel:[0,1] op_sel_hi:[1,1]
	v_pk_fma_f32 v[196:197], v[132:133], v[196:197], v[80:81] op_sel_hi:[0,1,1]
	s_and_saveexec_b64 s[8:9], s[44:45]
	ds_write_b32 v190, v213 offset:34112
	s_mov_b64 exec, s[8:9]
	v_pk_fma_f32 v[198:199], v[132:133], v[198:199], v[82:83] op_sel_hi:[0,1,1]
	v_pk_fma_f32 v[200:201], v[132:133], v[200:201], v[84:85] op_sel_hi:[0,1,1]
	v_pk_fma_f32 v[202:203], v[132:133], v[202:203], v[86:87] op_sel_hi:[0,1,1]
	v_pk_fma_f32 v[204:205], v[132:133], v[204:205], v[88:89] op_sel_hi:[0,1,1]
	v_pk_fma_f32 v[206:207], v[132:133], v[206:207], v[90:91] op_sel_hi:[0,1,1]
	v_pk_fma_f32 v[208:209], v[132:133], v[208:209], v[92:93] op_sel_hi:[0,1,1]
	v_pk_fma_f32 v[210:211], v[132:133], v[210:211], v[94:95] op_sel_hi:[0,1,1]
	s_waitcnt lgkmcnt(15)
	v_pk_fma_f32 v[128:129], v[64:65], v[196:197], v[214:215]
	v_pk_fma_f32 v[130:131], v[66:67], v[198:199], v[214:215]
	v_pk_fma_f32 v[128:129], v[68:69], v[200:201], v[128:129]
	v_pk_fma_f32 v[130:131], v[70:71], v[202:203], v[130:131]
	s_waitcnt lgkmcnt(14)
	v_pk_fma_f32 v[128:129], v[72:73], v[204:205], v[128:129]
	v_pk_fma_f32 v[130:131], v[74:75], v[206:207], v[130:131]
	s_waitcnt lgkmcnt(13)
	v_pk_fma_f32 v[128:129], v[76:77], v[208:209], v[128:129]
	v_pk_fma_f32 v[130:131], v[78:79], v[210:211], v[130:131]
	v_add_f32_e32 v128, v128, v129
	v_add_f32_e32 v130, v130, v131
	v_add_f32_e32 v212, v128, v130
	ds_read_b128 v[80:83], v194 offset:12288
	ds_read_b128 v[84:87], v194 offset:12544
	ds_read_b128 v[88:91], v194 offset:12800
	ds_read_b128 v[92:95], v194 offset:13056
	ds_read_b32 v134, v140 offset:35152
	ds_read_b32 v135, v190 offset:16640
	ds_read_b32 v132, v140 offset:35088
	ds_read_b128 v[64:67], v194 offset:4096
	ds_read_b128 v[68:71], v194 offset:4352
	ds_read_b128 v[72:75], v194 offset:4608
	ds_read_b128 v[76:79], v194 offset:4864
	s_waitcnt lgkmcnt(15)
	v_mul_f32_e32 v155, v156, v157
	v_pk_mul_f32 v[112:113], v[112:113], v[154:155] op_sel:[0,1] op_sel_hi:[1,1]
	v_add_f32_dpp v212, v212, v212 row_ror:8 row_mask:0xf bank_mask:0xf bound_ctrl:1
	v_pk_mul_f32 v[114:115], v[114:115], v[154:155] op_sel:[0,1] op_sel_hi:[1,1]
	v_pk_mul_f32 v[116:117], v[116:117], v[154:155] op_sel:[0,1] op_sel_hi:[1,1]
	v_add_f32_dpp v212, v212, v212 row_ror:4 row_mask:0xf bank_mask:0xf bound_ctrl:1
	v_pk_mul_f32 v[118:119], v[118:119], v[154:155] op_sel:[0,1] op_sel_hi:[1,1]
	v_pk_mul_f32 v[120:121], v[120:121], v[154:155] op_sel:[0,1] op_sel_hi:[1,1]
	v_add_f32_dpp v212, v212, v212 row_ror:2 row_mask:0xf bank_mask:0xf bound_ctrl:1
	v_pk_mul_f32 v[122:123], v[122:123], v[154:155] op_sel:[0,1] op_sel_hi:[1,1]
	v_pk_mul_f32 v[124:125], v[124:125], v[154:155] op_sel:[0,1] op_sel_hi:[1,1]
	v_add_f32_dpp v212, v212, v212 row_ror:1 row_mask:0xf bank_mask:0xf bound_ctrl:1
	v_pk_mul_f32 v[126:127], v[126:127], v[154:155] op_sel:[0,1] op_sel_hi:[1,1]
	v_pk_fma_f32 v[196:197], v[154:155], v[196:197], v[112:113] op_sel_hi:[0,1,1]
	s_and_saveexec_b64 s[8:9], s[44:45]
	ds_write_b32 v190, v212 offset:34176
	s_mov_b64 exec, s[8:9]
	v_pk_fma_f32 v[198:199], v[154:155], v[198:199], v[114:115] op_sel_hi:[0,1,1]
	v_pk_fma_f32 v[200:201], v[154:155], v[200:201], v[116:117] op_sel_hi:[0,1,1]
	v_pk_fma_f32 v[202:203], v[154:155], v[202:203], v[118:119] op_sel_hi:[0,1,1]
	v_pk_fma_f32 v[204:205], v[154:155], v[204:205], v[120:121] op_sel_hi:[0,1,1]
	v_pk_fma_f32 v[206:207], v[154:155], v[206:207], v[122:123] op_sel_hi:[0,1,1]
	v_pk_fma_f32 v[208:209], v[154:155], v[208:209], v[124:125] op_sel_hi:[0,1,1]
	v_pk_fma_f32 v[210:211], v[154:155], v[210:211], v[126:127] op_sel_hi:[0,1,1]
	s_waitcnt lgkmcnt(15)
	v_pk_fma_f32 v[128:129], v[96:97], v[196:197], v[214:215]
	v_pk_fma_f32 v[130:131], v[98:99], v[198:199], v[214:215]
	v_pk_fma_f32 v[128:129], v[100:101], v[200:201], v[128:129]
	v_pk_fma_f32 v[130:131], v[102:103], v[202:203], v[130:131]
	s_waitcnt lgkmcnt(14)
	v_pk_fma_f32 v[128:129], v[104:105], v[204:205], v[128:129]
	v_pk_fma_f32 v[130:131], v[106:107], v[206:207], v[130:131]
	s_waitcnt lgkmcnt(13)
	v_pk_fma_f32 v[128:129], v[108:109], v[208:209], v[128:129]
	v_pk_fma_f32 v[130:131], v[110:111], v[210:211], v[130:131]
	v_add_f32_e32 v128, v128, v129
	v_add_f32_e32 v130, v130, v131
	v_add_f32_e32 v213, v128, v130
	ds_read_b128 v[112:115], v194 offset:13312
	ds_read_b128 v[116:119], v194 offset:13568
	ds_read_b128 v[120:123], v194 offset:13824
	ds_read_b128 v[124:127], v194 offset:14080
	ds_read_b32 v156, v140 offset:35156
	ds_read_b32 v157, v190 offset:16704
	ds_read_b32 v154, v140 offset:35092
	ds_read_b128 v[96:99], v194 offset:5120
	ds_read_b128 v[100:103], v194 offset:5376
	ds_read_b128 v[104:107], v194 offset:5632
	ds_read_b128 v[108:111], v194 offset:5888
	s_waitcnt lgkmcnt(15)
	v_mul_f32_e32 v133, v134, v135
	v_pk_mul_f32 v[80:81], v[80:81], v[132:133] op_sel:[0,1] op_sel_hi:[1,1]
	v_add_f32_dpp v213, v213, v213 row_ror:8 row_mask:0xf bank_mask:0xf bound_ctrl:1
	v_pk_mul_f32 v[82:83], v[82:83], v[132:133] op_sel:[0,1] op_sel_hi:[1,1]
	v_pk_mul_f32 v[84:85], v[84:85], v[132:133] op_sel:[0,1] op_sel_hi:[1,1]
	v_add_f32_dpp v213, v213, v213 row_ror:4 row_mask:0xf bank_mask:0xf bound_ctrl:1
	v_pk_mul_f32 v[86:87], v[86:87], v[132:133] op_sel:[0,1] op_sel_hi:[1,1]
	v_pk_mul_f32 v[88:89], v[88:89], v[132:133] op_sel:[0,1] op_sel_hi:[1,1]
	v_add_f32_dpp v213, v213, v213 row_ror:2 row_mask:0xf bank_mask:0xf bound_ctrl:1
	v_pk_mul_f32 v[90:91], v[90:91], v[132:133] op_sel:[0,1] op_sel_hi:[1,1]
	v_pk_mul_f32 v[92:93], v[92:93], v[132:133] op_sel:[0,1] op_sel_hi:[1,1]
	v_add_f32_dpp v213, v213, v213 row_ror:1 row_mask:0xf bank_mask:0xf bound_ctrl:1
	v_pk_mul_f32 v[94:95], v[94:95], v[132:133] op_sel:[0,1] op_sel_hi:[1,1]
	v_pk_fma_f32 v[196:197], v[132:133], v[196:197], v[80:81] op_sel_hi:[0,1,1]
	s_and_saveexec_b64 s[8:9], s[44:45]
	ds_write_b32 v190, v213 offset:34240
	s_mov_b64 exec, s[8:9]
	v_pk_fma_f32 v[198:199], v[132:133], v[198:199], v[82:83] op_sel_hi:[0,1,1]
	v_pk_fma_f32 v[200:201], v[132:133], v[200:201], v[84:85] op_sel_hi:[0,1,1]
	v_pk_fma_f32 v[202:203], v[132:133], v[202:203], v[86:87] op_sel_hi:[0,1,1]
	v_pk_fma_f32 v[204:205], v[132:133], v[204:205], v[88:89] op_sel_hi:[0,1,1]
	v_pk_fma_f32 v[206:207], v[132:133], v[206:207], v[90:91] op_sel_hi:[0,1,1]
	v_pk_fma_f32 v[208:209], v[132:133], v[208:209], v[92:93] op_sel_hi:[0,1,1]
	v_pk_fma_f32 v[210:211], v[132:133], v[210:211], v[94:95] op_sel_hi:[0,1,1]
	s_waitcnt lgkmcnt(15)
	v_pk_fma_f32 v[128:129], v[64:65], v[196:197], v[214:215]
	v_pk_fma_f32 v[130:131], v[66:67], v[198:199], v[214:215]
	v_pk_fma_f32 v[128:129], v[68:69], v[200:201], v[128:129]
	v_pk_fma_f32 v[130:131], v[70:71], v[202:203], v[130:131]
	s_waitcnt lgkmcnt(14)
	v_pk_fma_f32 v[128:129], v[72:73], v[204:205], v[128:129]
	v_pk_fma_f32 v[130:131], v[74:75], v[206:207], v[130:131]
	s_waitcnt lgkmcnt(13)
	v_pk_fma_f32 v[128:129], v[76:77], v[208:209], v[128:129]
	v_pk_fma_f32 v[130:131], v[78:79], v[210:211], v[130:131]
	v_add_f32_e32 v128, v128, v129
	v_add_f32_e32 v130, v130, v131
	v_add_f32_e32 v212, v128, v130
	ds_read_b128 v[80:83], v194 offset:14336
	ds_read_b128 v[84:87], v194 offset:14592
	ds_read_b128 v[88:91], v194 offset:14848
	ds_read_b128 v[92:95], v194 offset:15104
	ds_read_b32 v134, v140 offset:35160
	ds_read_b32 v135, v190 offset:16768
	ds_read_b32 v132, v140 offset:35096
	ds_read_b128 v[64:67], v194 offset:6144
	ds_read_b128 v[68:71], v194 offset:6400
	ds_read_b128 v[72:75], v194 offset:6656
	ds_read_b128 v[76:79], v194 offset:6912
	s_waitcnt lgkmcnt(15)
	v_mul_f32_e32 v155, v156, v157
	v_pk_mul_f32 v[112:113], v[112:113], v[154:155] op_sel:[0,1] op_sel_hi:[1,1]
	v_add_f32_dpp v212, v212, v212 row_ror:8 row_mask:0xf bank_mask:0xf bound_ctrl:1
	v_pk_mul_f32 v[114:115], v[114:115], v[154:155] op_sel:[0,1] op_sel_hi:[1,1]
	v_pk_mul_f32 v[116:117], v[116:117], v[154:155] op_sel:[0,1] op_sel_hi:[1,1]
	v_add_f32_dpp v212, v212, v212 row_ror:4 row_mask:0xf bank_mask:0xf bound_ctrl:1
	v_pk_mul_f32 v[118:119], v[118:119], v[154:155] op_sel:[0,1] op_sel_hi:[1,1]
	v_pk_mul_f32 v[120:121], v[120:121], v[154:155] op_sel:[0,1] op_sel_hi:[1,1]
	v_add_f32_dpp v212, v212, v212 row_ror:2 row_mask:0xf bank_mask:0xf bound_ctrl:1
	v_pk_mul_f32 v[122:123], v[122:123], v[154:155] op_sel:[0,1] op_sel_hi:[1,1]
	v_pk_mul_f32 v[124:125], v[124:125], v[154:155] op_sel:[0,1] op_sel_hi:[1,1]
	v_add_f32_dpp v212, v212, v212 row_ror:1 row_mask:0xf bank_mask:0xf bound_ctrl:1
	v_pk_mul_f32 v[126:127], v[126:127], v[154:155] op_sel:[0,1] op_sel_hi:[1,1]
	v_pk_fma_f32 v[196:197], v[154:155], v[196:197], v[112:113] op_sel_hi:[0,1,1]
	s_and_saveexec_b64 s[8:9], s[44:45]
	ds_write_b32 v190, v212 offset:34304
	s_mov_b64 exec, s[8:9]
	v_pk_fma_f32 v[198:199], v[154:155], v[198:199], v[114:115] op_sel_hi:[0,1,1]
	v_pk_fma_f32 v[200:201], v[154:155], v[200:201], v[116:117] op_sel_hi:[0,1,1]
	v_pk_fma_f32 v[202:203], v[154:155], v[202:203], v[118:119] op_sel_hi:[0,1,1]
	v_pk_fma_f32 v[204:205], v[154:155], v[204:205], v[120:121] op_sel_hi:[0,1,1]
	v_pk_fma_f32 v[206:207], v[154:155], v[206:207], v[122:123] op_sel_hi:[0,1,1]
	v_pk_fma_f32 v[208:209], v[154:155], v[208:209], v[124:125] op_sel_hi:[0,1,1]
	v_pk_fma_f32 v[210:211], v[154:155], v[210:211], v[126:127] op_sel_hi:[0,1,1]
	s_waitcnt lgkmcnt(15)
	v_pk_fma_f32 v[128:129], v[96:97], v[196:197], v[214:215]
	v_pk_fma_f32 v[130:131], v[98:99], v[198:199], v[214:215]
	v_pk_fma_f32 v[128:129], v[100:101], v[200:201], v[128:129]
	v_pk_fma_f32 v[130:131], v[102:103], v[202:203], v[130:131]
	s_waitcnt lgkmcnt(14)
	v_pk_fma_f32 v[128:129], v[104:105], v[204:205], v[128:129]
	v_pk_fma_f32 v[130:131], v[106:107], v[206:207], v[130:131]
	s_waitcnt lgkmcnt(13)
	v_pk_fma_f32 v[128:129], v[108:109], v[208:209], v[128:129]
	v_pk_fma_f32 v[130:131], v[110:111], v[210:211], v[130:131]
	v_add_f32_e32 v128, v128, v129
	v_add_f32_e32 v130, v130, v131
	v_add_f32_e32 v213, v128, v130
	ds_read_b128 v[112:115], v194 offset:15360
	ds_read_b128 v[116:119], v194 offset:15616
	ds_read_b128 v[120:123], v194 offset:15872
	ds_read_b128 v[124:127], v194 offset:16128
	ds_read_b32 v156, v140 offset:35164
	ds_read_b32 v157, v190 offset:16832
	ds_read_b32 v154, v140 offset:35100
	ds_read_b128 v[96:99], v194 offset:7168
	ds_read_b128 v[100:103], v194 offset:7424
	ds_read_b128 v[104:107], v194 offset:7680
	ds_read_b128 v[108:111], v194 offset:7936
	s_waitcnt lgkmcnt(15)
	v_mul_f32_e32 v133, v134, v135
	v_pk_mul_f32 v[80:81], v[80:81], v[132:133] op_sel:[0,1] op_sel_hi:[1,1]
	v_add_f32_dpp v213, v213, v213 row_ror:8 row_mask:0xf bank_mask:0xf bound_ctrl:1
	v_pk_mul_f32 v[82:83], v[82:83], v[132:133] op_sel:[0,1] op_sel_hi:[1,1]
	v_pk_mul_f32 v[84:85], v[84:85], v[132:133] op_sel:[0,1] op_sel_hi:[1,1]
	v_add_f32_dpp v213, v213, v213 row_ror:4 row_mask:0xf bank_mask:0xf bound_ctrl:1
	v_pk_mul_f32 v[86:87], v[86:87], v[132:133] op_sel:[0,1] op_sel_hi:[1,1]
	v_pk_mul_f32 v[88:89], v[88:89], v[132:133] op_sel:[0,1] op_sel_hi:[1,1]
	v_add_f32_dpp v213, v213, v213 row_ror:2 row_mask:0xf bank_mask:0xf bound_ctrl:1
	v_pk_mul_f32 v[90:91], v[90:91], v[132:133] op_sel:[0,1] op_sel_hi:[1,1]
	v_pk_mul_f32 v[92:93], v[92:93], v[132:133] op_sel:[0,1] op_sel_hi:[1,1]
	v_add_f32_dpp v213, v213, v213 row_ror:1 row_mask:0xf bank_mask:0xf bound_ctrl:1
	v_pk_mul_f32 v[94:95], v[94:95], v[132:133] op_sel:[0,1] op_sel_hi:[1,1]
	v_pk_fma_f32 v[196:197], v[132:133], v[196:197], v[80:81] op_sel_hi:[0,1,1]
	s_and_saveexec_b64 s[8:9], s[44:45]
	ds_write_b32 v190, v213 offset:34368
	s_mov_b64 exec, s[8:9]
	v_pk_fma_f32 v[198:199], v[132:133], v[198:199], v[82:83] op_sel_hi:[0,1,1]
	v_pk_fma_f32 v[200:201], v[132:133], v[200:201], v[84:85] op_sel_hi:[0,1,1]
	v_pk_fma_f32 v[202:203], v[132:133], v[202:203], v[86:87] op_sel_hi:[0,1,1]
	v_pk_fma_f32 v[204:205], v[132:133], v[204:205], v[88:89] op_sel_hi:[0,1,1]
	v_pk_fma_f32 v[206:207], v[132:133], v[206:207], v[90:91] op_sel_hi:[0,1,1]
	v_pk_fma_f32 v[208:209], v[132:133], v[208:209], v[92:93] op_sel_hi:[0,1,1]
	v_pk_fma_f32 v[210:211], v[132:133], v[210:211], v[94:95] op_sel_hi:[0,1,1]
	s_waitcnt lgkmcnt(15)
	v_pk_fma_f32 v[128:129], v[64:65], v[196:197], v[214:215]
	v_pk_fma_f32 v[130:131], v[66:67], v[198:199], v[214:215]
	v_pk_fma_f32 v[128:129], v[68:69], v[200:201], v[128:129]
	v_pk_fma_f32 v[130:131], v[70:71], v[202:203], v[130:131]
	s_waitcnt lgkmcnt(14)
	v_pk_fma_f32 v[128:129], v[72:73], v[204:205], v[128:129]
	v_pk_fma_f32 v[130:131], v[74:75], v[206:207], v[130:131]
	s_waitcnt lgkmcnt(13)
	v_pk_fma_f32 v[128:129], v[76:77], v[208:209], v[128:129]
	v_pk_fma_f32 v[130:131], v[78:79], v[210:211], v[130:131]
	v_add_f32_e32 v128, v128, v129
	v_add_f32_e32 v130, v130, v131
	v_add_f32_e32 v212, v128, v130
	s_waitcnt lgkmcnt(6)
	v_mul_f32_e32 v155, v156, v157
	v_pk_mul_f32 v[112:113], v[112:113], v[154:155] op_sel:[0,1] op_sel_hi:[1,1]
	v_add_f32_dpp v212, v212, v212 row_ror:8 row_mask:0xf bank_mask:0xf bound_ctrl:1
	v_pk_mul_f32 v[114:115], v[114:115], v[154:155] op_sel:[0,1] op_sel_hi:[1,1]
	v_pk_mul_f32 v[116:117], v[116:117], v[154:155] op_sel:[0,1] op_sel_hi:[1,1]
	v_add_f32_dpp v212, v212, v212 row_ror:4 row_mask:0xf bank_mask:0xf bound_ctrl:1
	v_pk_mul_f32 v[118:119], v[118:119], v[154:155] op_sel:[0,1] op_sel_hi:[1,1]
	v_pk_mul_f32 v[120:121], v[120:121], v[154:155] op_sel:[0,1] op_sel_hi:[1,1]
	v_add_f32_dpp v212, v212, v212 row_ror:2 row_mask:0xf bank_mask:0xf bound_ctrl:1
	v_pk_mul_f32 v[122:123], v[122:123], v[154:155] op_sel:[0,1] op_sel_hi:[1,1]
	v_pk_mul_f32 v[124:125], v[124:125], v[154:155] op_sel:[0,1] op_sel_hi:[1,1]
	v_add_f32_dpp v212, v212, v212 row_ror:1 row_mask:0xf bank_mask:0xf bound_ctrl:1
	v_pk_mul_f32 v[126:127], v[126:127], v[154:155] op_sel:[0,1] op_sel_hi:[1,1]
	s_waitcnt lgkmcnt(5)
	v_pk_fma_f32 v[196:197], v[154:155], v[196:197], v[112:113] op_sel_hi:[0,1,1]
	s_and_saveexec_b64 s[8:9], s[44:45]
	ds_write_b32 v190, v212 offset:34432
	s_mov_b64 exec, s[8:9]
	v_pk_fma_f32 v[198:199], v[154:155], v[198:199], v[114:115] op_sel_hi:[0,1,1]
	v_pk_fma_f32 v[200:201], v[154:155], v[200:201], v[116:117] op_sel_hi:[0,1,1]
	v_pk_fma_f32 v[202:203], v[154:155], v[202:203], v[118:119] op_sel_hi:[0,1,1]
	v_pk_fma_f32 v[204:205], v[154:155], v[204:205], v[120:121] op_sel_hi:[0,1,1]
	v_pk_fma_f32 v[206:207], v[154:155], v[206:207], v[122:123] op_sel_hi:[0,1,1]
	v_pk_fma_f32 v[208:209], v[154:155], v[208:209], v[124:125] op_sel_hi:[0,1,1]
	v_pk_fma_f32 v[210:211], v[154:155], v[210:211], v[126:127] op_sel_hi:[0,1,1]
	s_waitcnt lgkmcnt(5)
	v_pk_fma_f32 v[128:129], v[96:97], v[196:197], v[214:215]
	v_pk_fma_f32 v[130:131], v[98:99], v[198:199], v[214:215]
	s_waitcnt lgkmcnt(4)
	v_pk_fma_f32 v[128:129], v[100:101], v[200:201], v[128:129]
	v_pk_fma_f32 v[130:131], v[102:103], v[202:203], v[130:131]
	s_waitcnt lgkmcnt(3)
	v_pk_fma_f32 v[128:129], v[104:105], v[204:205], v[128:129]
	v_pk_fma_f32 v[130:131], v[106:107], v[206:207], v[130:131]
	s_waitcnt lgkmcnt(2)
	v_pk_fma_f32 v[128:129], v[108:109], v[208:209], v[128:129]
	v_pk_fma_f32 v[130:131], v[110:111], v[210:211], v[130:131]
	v_add_f32_e32 v128, v128, v129
	v_add_f32_e32 v130, v130, v131
	v_add_f32_e32 v213, v128, v130
	s_nop 1
	v_add_f32_dpp v213, v213, v213 row_ror:8 row_mask:0xf bank_mask:0xf bound_ctrl:1
	s_nop 1
	v_add_f32_dpp v213, v213, v213 row_ror:4 row_mask:0xf bank_mask:0xf bound_ctrl:1
	s_nop 1
	v_add_f32_dpp v213, v213, v213 row_ror:2 row_mask:0xf bank_mask:0xf bound_ctrl:1
	s_nop 1
	v_add_f32_dpp v213, v213, v213 row_ror:1 row_mask:0xf bank_mask:0xf bound_ctrl:1
	s_and_saveexec_b64 s[8:9], s[44:45]
	ds_write_b32 v190, v213 offset:34496
	s_mov_b64 exec, s[8:9]
	s_waitcnt vmcnt(11)
	ds_write_b128 v188, v[16:19] offset:17024
	s_waitcnt vmcnt(9)
	ds_write_b128 v191, v[24:27] offset:17024
	ds_write_b128 v188, v[20:23] offset:25216
	s_waitcnt vmcnt(8)
	ds_write_b128 v191, v[28:31] offset:25216
	s_and_saveexec_b64 s[8:9], s[40:41]
	ds_write_b32 v145, v183 offset:33408
	s_or_b64 exec, exec, s[8:9]
	s_and_saveexec_b64 s[8:9], s[42:43]
	s_cbranch_execz .LBB0_1176
	v_add_f32_e32 v64, v178, v185
	v_mul_f32_e64 v65, |v64|, s62
	v_exp_f32_e32 v65, v65
	v_min_f32_e32 v64, 0, v64
	v_add_f32_e32 v65, 1.0, v65
	v_cmp_gt_f32_e32 vcc, s5, v65
	s_nop 1
	v_cndmask_b32_e64 v66, 0, 32, vcc
	v_ldexp_f32 v65, v65, v66
	v_log_f32_e32 v65, v65
	v_cndmask_b32_e32 v67, 0, v171, vcc
	v_add_f32_e32 v66, v147, v184
	v_mul_f32_e32 v68, 0x3f317217, v65
	v_fma_f32 v68, v65, s76, -v68
	v_fmac_f32_e32 v68, 0x3377d1cf, v65
	v_fmac_f32_e32 v68, 0x3f317217, v65
	v_cmp_lt_f32_e64 vcc, |v65|, s77
	s_nop 1
	v_cndmask_b32_e32 v65, v65, v68, vcc
	v_sub_f32_e32 v65, v65, v67
	v_sub_f32_e32 v64, v64, v65
	v_add_u32_e32 v65, 0x8400, v145
	ds_write2_b32 v65, v66, v64 offset0:32 offset1:48
.LBB0_1176:
	s_or_b64 exec, exec, s[8:9]
	s_and_saveexec_b64 s[8:9], s[46:47]
	s_cbranch_execz .LBB0_1187
	v_mov_b32_e32 v65, 0
	v_mov_b32_e32 v64, 0xf149f2ca
	s_and_saveexec_b64 s[64:65], s[42:43]
	v_add_u32_e32 v64, 0x8400, v145
	ds_read2_b32 v[64:65], v64 offset0:32 offset1:48
	s_or_b64 exec, exec, s[64:65]
	s_waitcnt lgkmcnt(0)
	v_add_f32_dpp v66, v64, v65 row_shr:1 row_mask:0xf bank_mask:0xf bound_ctrl:1
	v_max_f32_e32 v67, v64, v64
	v_max_f32_e32 v66, v66, v67
	v_cndmask_b32_e64 v66, v64, v66, s[48:49]
	v_add_f32_dpp v67, v65, v65 row_shr:1 row_mask:0xf bank_mask:0xf bound_ctrl:1
	v_cndmask_b32_e64 v67, v65, v67, s[48:49]
	v_max_f32_e32 v69, v66, v66
	s_nop 0
	v_add_f32_dpp v68, v66, v67 row_shr:2 row_mask:0xf bank_mask:0xf bound_ctrl:1
	v_max_f32_e32 v68, v68, v69
	v_add_f32_dpp v69, v67, v67 row_shr:2 row_mask:0xf bank_mask:0xf bound_ctrl:1
	v_cndmask_b32_e64 v66, v66, v68, s[50:51]
	v_cndmask_b32_e64 v67, v67, v69, s[50:51]
	v_max_f32_e32 v69, v66, v66
	s_nop 0
	v_add_f32_dpp v68, v66, v67 row_shr:4 row_mask:0xf bank_mask:0xf bound_ctrl:1
	v_max_f32_e32 v68, v68, v69
	v_cndmask_b32_e64 v66, v66, v68, s[52:53]
	ds_read_b32 v68, v140 offset:35328
	v_add_f32_dpp v69, v67, v67 row_shr:4 row_mask:0xf bank_mask:0xf bound_ctrl:1
	v_cndmask_b32_e64 v67, v67, v69, s[52:53]
	v_max_f32_e32 v66, v66, v66
	s_waitcnt lgkmcnt(0)
	v_add_f32_e32 v67, v68, v67
	v_max_f32_e32 v66, v67, v66
	v_mov_b32_e32 v67, 0
	v_sub_f32_e32 v64, v64, v66
	v_mul_f32_e32 v64, 0x3fb8aa3b, v64
	v_mov_b32_dpp v67, v66 row_shr:1 row_mask:0xf bank_mask:0xf
	v_cndmask_b32_e64 v67, v67, v68, s[38:39]
	v_add_f32_e32 v65, v65, v67
	v_sub_f32_e32 v65, v65, v66
	v_mul_f32_e32 v65, 0x3fb8aa3b, v65
	v_exp_f32_e32 v65, v65
	v_exp_f32_e32 v64, v64
	v_add_u32_e32 v67, 0x8800, v145
	ds_write2_b32 v67, v65, v64 offset0:160 offset1:176
	ds_write_b32 v145, v66 offset:35264
	s_and_b64 exec, exec, s[54:55]
	ds_write_b32 v140, v66 offset:35328

.LBB0_1182:
	s_and_saveexec_b64 s[8:9], s[40:41]
	s_cbranch_execz .LBB0_1189
	ds_read_b32 v66, v145 offset:34048
	v_add_u32_e32 v64, s85, v149
	v_ashrrev_i32_e32 v65, 31, v64
	v_lshlrev_b64 v[64:65], 12, v[64:65]
	v_lshl_add_u64 v[64:65], v[152:153], 0, v[64:65]
	s_waitcnt lgkmcnt(0)
	global_store_dword v[64:65], v66, off
.LBB0_1189:
	s_or_b64 exec, exec, s[8:9]
	s_waitcnt lgkmcnt(0)
	v_mov_b32_e32 v214, 0
	v_mov_b32_e32 v215, 0
	ds_read_b128 v[80:83], v194 offset:25216
	ds_read_b128 v[84:87], v194 offset:25472
	ds_read_b128 v[88:91], v194 offset:25728
	ds_read_b128 v[92:95], v194 offset:25984
	ds_read_b32 v134, v140 offset:35520
	ds_read_b32 v135, v190 offset:33408
	ds_read_b32 v132, v140 offset:35456
	ds_read_b128 v[64:67], v194 offset:17024
	ds_read_b128 v[68:71], v194 offset:17280
	ds_read_b128 v[72:75], v194 offset:17536
	ds_read_b128 v[76:79], v194 offset:17792
	ds_read_b128 v[112:115], v194 offset:26240
	ds_read_b128 v[116:119], v194 offset:26496
	ds_read_b128 v[120:123], v194 offset:26752
	ds_read_b128 v[124:127], v194 offset:27008
	ds_read_b32 v156, v140 offset:35524
	ds_read_b32 v157, v190 offset:33472
	ds_read_b32 v154, v140 offset:35460
	ds_read_b128 v[96:99], v194 offset:18048
	ds_read_b128 v[100:103], v194 offset:18304
	ds_read_b128 v[104:107], v194 offset:18560
	ds_read_b128 v[108:111], v194 offset:18816
	s_waitcnt lgkmcnt(15)
	v_mul_f32_e32 v133, v134, v135
	v_pk_mul_f32 v[80:81], v[80:81], v[132:133] op_sel:[0,1] op_sel_hi:[1,1]
	v_pk_mul_f32 v[82:83], v[82:83], v[132:133] op_sel:[0,1] op_sel_hi:[1,1]
	v_pk_mul_f32 v[84:85], v[84:85], v[132:133] op_sel:[0,1] op_sel_hi:[1,1]
	v_pk_mul_f32 v[86:87], v[86:87], v[132:133] op_sel:[0,1] op_sel_hi:[1,1]
	v_pk_mul_f32 v[88:89], v[88:89], v[132:133] op_sel:[0,1] op_sel_hi:[1,1]
	v_pk_mul_f32 v[90:91], v[90:91], v[132:133] op_sel:[0,1] op_sel_hi:[1,1]
	v_pk_mul_f32 v[92:93], v[92:93], v[132:133] op_sel:[0,1] op_sel_hi:[1,1]
	v_pk_mul_f32 v[94:95], v[94:95], v[132:133] op_sel:[0,1] op_sel_hi:[1,1]
	v_pk_fma_f32 v[196:197], v[132:133], v[196:197], v[80:81] op_sel_hi:[0,1,1]
	v_pk_fma_f32 v[198:199], v[132:133], v[198:199], v[82:83] op_sel_hi:[0,1,1]
	v_pk_fma_f32 v[200:201], v[132:133], v[200:201], v[84:85] op_sel_hi:[0,1,1]
	v_pk_fma_f32 v[202:203], v[132:133], v[202:203], v[86:87] op_sel_hi:[0,1,1]
	v_pk_fma_f32 v[204:205], v[132:133], v[204:205], v[88:89] op_sel_hi:[0,1,1]
	v_pk_fma_f32 v[206:207], v[132:133], v[206:207], v[90:91] op_sel_hi:[0,1,1]
	v_pk_fma_f32 v[208:209], v[132:133], v[208:209], v[92:93] op_sel_hi:[0,1,1]
	v_pk_fma_f32 v[210:211], v[132:133], v[210:211], v[94:95] op_sel_hi:[0,1,1]
	s_waitcnt lgkmcnt(14)
	v_pk_fma_f32 v[128:129], v[64:65], v[196:197], v[214:215]
	v_pk_fma_f32 v[130:131], v[66:67], v[198:199], v[214:215]
	s_waitcnt lgkmcnt(13)
	v_pk_fma_f32 v[128:129], v[68:69], v[200:201], v[128:129]
	v_pk_fma_f32 v[130:131], v[70:71], v[202:203], v[130:131]
	s_waitcnt lgkmcnt(12)
	v_pk_fma_f32 v[128:129], v[72:73], v[204:205], v[128:129]
	v_pk_fma_f32 v[130:131], v[74:75], v[206:207], v[130:131]
	s_waitcnt lgkmcnt(11)
	v_pk_fma_f32 v[128:129], v[76:77], v[208:209], v[128:129]
	v_pk_fma_f32 v[130:131], v[78:79], v[210:211], v[130:131]
	v_add_f32_e32 v128, v128, v129
	v_add_f32_e32 v130, v130, v131
	v_add_f32_e32 v212, v128, v130
	ds_read_b128 v[80:83], v194 offset:27264
	ds_read_b128 v[84:87], v194 offset:27520
	ds_read_b128 v[88:91], v194 offset:27776
	ds_read_b128 v[92:95], v194 offset:28032
	ds_read_b32 v134, v140 offset:35528
	ds_read_b32 v135, v190 offset:33536
	ds_read_b32 v132, v140 offset:35464
	ds_read_b128 v[64:67], v194 offset:19072
	ds_read_b128 v[68:71], v194 offset:19328
	ds_read_b128 v[72:75], v194 offset:19584
	ds_read_b128 v[76:79], v194 offset:19840
	s_waitcnt lgkmcnt(15)
	v_mul_f32_e32 v155, v156, v157
	v_pk_mul_f32 v[112:113], v[112:113], v[154:155] op_sel:[0,1] op_sel_hi:[1,1]
	v_add_f32_dpp v212, v212, v212 row_ror:8 row_mask:0xf bank_mask:0xf bound_ctrl:1
	v_pk_mul_f32 v[114:115], v[114:115], v[154:155] op_sel:[0,1] op_sel_hi:[1,1]
	v_pk_mul_f32 v[116:117], v[116:117], v[154:155] op_sel:[0,1] op_sel_hi:[1,1]
	v_add_f32_dpp v212, v212, v212 row_ror:4 row_mask:0xf bank_mask:0xf bound_ctrl:1
	v_pk_mul_f32 v[118:119], v[118:119], v[154:155] op_sel:[0,1] op_sel_hi:[1,1]
	v_pk_mul_f32 v[120:121], v[120:121], v[154:155] op_sel:[0,1] op_sel_hi:[1,1]
	v_add_f32_dpp v212, v212, v212 row_ror:2 row_mask:0xf bank_mask:0xf bound_ctrl:1
	v_pk_mul_f32 v[122:123], v[122:123], v[154:155] op_sel:[0,1] op_sel_hi:[1,1]
	v_pk_mul_f32 v[124:125], v[124:125], v[154:155] op_sel:[0,1] op_sel_hi:[1,1]
	v_add_f32_dpp v212, v212, v212 row_ror:1 row_mask:0xf bank_mask:0xf bound_ctrl:1
	v_pk_mul_f32 v[126:127], v[126:127], v[154:155] op_sel:[0,1] op_sel_hi:[1,1]
	v_pk_fma_f32 v[196:197], v[154:155], v[196:197], v[112:113] op_sel_hi:[0,1,1]
	s_and_saveexec_b64 s[8:9], s[44:45]
	ds_write_b32 v190, v212 offset:34560
	s_mov_b64 exec, s[8:9]
	v_pk_fma_f32 v[198:199], v[154:155], v[198:199], v[114:115] op_sel_hi:[0,1,1]
	v_pk_fma_f32 v[200:201], v[154:155], v[200:201], v[116:117] op_sel_hi:[0,1,1]
	v_pk_fma_f32 v[202:203], v[154:155], v[202:203], v[118:119] op_sel_hi:[0,1,1]
	v_pk_fma_f32 v[204:205], v[154:155], v[204:205], v[120:121] op_sel_hi:[0,1,1]
	v_pk_fma_f32 v[206:207], v[154:155], v[206:207], v[122:123] op_sel_hi:[0,1,1]
	v_pk_fma_f32 v[208:209], v[154:155], v[208:209], v[124:125] op_sel_hi:[0,1,1]
	v_pk_fma_f32 v[210:211], v[154:155], v[210:211], v[126:127] op_sel_hi:[0,1,1]
	s_waitcnt lgkmcnt(15)
	v_pk_fma_f32 v[128:129], v[96:97], v[196:197], v[214:215]
	v_pk_fma_f32 v[130:131], v[98:99], v[198:199], v[214:215]
	s_waitcnt lgkmcnt(14)
	v_pk_fma_f32 v[128:129], v[100:101], v[200:201], v[128:129]
	v_pk_fma_f32 v[130:131], v[102:103], v[202:203], v[130:131]
	s_waitcnt lgkmcnt(13)
	v_pk_fma_f32 v[128:129], v[104:105], v[204:205], v[128:129]
	v_pk_fma_f32 v[130:131], v[106:107], v[206:207], v[130:131]
	s_waitcnt lgkmcnt(12)
	v_pk_fma_f32 v[128:129], v[108:109], v[208:209], v[128:129]
	v_pk_fma_f32 v[130:131], v[110:111], v[210:211], v[130:131]
	v_add_f32_e32 v128, v128, v129
	v_add_f32_e32 v130, v130, v131
	v_add_f32_e32 v213, v128, v130
	ds_read_b128 v[112:115], v194 offset:28288
	ds_read_b128 v[116:119], v194 offset:28544
	ds_read_b128 v[120:123], v194 offset:28800
	ds_read_b128 v[124:127], v194 offset:29056
	ds_read_b32 v156, v140 offset:35532
	ds_read_b32 v157, v190 offset:33600
	ds_read_b32 v154, v140 offset:35468
	ds_read_b128 v[96:99], v194 offset:20096
	ds_read_b128 v[100:103], v194 offset:20352
	ds_read_b128 v[104:107], v194 offset:20608
	ds_read_b128 v[108:111], v194 offset:20864
	s_waitcnt lgkmcnt(15)
	v_mul_f32_e32 v133, v134, v135
	v_pk_mul_f32 v[80:81], v[80:81], v[132:133] op_sel:[0,1] op_sel_hi:[1,1]
	v_add_f32_dpp v213, v213, v213 row_ror:8 row_mask:0xf bank_mask:0xf bound_ctrl:1
	v_pk_mul_f32 v[82:83], v[82:83], v[132:133] op_sel:[0,1] op_sel_hi:[1,1]
	v_pk_mul_f32 v[84:85], v[84:85], v[132:133] op_sel:[0,1] op_sel_hi:[1,1]
	v_add_f32_dpp v213, v213, v213 row_ror:4 row_mask:0xf bank_mask:0xf bound_ctrl:1
	v_pk_mul_f32 v[86:87], v[86:87], v[132:133] op_sel:[0,1] op_sel_hi:[1,1]
	v_pk_mul_f32 v[88:89], v[88:89], v[132:133] op_sel:[0,1] op_sel_hi:[1,1]
	v_add_f32_dpp v213, v213, v213 row_ror:2 row_mask:0xf bank_mask:0xf bound_ctrl:1
	v_pk_mul_f32 v[90:91], v[90:91], v[132:133] op_sel:[0,1] op_sel_hi:[1,1]
	v_pk_mul_f32 v[92:93], v[92:93], v[132:133] op_sel:[0,1] op_sel_hi:[1,1]
	v_add_f32_dpp v213, v213, v213 row_ror:1 row_mask:0xf bank_mask:0xf bound_ctrl:1
	v_pk_mul_f32 v[94:95], v[94:95], v[132:133] op_sel:[0,1] op_sel_hi:[1,1]
	v_pk_fma_f32 v[196:197], v[132:133], v[196:197], v[80:81] op_sel_hi:[0,1,1]
	s_and_saveexec_b64 s[8:9], s[44:45]
	ds_write_b32 v190, v213 offset:34624
	s_mov_b64 exec, s[8:9]
	v_pk_fma_f32 v[198:199], v[132:133], v[198:199], v[82:83] op_sel_hi:[0,1,1]
	v_pk_fma_f32 v[200:201], v[132:133], v[200:201], v[84:85] op_sel_hi:[0,1,1]
	v_pk_fma_f32 v[202:203], v[132:133], v[202:203], v[86:87] op_sel_hi:[0,1,1]
	v_pk_fma_f32 v[204:205], v[132:133], v[204:205], v[88:89] op_sel_hi:[0,1,1]
	v_pk_fma_f32 v[206:207], v[132:133], v[206:207], v[90:91] op_sel_hi:[0,1,1]
	v_pk_fma_f32 v[208:209], v[132:133], v[208:209], v[92:93] op_sel_hi:[0,1,1]
	v_pk_fma_f32 v[210:211], v[132:133], v[210:211], v[94:95] op_sel_hi:[0,1,1]
	s_waitcnt lgkmcnt(15)
	v_pk_fma_f32 v[128:129], v[64:65], v[196:197], v[214:215]
	v_pk_fma_f32 v[130:131], v[66:67], v[198:199], v[214:215]
	v_pk_fma_f32 v[128:129], v[68:69], v[200:201], v[128:129]
	v_pk_fma_f32 v[130:131], v[70:71], v[202:203], v[130:131]
	s_waitcnt lgkmcnt(14)
	v_pk_fma_f32 v[128:129], v[72:73], v[204:205], v[128:129]
	v_pk_fma_f32 v[130:131], v[74:75], v[206:207], v[130:131]
	s_waitcnt lgkmcnt(13)
	v_pk_fma_f32 v[128:129], v[76:77], v[208:209], v[128:129]
	v_pk_fma_f32 v[130:131], v[78:79], v[210:211], v[130:131]
	v_add_f32_e32 v128, v128, v129
	v_add_f32_e32 v130, v130, v131
	v_add_f32_e32 v212, v128, v130
	ds_read_b128 v[80:83], v194 offset:29312
	ds_read_b128 v[84:87], v194 offset:29568
	ds_read_b128 v[88:91], v194 offset:29824
	ds_read_b128 v[92:95], v194 offset:30080
	ds_read_b32 v134, v140 offset:35536
	ds_read_b32 v135, v190 offset:33664
	ds_read_b32 v132, v140 offset:35472
	ds_read_b128 v[64:67], v194 offset:21120
	ds_read_b128 v[68:71], v194 offset:21376
	ds_read_b128 v[72:75], v194 offset:21632
	ds_read_b128 v[76:79], v194 offset:21888
	s_waitcnt lgkmcnt(15)
	v_mul_f32_e32 v155, v156, v157
	v_pk_mul_f32 v[112:113], v[112:113], v[154:155] op_sel:[0,1] op_sel_hi:[1,1]
	v_add_f32_dpp v212, v212, v212 row_ror:8 row_mask:0xf bank_mask:0xf bound_ctrl:1
	v_pk_mul_f32 v[114:115], v[114:115], v[154:155] op_sel:[0,1] op_sel_hi:[1,1]
	v_pk_mul_f32 v[116:117], v[116:117], v[154:155] op_sel:[0,1] op_sel_hi:[1,1]
	v_add_f32_dpp v212, v212, v212 row_ror:4 row_mask:0xf bank_mask:0xf bound_ctrl:1
	v_pk_mul_f32 v[118:119], v[118:119], v[154:155] op_sel:[0,1] op_sel_hi:[1,1]
	v_pk_mul_f32 v[120:121], v[120:121], v[154:155] op_sel:[0,1] op_sel_hi:[1,1]
	v_add_f32_dpp v212, v212, v212 row_ror:2 row_mask:0xf bank_mask:0xf bound_ctrl:1
	v_pk_mul_f32 v[122:123], v[122:123], v[154:155] op_sel:[0,1] op_sel_hi:[1,1]
	v_pk_mul_f32 v[124:125], v[124:125], v[154:155] op_sel:[0,1] op_sel_hi:[1,1]
	v_add_f32_dpp v212, v212, v212 row_ror:1 row_mask:0xf bank_mask:0xf bound_ctrl:1
	v_pk_mul_f32 v[126:127], v[126:127], v[154:155] op_sel:[0,1] op_sel_hi:[1,1]
	v_pk_fma_f32 v[196:197], v[154:155], v[196:197], v[112:113] op_sel_hi:[0,1,1]
	s_and_saveexec_b64 s[8:9], s[44:45]
	ds_write_b32 v190, v212 offset:34688
	s_mov_b64 exec, s[8:9]
	v_pk_fma_f32 v[198:199], v[154:155], v[198:199], v[114:115] op_sel_hi:[0,1,1]
	v_pk_fma_f32 v[200:201], v[154:155], v[200:201], v[116:117] op_sel_hi:[0,1,1]
	v_pk_fma_f32 v[202:203], v[154:155], v[202:203], v[118:119] op_sel_hi:[0,1,1]
	v_pk_fma_f32 v[204:205], v[154:155], v[204:205], v[120:121] op_sel_hi:[0,1,1]
	v_pk_fma_f32 v[206:207], v[154:155], v[206:207], v[122:123] op_sel_hi:[0,1,1]
	v_pk_fma_f32 v[208:209], v[154:155], v[208:209], v[124:125] op_sel_hi:[0,1,1]
	v_pk_fma_f32 v[210:211], v[154:155], v[210:211], v[126:127] op_sel_hi:[0,1,1]
	s_waitcnt lgkmcnt(15)
	v_pk_fma_f32 v[128:129], v[96:97], v[196:197], v[214:215]
	v_pk_fma_f32 v[130:131], v[98:99], v[198:199], v[214:215]
	v_pk_fma_f32 v[128:129], v[100:101], v[200:201], v[128:129]
	v_pk_fma_f32 v[130:131], v[102:103], v[202:203], v[130:131]
	s_waitcnt lgkmcnt(14)
	v_pk_fma_f32 v[128:129], v[104:105], v[204:205], v[128:129]
	v_pk_fma_f32 v[130:131], v[106:107], v[206:207], v[130:131]
	s_waitcnt lgkmcnt(13)
	v_pk_fma_f32 v[128:129], v[108:109], v[208:209], v[128:129]
	v_pk_fma_f32 v[130:131], v[110:111], v[210:211], v[130:131]
	v_add_f32_e32 v128, v128, v129
	v_add_f32_e32 v130, v130, v131
	v_add_f32_e32 v213, v128, v130
	ds_read_b128 v[112:115], v194 offset:30336
	ds_read_b128 v[116:119], v194 offset:30592
	ds_read_b128 v[120:123], v194 offset:30848
	ds_read_b128 v[124:127], v194 offset:31104
	ds_read_b32 v156, v140 offset:35540
	ds_read_b32 v157, v190 offset:33728
	ds_read_b32 v154, v140 offset:35476
	ds_read_b128 v[96:99], v194 offset:22144
	ds_read_b128 v[100:103], v194 offset:22400
	ds_read_b128 v[104:107], v194 offset:22656
	ds_read_b128 v[108:111], v194 offset:22912
	s_waitcnt lgkmcnt(15)
	v_mul_f32_e32 v133, v134, v135
	v_pk_mul_f32 v[80:81], v[80:81], v[132:133] op_sel:[0,1] op_sel_hi:[1,1]
	v_add_f32_dpp v213, v213, v213 row_ror:8 row_mask:0xf bank_mask:0xf bound_ctrl:1
	v_pk_mul_f32 v[82:83], v[82:83], v[132:133] op_sel:[0,1] op_sel_hi:[1,1]
	v_pk_mul_f32 v[84:85], v[84:85], v[132:133] op_sel:[0,1] op_sel_hi:[1,1]
	v_add_f32_dpp v213, v213, v213 row_ror:4 row_mask:0xf bank_mask:0xf bound_ctrl:1
	v_pk_mul_f32 v[86:87], v[86:87], v[132:133] op_sel:[0,1] op_sel_hi:[1,1]
	v_pk_mul_f32 v[88:89], v[88:89], v[132:133] op_sel:[0,1] op_sel_hi:[1,1]
	v_add_f32_dpp v213, v213, v213 row_ror:2 row_mask:0xf bank_mask:0xf bound_ctrl:1
	v_pk_mul_f32 v[90:91], v[90:91], v[132:133] op_sel:[0,1] op_sel_hi:[1,1]
	v_pk_mul_f32 v[92:93], v[92:93], v[132:133] op_sel:[0,1] op_sel_hi:[1,1]
	v_add_f32_dpp v213, v213, v213 row_ror:1 row_mask:0xf bank_mask:0xf bound_ctrl:1
	v_pk_mul_f32 v[94:95], v[94:95], v[132:133] op_sel:[0,1] op_sel_hi:[1,1]
	v_pk_fma_f32 v[196:197], v[132:133], v[196:197], v[80:81] op_sel_hi:[0,1,1]
	s_and_saveexec_b64 s[8:9], s[44:45]
	ds_write_b32 v190, v213 offset:34752
	s_mov_b64 exec, s[8:9]
	v_pk_fma_f32 v[198:199], v[132:133], v[198:199], v[82:83] op_sel_hi:[0,1,1]
	v_pk_fma_f32 v[200:201], v[132:133], v[200:201], v[84:85] op_sel_hi:[0,1,1]
	v_pk_fma_f32 v[202:203], v[132:133], v[202:203], v[86:87] op_sel_hi:[0,1,1]
	v_pk_fma_f32 v[204:205], v[132:133], v[204:205], v[88:89] op_sel_hi:[0,1,1]
	v_pk_fma_f32 v[206:207], v[132:133], v[206:207], v[90:91] op_sel_hi:[0,1,1]
	v_pk_fma_f32 v[208:209], v[132:133], v[208:209], v[92:93] op_sel_hi:[0,1,1]
	v_pk_fma_f32 v[210:211], v[132:133], v[210:211], v[94:95] op_sel_hi:[0,1,1]
	s_waitcnt lgkmcnt(15)
	v_pk_fma_f32 v[128:129], v[64:65], v[196:197], v[214:215]
	v_pk_fma_f32 v[130:131], v[66:67], v[198:199], v[214:215]
	v_pk_fma_f32 v[128:129], v[68:69], v[200:201], v[128:129]
	v_pk_fma_f32 v[130:131], v[70:71], v[202:203], v[130:131]
	s_waitcnt lgkmcnt(14)
	v_pk_fma_f32 v[128:129], v[72:73], v[204:205], v[128:129]
	v_pk_fma_f32 v[130:131], v[74:75], v[206:207], v[130:131]
	s_waitcnt lgkmcnt(13)
	v_pk_fma_f32 v[128:129], v[76:77], v[208:209], v[128:129]
	v_pk_fma_f32 v[130:131], v[78:79], v[210:211], v[130:131]
	v_add_f32_e32 v128, v128, v129
	v_add_f32_e32 v130, v130, v131
	v_add_f32_e32 v212, v128, v130
	ds_read_b128 v[80:83], v194 offset:31360
	ds_read_b128 v[84:87], v194 offset:31616
	ds_read_b128 v[88:91], v194 offset:31872
	ds_read_b128 v[92:95], v194 offset:32128
	ds_read_b32 v134, v140 offset:35544
	ds_read_b32 v135, v190 offset:33792
	ds_read_b32 v132, v140 offset:35480
	ds_read_b128 v[64:67], v194 offset:23168
	ds_read_b128 v[68:71], v194 offset:23424
	ds_read_b128 v[72:75], v194 offset:23680
	ds_read_b128 v[76:79], v194 offset:23936
	s_waitcnt lgkmcnt(15)
	v_mul_f32_e32 v155, v156, v157
	v_pk_mul_f32 v[112:113], v[112:113], v[154:155] op_sel:[0,1] op_sel_hi:[1,1]
	v_add_f32_dpp v212, v212, v212 row_ror:8 row_mask:0xf bank_mask:0xf bound_ctrl:1
	v_pk_mul_f32 v[114:115], v[114:115], v[154:155] op_sel:[0,1] op_sel_hi:[1,1]
	v_pk_mul_f32 v[116:117], v[116:117], v[154:155] op_sel:[0,1] op_sel_hi:[1,1]
	v_add_f32_dpp v212, v212, v212 row_ror:4 row_mask:0xf bank_mask:0xf bound_ctrl:1
	v_pk_mul_f32 v[118:119], v[118:119], v[154:155] op_sel:[0,1] op_sel_hi:[1,1]
	v_pk_mul_f32 v[120:121], v[120:121], v[154:155] op_sel:[0,1] op_sel_hi:[1,1]
	v_add_f32_dpp v212, v212, v212 row_ror:2 row_mask:0xf bank_mask:0xf bound_ctrl:1
	v_pk_mul_f32 v[122:123], v[122:123], v[154:155] op_sel:[0,1] op_sel_hi:[1,1]
	v_pk_mul_f32 v[124:125], v[124:125], v[154:155] op_sel:[0,1] op_sel_hi:[1,1]
	v_add_f32_dpp v212, v212, v212 row_ror:1 row_mask:0xf bank_mask:0xf bound_ctrl:1
	v_pk_mul_f32 v[126:127], v[126:127], v[154:155] op_sel:[0,1] op_sel_hi:[1,1]
	v_pk_fma_f32 v[196:197], v[154:155], v[196:197], v[112:113] op_sel_hi:[0,1,1]
	s_and_saveexec_b64 s[8:9], s[44:45]
	ds_write_b32 v190, v212 offset:34816
	s_mov_b64 exec, s[8:9]
	v_pk_fma_f32 v[198:199], v[154:155], v[198:199], v[114:115] op_sel_hi:[0,1,1]
	v_pk_fma_f32 v[200:201], v[154:155], v[200:201], v[116:117] op_sel_hi:[0,1,1]
	v_pk_fma_f32 v[202:203], v[154:155], v[202:203], v[118:119] op_sel_hi:[0,1,1]
	v_pk_fma_f32 v[204:205], v[154:155], v[204:205], v[120:121] op_sel_hi:[0,1,1]
	v_pk_fma_f32 v[206:207], v[154:155], v[206:207], v[122:123] op_sel_hi:[0,1,1]
	v_pk_fma_f32 v[208:209], v[154:155], v[208:209], v[124:125] op_sel_hi:[0,1,1]
	v_pk_fma_f32 v[210:211], v[154:155], v[210:211], v[126:127] op_sel_hi:[0,1,1]
	s_waitcnt lgkmcnt(15)
	v_pk_fma_f32 v[128:129], v[96:97], v[196:197], v[214:215]
	v_pk_fma_f32 v[130:131], v[98:99], v[198:199], v[214:215]
	v_pk_fma_f32 v[128:129], v[100:101], v[200:201], v[128:129]
	v_pk_fma_f32 v[130:131], v[102:103], v[202:203], v[130:131]
	s_waitcnt lgkmcnt(14)
	v_pk_fma_f32 v[128:129], v[104:105], v[204:205], v[128:129]
	v_pk_fma_f32 v[130:131], v[106:107], v[206:207], v[130:131]
	s_waitcnt lgkmcnt(13)
	v_pk_fma_f32 v[128:129], v[108:109], v[208:209], v[128:129]
	v_pk_fma_f32 v[130:131], v[110:111], v[210:211], v[130:131]
	v_add_f32_e32 v128, v128, v129
	v_add_f32_e32 v130, v130, v131
	v_add_f32_e32 v213, v128, v130
	ds_read_b128 v[112:115], v194 offset:32384
	ds_read_b128 v[116:119], v194 offset:32640
	ds_read_b128 v[120:123], v194 offset:32896
	ds_read_b128 v[124:127], v194 offset:33152
	ds_read_b32 v156, v140 offset:35548
	ds_read_b32 v157, v190 offset:33856
	ds_read_b32 v154, v140 offset:35484
	ds_read_b128 v[96:99], v194 offset:24192
	ds_read_b128 v[100:103], v194 offset:24448
	ds_read_b128 v[104:107], v194 offset:24704
	ds_read_b128 v[108:111], v194 offset:24960
	s_waitcnt lgkmcnt(15)
	v_mul_f32_e32 v133, v134, v135
	v_pk_mul_f32 v[80:81], v[80:81], v[132:133] op_sel:[0,1] op_sel_hi:[1,1]
	v_add_f32_dpp v213, v213, v213 row_ror:8 row_mask:0xf bank_mask:0xf bound_ctrl:1
	v_pk_mul_f32 v[82:83], v[82:83], v[132:133] op_sel:[0,1] op_sel_hi:[1,1]
	v_pk_mul_f32 v[84:85], v[84:85], v[132:133] op_sel:[0,1] op_sel_hi:[1,1]
	v_add_f32_dpp v213, v213, v213 row_ror:4 row_mask:0xf bank_mask:0xf bound_ctrl:1
	v_pk_mul_f32 v[86:87], v[86:87], v[132:133] op_sel:[0,1] op_sel_hi:[1,1]
	v_pk_mul_f32 v[88:89], v[88:89], v[132:133] op_sel:[0,1] op_sel_hi:[1,1]
	v_add_f32_dpp v213, v213, v213 row_ror:2 row_mask:0xf bank_mask:0xf bound_ctrl:1
	v_pk_mul_f32 v[90:91], v[90:91], v[132:133] op_sel:[0,1] op_sel_hi:[1,1]
	v_pk_mul_f32 v[92:93], v[92:93], v[132:133] op_sel:[0,1] op_sel_hi:[1,1]
	v_add_f32_dpp v213, v213, v213 row_ror:1 row_mask:0xf bank_mask:0xf bound_ctrl:1
	v_pk_mul_f32 v[94:95], v[94:95], v[132:133] op_sel:[0,1] op_sel_hi:[1,1]
	v_pk_fma_f32 v[196:197], v[132:133], v[196:197], v[80:81] op_sel_hi:[0,1,1]
	s_and_saveexec_b64 s[8:9], s[44:45]
	ds_write_b32 v190, v213 offset:34880
	s_mov_b64 exec, s[8:9]
	v_pk_fma_f32 v[198:199], v[132:133], v[198:199], v[82:83] op_sel_hi:[0,1,1]
	v_pk_fma_f32 v[200:201], v[132:133], v[200:201], v[84:85] op_sel_hi:[0,1,1]
	v_pk_fma_f32 v[202:203], v[132:133], v[202:203], v[86:87] op_sel_hi:[0,1,1]
	v_pk_fma_f32 v[204:205], v[132:133], v[204:205], v[88:89] op_sel_hi:[0,1,1]
	v_pk_fma_f32 v[206:207], v[132:133], v[206:207], v[90:91] op_sel_hi:[0,1,1]
	v_pk_fma_f32 v[208:209], v[132:133], v[208:209], v[92:93] op_sel_hi:[0,1,1]
	v_pk_fma_f32 v[210:211], v[132:133], v[210:211], v[94:95] op_sel_hi:[0,1,1]
	s_waitcnt lgkmcnt(15)
	v_pk_fma_f32 v[128:129], v[64:65], v[196:197], v[214:215]
	v_pk_fma_f32 v[130:131], v[66:67], v[198:199], v[214:215]
	v_pk_fma_f32 v[128:129], v[68:69], v[200:201], v[128:129]
	v_pk_fma_f32 v[130:131], v[70:71], v[202:203], v[130:131]
	s_waitcnt lgkmcnt(14)
	v_pk_fma_f32 v[128:129], v[72:73], v[204:205], v[128:129]
	v_pk_fma_f32 v[130:131], v[74:75], v[206:207], v[130:131]
	s_waitcnt lgkmcnt(13)
	v_pk_fma_f32 v[128:129], v[76:77], v[208:209], v[128:129]
	v_pk_fma_f32 v[130:131], v[78:79], v[210:211], v[130:131]
	v_add_f32_e32 v128, v128, v129
	v_add_f32_e32 v130, v130, v131
	v_add_f32_e32 v212, v128, v130
	s_waitcnt lgkmcnt(6)
	v_mul_f32_e32 v155, v156, v157
	v_pk_mul_f32 v[112:113], v[112:113], v[154:155] op_sel:[0,1] op_sel_hi:[1,1]
	v_add_f32_dpp v212, v212, v212 row_ror:8 row_mask:0xf bank_mask:0xf bound_ctrl:1
	v_pk_mul_f32 v[114:115], v[114:115], v[154:155] op_sel:[0,1] op_sel_hi:[1,1]
	v_pk_mul_f32 v[116:117], v[116:117], v[154:155] op_sel:[0,1] op_sel_hi:[1,1]
	v_add_f32_dpp v212, v212, v212 row_ror:4 row_mask:0xf bank_mask:0xf bound_ctrl:1
	v_pk_mul_f32 v[118:119], v[118:119], v[154:155] op_sel:[0,1] op_sel_hi:[1,1]
	v_pk_mul_f32 v[120:121], v[120:121], v[154:155] op_sel:[0,1] op_sel_hi:[1,1]
	v_add_f32_dpp v212, v212, v212 row_ror:2 row_mask:0xf bank_mask:0xf bound_ctrl:1
	v_pk_mul_f32 v[122:123], v[122:123], v[154:155] op_sel:[0,1] op_sel_hi:[1,1]
	v_pk_mul_f32 v[124:125], v[124:125], v[154:155] op_sel:[0,1] op_sel_hi:[1,1]
	v_add_f32_dpp v212, v212, v212 row_ror:1 row_mask:0xf bank_mask:0xf bound_ctrl:1
	v_pk_mul_f32 v[126:127], v[126:127], v[154:155] op_sel:[0,1] op_sel_hi:[1,1]
	s_waitcnt lgkmcnt(5)
	v_pk_fma_f32 v[196:197], v[154:155], v[196:197], v[112:113] op_sel_hi:[0,1,1]
	s_and_saveexec_b64 s[8:9], s[44:45]
	ds_write_b32 v190, v212 offset:34944
	s_mov_b64 exec, s[8:9]
	v_pk_fma_f32 v[198:199], v[154:155], v[198:199], v[114:115] op_sel_hi:[0,1,1]
	v_pk_fma_f32 v[200:201], v[154:155], v[200:201], v[116:117] op_sel_hi:[0,1,1]
	v_pk_fma_f32 v[202:203], v[154:155], v[202:203], v[118:119] op_sel_hi:[0,1,1]
	v_pk_fma_f32 v[204:205], v[154:155], v[204:205], v[120:121] op_sel_hi:[0,1,1]
	v_pk_fma_f32 v[206:207], v[154:155], v[206:207], v[122:123] op_sel_hi:[0,1,1]
	v_pk_fma_f32 v[208:209], v[154:155], v[208:209], v[124:125] op_sel_hi:[0,1,1]
	v_pk_fma_f32 v[210:211], v[154:155], v[210:211], v[126:127] op_sel_hi:[0,1,1]
	s_waitcnt lgkmcnt(5)
	v_pk_fma_f32 v[128:129], v[96:97], v[196:197], v[214:215]
	v_pk_fma_f32 v[130:131], v[98:99], v[198:199], v[214:215]
	s_waitcnt lgkmcnt(4)
	v_pk_fma_f32 v[128:129], v[100:101], v[200:201], v[128:129]
	v_pk_fma_f32 v[130:131], v[102:103], v[202:203], v[130:131]
	s_waitcnt lgkmcnt(3)
	v_pk_fma_f32 v[128:129], v[104:105], v[204:205], v[128:129]
	v_pk_fma_f32 v[130:131], v[106:107], v[206:207], v[130:131]
	s_waitcnt lgkmcnt(2)
	v_pk_fma_f32 v[128:129], v[108:109], v[208:209], v[128:129]
	v_pk_fma_f32 v[130:131], v[110:111], v[210:211], v[130:131]
	v_add_f32_e32 v128, v128, v129
	v_add_f32_e32 v130, v130, v131
	v_add_f32_e32 v213, v128, v130
	s_nop 1
	v_add_f32_dpp v213, v213, v213 row_ror:8 row_mask:0xf bank_mask:0xf bound_ctrl:1
	s_nop 1
	v_add_f32_dpp v213, v213, v213 row_ror:4 row_mask:0xf bank_mask:0xf bound_ctrl:1
	s_nop 1
	v_add_f32_dpp v213, v213, v213 row_ror:2 row_mask:0xf bank_mask:0xf bound_ctrl:1
	s_nop 1
	v_add_f32_dpp v213, v213, v213 row_ror:1 row_mask:0xf bank_mask:0xf bound_ctrl:1
	s_and_saveexec_b64 s[8:9], s[44:45]
	ds_write_b32 v190, v213 offset:35008
	s_mov_b64 exec, s[8:9]
	s_waitcnt vmcnt(7)
	ds_write_b128 v188, v[32:35]
	s_waitcnt vmcnt(5)
	ds_write_b128 v191, v[40:43]
	ds_write_b128 v188, v[36:39] offset:8192
	s_waitcnt vmcnt(4)
	ds_write_b128 v191, v[44:47] offset:8192
	s_and_saveexec_b64 s[8:9], s[40:41]
	ds_write_b32 v145, v186 offset:16384
	s_or_b64 exec, exec, s[8:9]
	s_and_saveexec_b64 s[8:9], s[42:43]
	s_cbranch_execz .LBB0_1209
	v_add_f32_e32 v64, v178, v189
	v_mul_f32_e64 v65, |v64|, s62
	v_exp_f32_e32 v65, v65
	v_min_f32_e32 v64, 0, v64
	v_add_f32_e32 v65, 1.0, v65
	v_cmp_gt_f32_e32 vcc, s5, v65
	s_nop 1
	v_cndmask_b32_e64 v66, 0, 32, vcc
	v_ldexp_f32 v65, v65, v66
	v_log_f32_e32 v65, v65
	v_cndmask_b32_e32 v67, 0, v171, vcc
	v_add_f32_e32 v66, v147, v187
	v_mul_f32_e32 v68, 0x3f317217, v65
	v_fma_f32 v68, v65, s76, -v68
	v_fmac_f32_e32 v68, 0x3377d1cf, v65
	v_fmac_f32_e32 v68, 0x3f317217, v65
	v_cmp_lt_f32_e64 vcc, |v65|, s77
	s_nop 1
	v_cndmask_b32_e32 v65, v65, v68, vcc
	v_sub_f32_e32 v65, v65, v67
	v_sub_f32_e32 v64, v64, v65
	v_add_u32_e32 v65, 0x4000, v145
	ds_write2_b32 v65, v66, v64 offset0:128 offset1:144

.LBB0_1215:
	s_and_saveexec_b64 s[8:9], s[40:41]
	s_cbranch_execz .LBB0_1222
	ds_read_b32 v66, v145 offset:34560
	v_add3_u32 v64, v149, s85, 8
	v_ashrrev_i32_e32 v65, 31, v64
	v_lshlrev_b64 v[64:65], 12, v[64:65]
	v_lshl_add_u64 v[64:65], v[152:153], 0, v[64:65]
	s_waitcnt lgkmcnt(0)
	global_store_dword v[64:65], v66, off
.LBB0_1222:
	s_or_b64 exec, exec, s[8:9]
	s_waitcnt lgkmcnt(0)
	v_mov_b32_e32 v214, 0
	v_mov_b32_e32 v215, 0
	ds_read_b128 v[80:83], v194 offset:8192
	ds_read_b128 v[84:87], v194 offset:8448
	ds_read_b128 v[88:91], v194 offset:8704
	ds_read_b128 v[92:95], v194 offset:8960
	ds_read_b32 v134, v140 offset:35136
	ds_read_b32 v135, v190 offset:16384
	ds_read_b32 v132, v140 offset:35072
	ds_read_b128 v[64:67], v194
	ds_read_b128 v[68:71], v194 offset:256
	ds_read_b128 v[72:75], v194 offset:512
	ds_read_b128 v[76:79], v194 offset:768
	ds_read_b128 v[112:115], v194 offset:9216
	ds_read_b128 v[116:119], v194 offset:9472
	ds_read_b128 v[120:123], v194 offset:9728
	ds_read_b128 v[124:127], v194 offset:9984
	ds_read_b32 v156, v140 offset:35140
	ds_read_b32 v157, v190 offset:16448
	ds_read_b32 v154, v140 offset:35076
	ds_read_b128 v[96:99], v194 offset:1024
	ds_read_b128 v[100:103], v194 offset:1280
	ds_read_b128 v[104:107], v194 offset:1536
	ds_read_b128 v[108:111], v194 offset:1792
	s_waitcnt lgkmcnt(15)
	v_mul_f32_e32 v133, v134, v135
	v_pk_mul_f32 v[80:81], v[80:81], v[132:133] op_sel:[0,1] op_sel_hi:[1,1]
	v_pk_mul_f32 v[82:83], v[82:83], v[132:133] op_sel:[0,1] op_sel_hi:[1,1]
	v_pk_mul_f32 v[84:85], v[84:85], v[132:133] op_sel:[0,1] op_sel_hi:[1,1]
	v_pk_mul_f32 v[86:87], v[86:87], v[132:133] op_sel:[0,1] op_sel_hi:[1,1]
	v_pk_mul_f32 v[88:89], v[88:89], v[132:133] op_sel:[0,1] op_sel_hi:[1,1]
	v_pk_mul_f32 v[90:91], v[90:91], v[132:133] op_sel:[0,1] op_sel_hi:[1,1]
	v_pk_mul_f32 v[92:93], v[92:93], v[132:133] op_sel:[0,1] op_sel_hi:[1,1]
	v_pk_mul_f32 v[94:95], v[94:95], v[132:133] op_sel:[0,1] op_sel_hi:[1,1]
	v_pk_fma_f32 v[196:197], v[132:133], v[196:197], v[80:81] op_sel_hi:[0,1,1]
	v_pk_fma_f32 v[198:199], v[132:133], v[198:199], v[82:83] op_sel_hi:[0,1,1]
	v_pk_fma_f32 v[200:201], v[132:133], v[200:201], v[84:85] op_sel_hi:[0,1,1]
	v_pk_fma_f32 v[202:203], v[132:133], v[202:203], v[86:87] op_sel_hi:[0,1,1]
	v_pk_fma_f32 v[204:205], v[132:133], v[204:205], v[88:89] op_sel_hi:[0,1,1]
	v_pk_fma_f32 v[206:207], v[132:133], v[206:207], v[90:91] op_sel_hi:[0,1,1]
	v_pk_fma_f32 v[208:209], v[132:133], v[208:209], v[92:93] op_sel_hi:[0,1,1]
	v_pk_fma_f32 v[210:211], v[132:133], v[210:211], v[94:95] op_sel_hi:[0,1,1]
	s_waitcnt lgkmcnt(14)
	v_pk_fma_f32 v[128:129], v[64:65], v[196:197], v[214:215]
	v_pk_fma_f32 v[130:131], v[66:67], v[198:199], v[214:215]
	s_waitcnt lgkmcnt(13)
	v_pk_fma_f32 v[128:129], v[68:69], v[200:201], v[128:129]
	v_pk_fma_f32 v[130:131], v[70:71], v[202:203], v[130:131]
	s_waitcnt lgkmcnt(12)
	v_pk_fma_f32 v[128:129], v[72:73], v[204:205], v[128:129]
	v_pk_fma_f32 v[130:131], v[74:75], v[206:207], v[130:131]
	s_waitcnt lgkmcnt(11)
	v_pk_fma_f32 v[128:129], v[76:77], v[208:209], v[128:129]
	v_pk_fma_f32 v[130:131], v[78:79], v[210:211], v[130:131]
	v_add_f32_e32 v128, v128, v129
	v_add_f32_e32 v130, v130, v131
	v_add_f32_e32 v212, v128, v130
	ds_read_b128 v[80:83], v194 offset:10240
	ds_read_b128 v[84:87], v194 offset:10496
	ds_read_b128 v[88:91], v194 offset:10752
	ds_read_b128 v[92:95], v194 offset:11008
	ds_read_b32 v134, v140 offset:35144
	ds_read_b32 v135, v190 offset:16512
	ds_read_b32 v132, v140 offset:35080
	ds_read_b128 v[64:67], v194 offset:2048
	ds_read_b128 v[68:71], v194 offset:2304
	ds_read_b128 v[72:75], v194 offset:2560
	ds_read_b128 v[76:79], v194 offset:2816
	s_waitcnt lgkmcnt(15)
	v_mul_f32_e32 v155, v156, v157
	v_pk_mul_f32 v[112:113], v[112:113], v[154:155] op_sel:[0,1] op_sel_hi:[1,1]
	v_add_f32_dpp v212, v212, v212 row_ror:8 row_mask:0xf bank_mask:0xf bound_ctrl:1
	v_pk_mul_f32 v[114:115], v[114:115], v[154:155] op_sel:[0,1] op_sel_hi:[1,1]
	v_pk_mul_f32 v[116:117], v[116:117], v[154:155] op_sel:[0,1] op_sel_hi:[1,1]
	v_add_f32_dpp v212, v212, v212 row_ror:4 row_mask:0xf bank_mask:0xf bound_ctrl:1
	v_pk_mul_f32 v[118:119], v[118:119], v[154:155] op_sel:[0,1] op_sel_hi:[1,1]
	v_pk_mul_f32 v[120:121], v[120:121], v[154:155] op_sel:[0,1] op_sel_hi:[1,1]
	v_add_f32_dpp v212, v212, v212 row_ror:2 row_mask:0xf bank_mask:0xf bound_ctrl:1
	v_pk_mul_f32 v[122:123], v[122:123], v[154:155] op_sel:[0,1] op_sel_hi:[1,1]
	v_pk_mul_f32 v[124:125], v[124:125], v[154:155] op_sel:[0,1] op_sel_hi:[1,1]
	v_add_f32_dpp v212, v212, v212 row_ror:1 row_mask:0xf bank_mask:0xf bound_ctrl:1
	v_pk_mul_f32 v[126:127], v[126:127], v[154:155] op_sel:[0,1] op_sel_hi:[1,1]
	v_pk_fma_f32 v[196:197], v[154:155], v[196:197], v[112:113] op_sel_hi:[0,1,1]
	s_and_saveexec_b64 s[8:9], s[44:45]
	ds_write_b32 v190, v212 offset:34048
	s_mov_b64 exec, s[8:9]
	v_pk_fma_f32 v[198:199], v[154:155], v[198:199], v[114:115] op_sel_hi:[0,1,1]
	v_pk_fma_f32 v[200:201], v[154:155], v[200:201], v[116:117] op_sel_hi:[0,1,1]
	v_pk_fma_f32 v[202:203], v[154:155], v[202:203], v[118:119] op_sel_hi:[0,1,1]
	v_pk_fma_f32 v[204:205], v[154:155], v[204:205], v[120:121] op_sel_hi:[0,1,1]
	v_pk_fma_f32 v[206:207], v[154:155], v[206:207], v[122:123] op_sel_hi:[0,1,1]
	v_pk_fma_f32 v[208:209], v[154:155], v[208:209], v[124:125] op_sel_hi:[0,1,1]
	v_pk_fma_f32 v[210:211], v[154:155], v[210:211], v[126:127] op_sel_hi:[0,1,1]
	s_waitcnt lgkmcnt(15)
	v_pk_fma_f32 v[128:129], v[96:97], v[196:197], v[214:215]
	v_pk_fma_f32 v[130:131], v[98:99], v[198:199], v[214:215]
	s_waitcnt lgkmcnt(14)
	v_pk_fma_f32 v[128:129], v[100:101], v[200:201], v[128:129]
	v_pk_fma_f32 v[130:131], v[102:103], v[202:203], v[130:131]
	s_waitcnt lgkmcnt(13)
	v_pk_fma_f32 v[128:129], v[104:105], v[204:205], v[128:129]
	v_pk_fma_f32 v[130:131], v[106:107], v[206:207], v[130:131]
	s_waitcnt lgkmcnt(12)
	v_pk_fma_f32 v[128:129], v[108:109], v[208:209], v[128:129]
	v_pk_fma_f32 v[130:131], v[110:111], v[210:211], v[130:131]
	v_add_f32_e32 v128, v128, v129
	v_add_f32_e32 v130, v130, v131
	v_add_f32_e32 v213, v128, v130
	ds_read_b128 v[112:115], v194 offset:11264
	ds_read_b128 v[116:119], v194 offset:11520
	ds_read_b128 v[120:123], v194 offset:11776
	ds_read_b128 v[124:127], v194 offset:12032
	ds_read_b32 v156, v140 offset:35148
	ds_read_b32 v157, v190 offset:16576
	ds_read_b32 v154, v140 offset:35084
	ds_read_b128 v[96:99], v194 offset:3072
	ds_read_b128 v[100:103], v194 offset:3328
	ds_read_b128 v[104:107], v194 offset:3584
	ds_read_b128 v[108:111], v194 offset:3840
	s_waitcnt lgkmcnt(15)
	v_mul_f32_e32 v133, v134, v135
	v_pk_mul_f32 v[80:81], v[80:81], v[132:133] op_sel:[0,1] op_sel_hi:[1,1]
	v_add_f32_dpp v213, v213, v213 row_ror:8 row_mask:0xf bank_mask:0xf bound_ctrl:1
	v_pk_mul_f32 v[82:83], v[82:83], v[132:133] op_sel:[0,1] op_sel_hi:[1,1]
	v_pk_mul_f32 v[84:85], v[84:85], v[132:133] op_sel:[0,1] op_sel_hi:[1,1]
	v_add_f32_dpp v213, v213, v213 row_ror:4 row_mask:0xf bank_mask:0xf bound_ctrl:1
	v_pk_mul_f32 v[86:87], v[86:87], v[132:133] op_sel:[0,1] op_sel_hi:[1,1]
	v_pk_mul_f32 v[88:89], v[88:89], v[132:133] op_sel:[0,1] op_sel_hi:[1,1]
	v_add_f32_dpp v213, v213, v213 row_ror:2 row_mask:0xf bank_mask:0xf bound_ctrl:1
	v_pk_mul_f32 v[90:91], v[90:91], v[132:133] op_sel:[0,1] op_sel_hi:[1,1]
	v_pk_mul_f32 v[92:93], v[92:93], v[132:133] op_sel:[0,1] op_sel_hi:[1,1]
	v_add_f32_dpp v213, v213, v213 row_ror:1 row_mask:0xf bank_mask:0xf bound_ctrl:1
	v_pk_mul_f32 v[94:95], v[94:95], v[132:133] op_sel:[0,1] op_sel_hi:[1,1]
	v_pk_fma_f32 v[196:197], v[132:133], v[196:197], v[80:81] op_sel_hi:[0,1,1]
	s_and_saveexec_b64 s[8:9], s[44:45]
	ds_write_b32 v190, v213 offset:34112
	s_mov_b64 exec, s[8:9]
	v_pk_fma_f32 v[198:199], v[132:133], v[198:199], v[82:83] op_sel_hi:[0,1,1]
	v_pk_fma_f32 v[200:201], v[132:133], v[200:201], v[84:85] op_sel_hi:[0,1,1]
	v_pk_fma_f32 v[202:203], v[132:133], v[202:203], v[86:87] op_sel_hi:[0,1,1]
	v_pk_fma_f32 v[204:205], v[132:133], v[204:205], v[88:89] op_sel_hi:[0,1,1]
	v_pk_fma_f32 v[206:207], v[132:133], v[206:207], v[90:91] op_sel_hi:[0,1,1]
	v_pk_fma_f32 v[208:209], v[132:133], v[208:209], v[92:93] op_sel_hi:[0,1,1]
	v_pk_fma_f32 v[210:211], v[132:133], v[210:211], v[94:95] op_sel_hi:[0,1,1]
	s_waitcnt lgkmcnt(15)
	v_pk_fma_f32 v[128:129], v[64:65], v[196:197], v[214:215]
	v_pk_fma_f32 v[130:131], v[66:67], v[198:199], v[214:215]
	v_pk_fma_f32 v[128:129], v[68:69], v[200:201], v[128:129]
	v_pk_fma_f32 v[130:131], v[70:71], v[202:203], v[130:131]
	s_waitcnt lgkmcnt(14)
	v_pk_fma_f32 v[128:129], v[72:73], v[204:205], v[128:129]
	v_pk_fma_f32 v[130:131], v[74:75], v[206:207], v[130:131]
	s_waitcnt lgkmcnt(13)
	v_pk_fma_f32 v[128:129], v[76:77], v[208:209], v[128:129]
	v_pk_fma_f32 v[130:131], v[78:79], v[210:211], v[130:131]
	v_add_f32_e32 v128, v128, v129
	v_add_f32_e32 v130, v130, v131
	v_add_f32_e32 v212, v128, v130
	ds_read_b128 v[80:83], v194 offset:12288
	ds_read_b128 v[84:87], v194 offset:12544
	ds_read_b128 v[88:91], v194 offset:12800
	ds_read_b128 v[92:95], v194 offset:13056
	ds_read_b32 v134, v140 offset:35152
	ds_read_b32 v135, v190 offset:16640
	ds_read_b32 v132, v140 offset:35088
	ds_read_b128 v[64:67], v194 offset:4096
	ds_read_b128 v[68:71], v194 offset:4352
	ds_read_b128 v[72:75], v194 offset:4608
	ds_read_b128 v[76:79], v194 offset:4864
	s_waitcnt lgkmcnt(15)
	v_mul_f32_e32 v155, v156, v157
	v_pk_mul_f32 v[112:113], v[112:113], v[154:155] op_sel:[0,1] op_sel_hi:[1,1]
	v_add_f32_dpp v212, v212, v212 row_ror:8 row_mask:0xf bank_mask:0xf bound_ctrl:1
	v_pk_mul_f32 v[114:115], v[114:115], v[154:155] op_sel:[0,1] op_sel_hi:[1,1]
	v_pk_mul_f32 v[116:117], v[116:117], v[154:155] op_sel:[0,1] op_sel_hi:[1,1]
	v_add_f32_dpp v212, v212, v212 row_ror:4 row_mask:0xf bank_mask:0xf bound_ctrl:1
	v_pk_mul_f32 v[118:119], v[118:119], v[154:155] op_sel:[0,1] op_sel_hi:[1,1]
	v_pk_mul_f32 v[120:121], v[120:121], v[154:155] op_sel:[0,1] op_sel_hi:[1,1]
	v_add_f32_dpp v212, v212, v212 row_ror:2 row_mask:0xf bank_mask:0xf bound_ctrl:1
	v_pk_mul_f32 v[122:123], v[122:123], v[154:155] op_sel:[0,1] op_sel_hi:[1,1]
	v_pk_mul_f32 v[124:125], v[124:125], v[154:155] op_sel:[0,1] op_sel_hi:[1,1]
	v_add_f32_dpp v212, v212, v212 row_ror:1 row_mask:0xf bank_mask:0xf bound_ctrl:1
	v_pk_mul_f32 v[126:127], v[126:127], v[154:155] op_sel:[0,1] op_sel_hi:[1,1]
	v_pk_fma_f32 v[196:197], v[154:155], v[196:197], v[112:113] op_sel_hi:[0,1,1]
	s_and_saveexec_b64 s[8:9], s[44:45]
	ds_write_b32 v190, v212 offset:34176
	s_mov_b64 exec, s[8:9]
	v_pk_fma_f32 v[198:199], v[154:155], v[198:199], v[114:115] op_sel_hi:[0,1,1]
	v_pk_fma_f32 v[200:201], v[154:155], v[200:201], v[116:117] op_sel_hi:[0,1,1]
	v_pk_fma_f32 v[202:203], v[154:155], v[202:203], v[118:119] op_sel_hi:[0,1,1]
	v_pk_fma_f32 v[204:205], v[154:155], v[204:205], v[120:121] op_sel_hi:[0,1,1]
	v_pk_fma_f32 v[206:207], v[154:155], v[206:207], v[122:123] op_sel_hi:[0,1,1]
	v_pk_fma_f32 v[208:209], v[154:155], v[208:209], v[124:125] op_sel_hi:[0,1,1]
	v_pk_fma_f32 v[210:211], v[154:155], v[210:211], v[126:127] op_sel_hi:[0,1,1]
	s_waitcnt lgkmcnt(15)
	v_pk_fma_f32 v[128:129], v[96:97], v[196:197], v[214:215]
	v_pk_fma_f32 v[130:131], v[98:99], v[198:199], v[214:215]
	v_pk_fma_f32 v[128:129], v[100:101], v[200:201], v[128:129]
	v_pk_fma_f32 v[130:131], v[102:103], v[202:203], v[130:131]
	s_waitcnt lgkmcnt(14)
	v_pk_fma_f32 v[128:129], v[104:105], v[204:205], v[128:129]
	v_pk_fma_f32 v[130:131], v[106:107], v[206:207], v[130:131]
	s_waitcnt lgkmcnt(13)
	v_pk_fma_f32 v[128:129], v[108:109], v[208:209], v[128:129]
	v_pk_fma_f32 v[130:131], v[110:111], v[210:211], v[130:131]
	v_add_f32_e32 v128, v128, v129
	v_add_f32_e32 v130, v130, v131
	v_add_f32_e32 v213, v128, v130
	ds_read_b128 v[112:115], v194 offset:13312
	ds_read_b128 v[116:119], v194 offset:13568
	ds_read_b128 v[120:123], v194 offset:13824
	ds_read_b128 v[124:127], v194 offset:14080
	ds_read_b32 v156, v140 offset:35156
	ds_read_b32 v157, v190 offset:16704
	ds_read_b32 v154, v140 offset:35092
	ds_read_b128 v[96:99], v194 offset:5120
	ds_read_b128 v[100:103], v194 offset:5376
	ds_read_b128 v[104:107], v194 offset:5632
	ds_read_b128 v[108:111], v194 offset:5888
	s_waitcnt lgkmcnt(15)
	v_mul_f32_e32 v133, v134, v135
	v_pk_mul_f32 v[80:81], v[80:81], v[132:133] op_sel:[0,1] op_sel_hi:[1,1]
	v_add_f32_dpp v213, v213, v213 row_ror:8 row_mask:0xf bank_mask:0xf bound_ctrl:1
	v_pk_mul_f32 v[82:83], v[82:83], v[132:133] op_sel:[0,1] op_sel_hi:[1,1]
	v_pk_mul_f32 v[84:85], v[84:85], v[132:133] op_sel:[0,1] op_sel_hi:[1,1]
	v_add_f32_dpp v213, v213, v213 row_ror:4 row_mask:0xf bank_mask:0xf bound_ctrl:1
	v_pk_mul_f32 v[86:87], v[86:87], v[132:133] op_sel:[0,1] op_sel_hi:[1,1]
	v_pk_mul_f32 v[88:89], v[88:89], v[132:133] op_sel:[0,1] op_sel_hi:[1,1]
	v_add_f32_dpp v213, v213, v213 row_ror:2 row_mask:0xf bank_mask:0xf bound_ctrl:1
	v_pk_mul_f32 v[90:91], v[90:91], v[132:133] op_sel:[0,1] op_sel_hi:[1,1]
	v_pk_mul_f32 v[92:93], v[92:93], v[132:133] op_sel:[0,1] op_sel_hi:[1,1]
	v_add_f32_dpp v213, v213, v213 row_ror:1 row_mask:0xf bank_mask:0xf bound_ctrl:1
	v_pk_mul_f32 v[94:95], v[94:95], v[132:133] op_sel:[0,1] op_sel_hi:[1,1]
	v_pk_fma_f32 v[196:197], v[132:133], v[196:197], v[80:81] op_sel_hi:[0,1,1]
	s_and_saveexec_b64 s[8:9], s[44:45]
	ds_write_b32 v190, v213 offset:34240
	s_mov_b64 exec, s[8:9]
	v_pk_fma_f32 v[198:199], v[132:133], v[198:199], v[82:83] op_sel_hi:[0,1,1]
	v_pk_fma_f32 v[200:201], v[132:133], v[200:201], v[84:85] op_sel_hi:[0,1,1]
	v_pk_fma_f32 v[202:203], v[132:133], v[202:203], v[86:87] op_sel_hi:[0,1,1]
	v_pk_fma_f32 v[204:205], v[132:133], v[204:205], v[88:89] op_sel_hi:[0,1,1]
	v_pk_fma_f32 v[206:207], v[132:133], v[206:207], v[90:91] op_sel_hi:[0,1,1]
	v_pk_fma_f32 v[208:209], v[132:133], v[208:209], v[92:93] op_sel_hi:[0,1,1]
	v_pk_fma_f32 v[210:211], v[132:133], v[210:211], v[94:95] op_sel_hi:[0,1,1]
	s_waitcnt lgkmcnt(15)
	v_pk_fma_f32 v[128:129], v[64:65], v[196:197], v[214:215]
	v_pk_fma_f32 v[130:131], v[66:67], v[198:199], v[214:215]
	v_pk_fma_f32 v[128:129], v[68:69], v[200:201], v[128:129]
	v_pk_fma_f32 v[130:131], v[70:71], v[202:203], v[130:131]
	s_waitcnt lgkmcnt(14)
	v_pk_fma_f32 v[128:129], v[72:73], v[204:205], v[128:129]
	v_pk_fma_f32 v[130:131], v[74:75], v[206:207], v[130:131]
	s_waitcnt lgkmcnt(13)
	v_pk_fma_f32 v[128:129], v[76:77], v[208:209], v[128:129]
	v_pk_fma_f32 v[130:131], v[78:79], v[210:211], v[130:131]
	v_add_f32_e32 v128, v128, v129
	v_add_f32_e32 v130, v130, v131
	v_add_f32_e32 v212, v128, v130
	ds_read_b128 v[80:83], v194 offset:14336
	ds_read_b128 v[84:87], v194 offset:14592
	ds_read_b128 v[88:91], v194 offset:14848
	ds_read_b128 v[92:95], v194 offset:15104
	ds_read_b32 v134, v140 offset:35160
	ds_read_b32 v135, v190 offset:16768
	ds_read_b32 v132, v140 offset:35096
	ds_read_b128 v[64:67], v194 offset:6144
	ds_read_b128 v[68:71], v194 offset:6400
	ds_read_b128 v[72:75], v194 offset:6656
	ds_read_b128 v[76:79], v194 offset:6912
	s_waitcnt lgkmcnt(15)
	v_mul_f32_e32 v155, v156, v157
	v_pk_mul_f32 v[112:113], v[112:113], v[154:155] op_sel:[0,1] op_sel_hi:[1,1]
	v_add_f32_dpp v212, v212, v212 row_ror:8 row_mask:0xf bank_mask:0xf bound_ctrl:1
	v_pk_mul_f32 v[114:115], v[114:115], v[154:155] op_sel:[0,1] op_sel_hi:[1,1]
	v_pk_mul_f32 v[116:117], v[116:117], v[154:155] op_sel:[0,1] op_sel_hi:[1,1]
	v_add_f32_dpp v212, v212, v212 row_ror:4 row_mask:0xf bank_mask:0xf bound_ctrl:1
	v_pk_mul_f32 v[118:119], v[118:119], v[154:155] op_sel:[0,1] op_sel_hi:[1,1]
	v_pk_mul_f32 v[120:121], v[120:121], v[154:155] op_sel:[0,1] op_sel_hi:[1,1]
	v_add_f32_dpp v212, v212, v212 row_ror:2 row_mask:0xf bank_mask:0xf bound_ctrl:1
	v_pk_mul_f32 v[122:123], v[122:123], v[154:155] op_sel:[0,1] op_sel_hi:[1,1]
	v_pk_mul_f32 v[124:125], v[124:125], v[154:155] op_sel:[0,1] op_sel_hi:[1,1]
	v_add_f32_dpp v212, v212, v212 row_ror:1 row_mask:0xf bank_mask:0xf bound_ctrl:1
	v_pk_mul_f32 v[126:127], v[126:127], v[154:155] op_sel:[0,1] op_sel_hi:[1,1]
	v_pk_fma_f32 v[196:197], v[154:155], v[196:197], v[112:113] op_sel_hi:[0,1,1]
	s_and_saveexec_b64 s[8:9], s[44:45]
	ds_write_b32 v190, v212 offset:34304
	s_mov_b64 exec, s[8:9]
	v_pk_fma_f32 v[198:199], v[154:155], v[198:199], v[114:115] op_sel_hi:[0,1,1]
	v_pk_fma_f32 v[200:201], v[154:155], v[200:201], v[116:117] op_sel_hi:[0,1,1]
	v_pk_fma_f32 v[202:203], v[154:155], v[202:203], v[118:119] op_sel_hi:[0,1,1]
	v_pk_fma_f32 v[204:205], v[154:155], v[204:205], v[120:121] op_sel_hi:[0,1,1]
	v_pk_fma_f32 v[206:207], v[154:155], v[206:207], v[122:123] op_sel_hi:[0,1,1]
	v_pk_fma_f32 v[208:209], v[154:155], v[208:209], v[124:125] op_sel_hi:[0,1,1]
	v_pk_fma_f32 v[210:211], v[154:155], v[210:211], v[126:127] op_sel_hi:[0,1,1]
	s_waitcnt lgkmcnt(15)
	v_pk_fma_f32 v[128:129], v[96:97], v[196:197], v[214:215]
	v_pk_fma_f32 v[130:131], v[98:99], v[198:199], v[214:215]
	v_pk_fma_f32 v[128:129], v[100:101], v[200:201], v[128:129]
	v_pk_fma_f32 v[130:131], v[102:103], v[202:203], v[130:131]
	s_waitcnt lgkmcnt(14)
	v_pk_fma_f32 v[128:129], v[104:105], v[204:205], v[128:129]
	v_pk_fma_f32 v[130:131], v[106:107], v[206:207], v[130:131]
	s_waitcnt lgkmcnt(13)
	v_pk_fma_f32 v[128:129], v[108:109], v[208:209], v[128:129]
	v_pk_fma_f32 v[130:131], v[110:111], v[210:211], v[130:131]
	v_add_f32_e32 v128, v128, v129
	v_add_f32_e32 v130, v130, v131
	v_add_f32_e32 v213, v128, v130
	ds_read_b128 v[112:115], v194 offset:15360
	ds_read_b128 v[116:119], v194 offset:15616
	ds_read_b128 v[120:123], v194 offset:15872
	ds_read_b128 v[124:127], v194 offset:16128
	ds_read_b32 v156, v140 offset:35164
	ds_read_b32 v157, v190 offset:16832
	ds_read_b32 v154, v140 offset:35100
	ds_read_b128 v[96:99], v194 offset:7168
	ds_read_b128 v[100:103], v194 offset:7424
	ds_read_b128 v[104:107], v194 offset:7680
	ds_read_b128 v[108:111], v194 offset:7936
	s_waitcnt lgkmcnt(15)
	v_mul_f32_e32 v133, v134, v135
	v_pk_mul_f32 v[80:81], v[80:81], v[132:133] op_sel:[0,1] op_sel_hi:[1,1]
	v_add_f32_dpp v213, v213, v213 row_ror:8 row_mask:0xf bank_mask:0xf bound_ctrl:1
	v_pk_mul_f32 v[82:83], v[82:83], v[132:133] op_sel:[0,1] op_sel_hi:[1,1]
	v_pk_mul_f32 v[84:85], v[84:85], v[132:133] op_sel:[0,1] op_sel_hi:[1,1]
	v_add_f32_dpp v213, v213, v213 row_ror:4 row_mask:0xf bank_mask:0xf bound_ctrl:1
	v_pk_mul_f32 v[86:87], v[86:87], v[132:133] op_sel:[0,1] op_sel_hi:[1,1]
	v_pk_mul_f32 v[88:89], v[88:89], v[132:133] op_sel:[0,1] op_sel_hi:[1,1]
	v_add_f32_dpp v213, v213, v213 row_ror:2 row_mask:0xf bank_mask:0xf bound_ctrl:1
	v_pk_mul_f32 v[90:91], v[90:91], v[132:133] op_sel:[0,1] op_sel_hi:[1,1]
	v_pk_mul_f32 v[92:93], v[92:93], v[132:133] op_sel:[0,1] op_sel_hi:[1,1]
	v_add_f32_dpp v213, v213, v213 row_ror:1 row_mask:0xf bank_mask:0xf bound_ctrl:1
	v_pk_mul_f32 v[94:95], v[94:95], v[132:133] op_sel:[0,1] op_sel_hi:[1,1]
	v_pk_fma_f32 v[196:197], v[132:133], v[196:197], v[80:81] op_sel_hi:[0,1,1]
	s_and_saveexec_b64 s[8:9], s[44:45]
	ds_write_b32 v190, v213 offset:34368
	s_mov_b64 exec, s[8:9]
	v_pk_fma_f32 v[198:199], v[132:133], v[198:199], v[82:83] op_sel_hi:[0,1,1]
	v_pk_fma_f32 v[200:201], v[132:133], v[200:201], v[84:85] op_sel_hi:[0,1,1]
	v_pk_fma_f32 v[202:203], v[132:133], v[202:203], v[86:87] op_sel_hi:[0,1,1]
	v_pk_fma_f32 v[204:205], v[132:133], v[204:205], v[88:89] op_sel_hi:[0,1,1]
	v_pk_fma_f32 v[206:207], v[132:133], v[206:207], v[90:91] op_sel_hi:[0,1,1]
	v_pk_fma_f32 v[208:209], v[132:133], v[208:209], v[92:93] op_sel_hi:[0,1,1]
	v_pk_fma_f32 v[210:211], v[132:133], v[210:211], v[94:95] op_sel_hi:[0,1,1]
	s_waitcnt lgkmcnt(15)
	v_pk_fma_f32 v[128:129], v[64:65], v[196:197], v[214:215]
	v_pk_fma_f32 v[130:131], v[66:67], v[198:199], v[214:215]
	v_pk_fma_f32 v[128:129], v[68:69], v[200:201], v[128:129]
	v_pk_fma_f32 v[130:131], v[70:71], v[202:203], v[130:131]
	s_waitcnt lgkmcnt(14)
	v_pk_fma_f32 v[128:129], v[72:73], v[204:205], v[128:129]
	v_pk_fma_f32 v[130:131], v[74:75], v[206:207], v[130:131]
	s_waitcnt lgkmcnt(13)
	v_pk_fma_f32 v[128:129], v[76:77], v[208:209], v[128:129]
	v_pk_fma_f32 v[130:131], v[78:79], v[210:211], v[130:131]
	v_add_f32_e32 v128, v128, v129
	v_add_f32_e32 v130, v130, v131
	v_add_f32_e32 v212, v128, v130
	s_waitcnt lgkmcnt(6)
	v_mul_f32_e32 v155, v156, v157
	v_pk_mul_f32 v[112:113], v[112:113], v[154:155] op_sel:[0,1] op_sel_hi:[1,1]
	v_add_f32_dpp v212, v212, v212 row_ror:8 row_mask:0xf bank_mask:0xf bound_ctrl:1
	v_pk_mul_f32 v[114:115], v[114:115], v[154:155] op_sel:[0,1] op_sel_hi:[1,1]
	v_pk_mul_f32 v[116:117], v[116:117], v[154:155] op_sel:[0,1] op_sel_hi:[1,1]
	v_add_f32_dpp v212, v212, v212 row_ror:4 row_mask:0xf bank_mask:0xf bound_ctrl:1
	v_pk_mul_f32 v[118:119], v[118:119], v[154:155] op_sel:[0,1] op_sel_hi:[1,1]
	v_pk_mul_f32 v[120:121], v[120:121], v[154:155] op_sel:[0,1] op_sel_hi:[1,1]
	v_add_f32_dpp v212, v212, v212 row_ror:2 row_mask:0xf bank_mask:0xf bound_ctrl:1
	v_pk_mul_f32 v[122:123], v[122:123], v[154:155] op_sel:[0,1] op_sel_hi:[1,1]
	v_pk_mul_f32 v[124:125], v[124:125], v[154:155] op_sel:[0,1] op_sel_hi:[1,1]
	v_add_f32_dpp v212, v212, v212 row_ror:1 row_mask:0xf bank_mask:0xf bound_ctrl:1
	v_pk_mul_f32 v[126:127], v[126:127], v[154:155] op_sel:[0,1] op_sel_hi:[1,1]
	s_waitcnt lgkmcnt(5)
	v_pk_fma_f32 v[196:197], v[154:155], v[196:197], v[112:113] op_sel_hi:[0,1,1]
	s_and_saveexec_b64 s[8:9], s[44:45]
	ds_write_b32 v190, v212 offset:34432
	s_mov_b64 exec, s[8:9]
	v_pk_fma_f32 v[198:199], v[154:155], v[198:199], v[114:115] op_sel_hi:[0,1,1]
	v_pk_fma_f32 v[200:201], v[154:155], v[200:201], v[116:117] op_sel_hi:[0,1,1]
	v_pk_fma_f32 v[202:203], v[154:155], v[202:203], v[118:119] op_sel_hi:[0,1,1]
	v_pk_fma_f32 v[204:205], v[154:155], v[204:205], v[120:121] op_sel_hi:[0,1,1]
	v_pk_fma_f32 v[206:207], v[154:155], v[206:207], v[122:123] op_sel_hi:[0,1,1]
	v_pk_fma_f32 v[208:209], v[154:155], v[208:209], v[124:125] op_sel_hi:[0,1,1]
	v_pk_fma_f32 v[210:211], v[154:155], v[210:211], v[126:127] op_sel_hi:[0,1,1]
	s_waitcnt lgkmcnt(5)
	v_pk_fma_f32 v[128:129], v[96:97], v[196:197], v[214:215]
	v_pk_fma_f32 v[130:131], v[98:99], v[198:199], v[214:215]
	s_waitcnt lgkmcnt(4)
	v_pk_fma_f32 v[128:129], v[100:101], v[200:201], v[128:129]
	v_pk_fma_f32 v[130:131], v[102:103], v[202:203], v[130:131]
	s_waitcnt lgkmcnt(3)
	v_pk_fma_f32 v[128:129], v[104:105], v[204:205], v[128:129]
	v_pk_fma_f32 v[130:131], v[106:107], v[206:207], v[130:131]
	s_waitcnt lgkmcnt(2)
	v_pk_fma_f32 v[128:129], v[108:109], v[208:209], v[128:129]
	v_pk_fma_f32 v[130:131], v[110:111], v[210:211], v[130:131]
	v_add_f32_e32 v128, v128, v129
	v_add_f32_e32 v130, v130, v131
	v_add_f32_e32 v213, v128, v130
	s_nop 1
	v_add_f32_dpp v213, v213, v213 row_ror:8 row_mask:0xf bank_mask:0xf bound_ctrl:1
	s_nop 1
	v_add_f32_dpp v213, v213, v213 row_ror:4 row_mask:0xf bank_mask:0xf bound_ctrl:1
	s_nop 1
	v_add_f32_dpp v213, v213, v213 row_ror:2 row_mask:0xf bank_mask:0xf bound_ctrl:1
	s_nop 1
	v_add_f32_dpp v213, v213, v213 row_ror:1 row_mask:0xf bank_mask:0xf bound_ctrl:1
	s_and_saveexec_b64 s[8:9], s[44:45]
	ds_write_b32 v190, v213 offset:34496
	s_mov_b64 exec, s[8:9]
	s_waitcnt vmcnt(3)
	ds_write_b128 v188, v[48:51] offset:17024
	s_waitcnt vmcnt(1)
	ds_write_b128 v191, v[56:59] offset:17024
	ds_write_b128 v188, v[52:55] offset:25216
	s_waitcnt vmcnt(0)
	ds_write_b128 v191, v[60:63] offset:25216
	s_and_saveexec_b64 s[8:9], s[40:41]
	ds_write_b32 v145, v192 offset:33408
	s_or_b64 exec, exec, s[8:9]
	s_and_saveexec_b64 s[8:9], s[42:43]
	s_cbranch_execz .LBB0_1242
	v_add_f32_e32 v64, v178, v195
	v_mul_f32_e64 v65, |v64|, s62
	v_exp_f32_e32 v65, v65
	v_min_f32_e32 v64, 0, v64
	v_add_f32_e32 v65, 1.0, v65
	v_cmp_gt_f32_e32 vcc, s5, v65
	s_nop 1
	v_cndmask_b32_e64 v66, 0, 32, vcc
	v_ldexp_f32 v65, v65, v66
	v_log_f32_e32 v65, v65
	v_cndmask_b32_e32 v67, 0, v171, vcc
	v_add_f32_e32 v66, v147, v193
	v_mul_f32_e32 v68, 0x3f317217, v65
	v_fma_f32 v68, v65, s76, -v68
	v_fmac_f32_e32 v68, 0x3377d1cf, v65
	v_fmac_f32_e32 v68, 0x3f317217, v65
	v_cmp_lt_f32_e64 vcc, |v65|, s77
	s_nop 1
	v_cndmask_b32_e32 v65, v65, v68, vcc
	v_sub_f32_e32 v65, v65, v67
	v_sub_f32_e32 v64, v64, v65
	v_add_u32_e32 v65, 0x8400, v145
	ds_write2_b32 v65, v66, v64 offset0:32 offset1:48
.LBB0_1242:
	s_or_b64 exec, exec, s[8:9]
	s_and_saveexec_b64 s[8:9], s[46:47]
	s_cbranch_execz .LBB0_1253
	v_mov_b32_e32 v64, 0xf149f2ca
	v_mov_b32_e32 v65, 0
	s_and_saveexec_b64 s[64:65], s[42:43]
	v_add_u32_e32 v64, 0x8400, v145
	ds_read2_b32 v[64:65], v64 offset0:32 offset1:48
	s_or_b64 exec, exec, s[64:65]
	s_waitcnt lgkmcnt(0)
	v_add_f32_dpp v66, v64, v65 row_shr:1 row_mask:0xf bank_mask:0xf bound_ctrl:1
	v_max_f32_e32 v67, v64, v64
	v_max_f32_e32 v66, v66, v67
	v_cndmask_b32_e64 v66, v64, v66, s[48:49]
	v_add_f32_dpp v67, v65, v65 row_shr:1 row_mask:0xf bank_mask:0xf bound_ctrl:1
	v_cndmask_b32_e64 v67, v65, v67, s[48:49]
	v_max_f32_e32 v69, v66, v66
	s_nop 0
	v_add_f32_dpp v68, v66, v67 row_shr:2 row_mask:0xf bank_mask:0xf bound_ctrl:1
	v_max_f32_e32 v68, v68, v69
	v_add_f32_dpp v69, v67, v67 row_shr:2 row_mask:0xf bank_mask:0xf bound_ctrl:1
	v_cndmask_b32_e64 v67, v67, v69, s[50:51]
	v_cndmask_b32_e64 v66, v66, v68, s[50:51]
	v_max_f32_e32 v69, v66, v66
	s_nop 0
	v_add_f32_dpp v68, v66, v67 row_shr:4 row_mask:0xf bank_mask:0xf bound_ctrl:1
	v_max_f32_e32 v68, v68, v69
	v_cndmask_b32_e64 v66, v66, v68, s[52:53]
	ds_read_b32 v68, v140 offset:35328
	v_add_f32_dpp v69, v67, v67 row_shr:4 row_mask:0xf bank_mask:0xf bound_ctrl:1
	v_cndmask_b32_e64 v67, v67, v69, s[52:53]
	v_max_f32_e32 v66, v66, v66
	s_waitcnt lgkmcnt(0)
	v_add_f32_e32 v67, v68, v67
	v_max_f32_e32 v66, v67, v66
	v_mov_b32_e32 v67, 0
	v_sub_f32_e32 v64, v64, v66
	v_mul_f32_e32 v64, 0x3fb8aa3b, v64
	v_mov_b32_dpp v67, v66 row_shr:1 row_mask:0xf bank_mask:0xf
	v_cndmask_b32_e64 v67, v67, v68, s[38:39]
	v_add_f32_e32 v65, v65, v67
	v_sub_f32_e32 v65, v65, v66
	v_mul_f32_e32 v65, 0x3fb8aa3b, v65
	v_exp_f32_e32 v65, v65
	v_exp_f32_e32 v64, v64
	v_add_u32_e32 v67, 0x8800, v145
	ds_write2_b32 v67, v65, v64 offset0:160 offset1:176
	ds_write_b32 v145, v66 offset:35264
	s_and_b64 exec, exec, s[54:55]
	ds_write_b32 v140, v66 offset:35328

.LBB0_1248:
	s_and_saveexec_b64 s[8:9], s[40:41]
	s_cbranch_execz .LBB0_1255
	ds_read_b32 v66, v145 offset:34048
	v_add3_u32 v64, v149, s85, 16
	v_ashrrev_i32_e32 v65, 31, v64
	v_lshlrev_b64 v[64:65], 12, v[64:65]
	v_lshl_add_u64 v[64:65], v[152:153], 0, v[64:65]
	s_waitcnt lgkmcnt(0)
	global_store_dword v[64:65], v66, off
.LBB0_1255:
	s_or_b64 exec, exec, s[8:9]
	s_waitcnt lgkmcnt(0)
	v_mov_b32_e32 v214, 0
	v_mov_b32_e32 v215, 0
	ds_read_b128 v[80:83], v194 offset:25216
	ds_read_b128 v[84:87], v194 offset:25472
	ds_read_b128 v[88:91], v194 offset:25728
	ds_read_b128 v[92:95], v194 offset:25984
	ds_read_b32 v134, v140 offset:35520
	ds_read_b32 v135, v190 offset:33408
	ds_read_b32 v132, v140 offset:35456
	ds_read_b128 v[64:67], v194 offset:17024
	ds_read_b128 v[68:71], v194 offset:17280
	ds_read_b128 v[72:75], v194 offset:17536
	ds_read_b128 v[76:79], v194 offset:17792
	ds_read_b128 v[112:115], v194 offset:26240
	ds_read_b128 v[116:119], v194 offset:26496
	ds_read_b128 v[120:123], v194 offset:26752
	ds_read_b128 v[124:127], v194 offset:27008
	ds_read_b32 v156, v140 offset:35524
	ds_read_b32 v157, v190 offset:33472
	ds_read_b32 v154, v140 offset:35460
	ds_read_b128 v[96:99], v194 offset:18048
	ds_read_b128 v[100:103], v194 offset:18304
	ds_read_b128 v[104:107], v194 offset:18560
	ds_read_b128 v[108:111], v194 offset:18816
	s_waitcnt lgkmcnt(15)
	v_mul_f32_e32 v133, v134, v135
	v_pk_mul_f32 v[80:81], v[80:81], v[132:133] op_sel:[0,1] op_sel_hi:[1,1]
	v_pk_mul_f32 v[82:83], v[82:83], v[132:133] op_sel:[0,1] op_sel_hi:[1,1]
	v_pk_mul_f32 v[84:85], v[84:85], v[132:133] op_sel:[0,1] op_sel_hi:[1,1]
	v_pk_mul_f32 v[86:87], v[86:87], v[132:133] op_sel:[0,1] op_sel_hi:[1,1]
	v_pk_mul_f32 v[88:89], v[88:89], v[132:133] op_sel:[0,1] op_sel_hi:[1,1]
	v_pk_mul_f32 v[90:91], v[90:91], v[132:133] op_sel:[0,1] op_sel_hi:[1,1]
	v_pk_mul_f32 v[92:93], v[92:93], v[132:133] op_sel:[0,1] op_sel_hi:[1,1]
	v_pk_mul_f32 v[94:95], v[94:95], v[132:133] op_sel:[0,1] op_sel_hi:[1,1]
	v_pk_fma_f32 v[196:197], v[132:133], v[196:197], v[80:81] op_sel_hi:[0,1,1]
	v_pk_fma_f32 v[198:199], v[132:133], v[198:199], v[82:83] op_sel_hi:[0,1,1]
	v_pk_fma_f32 v[200:201], v[132:133], v[200:201], v[84:85] op_sel_hi:[0,1,1]
	v_pk_fma_f32 v[202:203], v[132:133], v[202:203], v[86:87] op_sel_hi:[0,1,1]
	v_pk_fma_f32 v[204:205], v[132:133], v[204:205], v[88:89] op_sel_hi:[0,1,1]
	v_pk_fma_f32 v[206:207], v[132:133], v[206:207], v[90:91] op_sel_hi:[0,1,1]
	v_pk_fma_f32 v[208:209], v[132:133], v[208:209], v[92:93] op_sel_hi:[0,1,1]
	v_pk_fma_f32 v[210:211], v[132:133], v[210:211], v[94:95] op_sel_hi:[0,1,1]
	s_waitcnt lgkmcnt(14)
	v_pk_fma_f32 v[128:129], v[64:65], v[196:197], v[214:215]
	v_pk_fma_f32 v[130:131], v[66:67], v[198:199], v[214:215]
	s_waitcnt lgkmcnt(13)
	v_pk_fma_f32 v[128:129], v[68:69], v[200:201], v[128:129]
	v_pk_fma_f32 v[130:131], v[70:71], v[202:203], v[130:131]
	s_waitcnt lgkmcnt(12)
	v_pk_fma_f32 v[128:129], v[72:73], v[204:205], v[128:129]
	v_pk_fma_f32 v[130:131], v[74:75], v[206:207], v[130:131]
	s_waitcnt lgkmcnt(11)
	v_pk_fma_f32 v[128:129], v[76:77], v[208:209], v[128:129]
	v_pk_fma_f32 v[130:131], v[78:79], v[210:211], v[130:131]
	v_add_f32_e32 v128, v128, v129
	v_add_f32_e32 v130, v130, v131
	v_add_f32_e32 v212, v128, v130
	ds_read_b128 v[80:83], v194 offset:27264
	ds_read_b128 v[84:87], v194 offset:27520
	ds_read_b128 v[88:91], v194 offset:27776
	ds_read_b128 v[92:95], v194 offset:28032
	ds_read_b32 v134, v140 offset:35528
	ds_read_b32 v135, v190 offset:33536
	ds_read_b32 v132, v140 offset:35464
	ds_read_b128 v[64:67], v194 offset:19072
	ds_read_b128 v[68:71], v194 offset:19328
	ds_read_b128 v[72:75], v194 offset:19584
	ds_read_b128 v[76:79], v194 offset:19840
	s_waitcnt lgkmcnt(15)
	v_mul_f32_e32 v155, v156, v157
	v_pk_mul_f32 v[112:113], v[112:113], v[154:155] op_sel:[0,1] op_sel_hi:[1,1]
	v_add_f32_dpp v212, v212, v212 row_ror:8 row_mask:0xf bank_mask:0xf bound_ctrl:1
	v_pk_mul_f32 v[114:115], v[114:115], v[154:155] op_sel:[0,1] op_sel_hi:[1,1]
	v_pk_mul_f32 v[116:117], v[116:117], v[154:155] op_sel:[0,1] op_sel_hi:[1,1]
	v_add_f32_dpp v212, v212, v212 row_ror:4 row_mask:0xf bank_mask:0xf bound_ctrl:1
	v_pk_mul_f32 v[118:119], v[118:119], v[154:155] op_sel:[0,1] op_sel_hi:[1,1]
	v_pk_mul_f32 v[120:121], v[120:121], v[154:155] op_sel:[0,1] op_sel_hi:[1,1]
	v_add_f32_dpp v212, v212, v212 row_ror:2 row_mask:0xf bank_mask:0xf bound_ctrl:1
	v_pk_mul_f32 v[122:123], v[122:123], v[154:155] op_sel:[0,1] op_sel_hi:[1,1]
	v_pk_mul_f32 v[124:125], v[124:125], v[154:155] op_sel:[0,1] op_sel_hi:[1,1]
	v_add_f32_dpp v212, v212, v212 row_ror:1 row_mask:0xf bank_mask:0xf bound_ctrl:1
	v_pk_mul_f32 v[126:127], v[126:127], v[154:155] op_sel:[0,1] op_sel_hi:[1,1]
	v_pk_fma_f32 v[196:197], v[154:155], v[196:197], v[112:113] op_sel_hi:[0,1,1]
	s_and_saveexec_b64 s[8:9], s[44:45]
	ds_write_b32 v190, v212 offset:34560
	s_mov_b64 exec, s[8:9]
	v_pk_fma_f32 v[198:199], v[154:155], v[198:199], v[114:115] op_sel_hi:[0,1,1]
	v_pk_fma_f32 v[200:201], v[154:155], v[200:201], v[116:117] op_sel_hi:[0,1,1]
	v_pk_fma_f32 v[202:203], v[154:155], v[202:203], v[118:119] op_sel_hi:[0,1,1]
	v_pk_fma_f32 v[204:205], v[154:155], v[204:205], v[120:121] op_sel_hi:[0,1,1]
	v_pk_fma_f32 v[206:207], v[154:155], v[206:207], v[122:123] op_sel_hi:[0,1,1]
	v_pk_fma_f32 v[208:209], v[154:155], v[208:209], v[124:125] op_sel_hi:[0,1,1]
	v_pk_fma_f32 v[210:211], v[154:155], v[210:211], v[126:127] op_sel_hi:[0,1,1]
	s_waitcnt lgkmcnt(15)
	v_pk_fma_f32 v[128:129], v[96:97], v[196:197], v[214:215]
	v_pk_fma_f32 v[130:131], v[98:99], v[198:199], v[214:215]
	s_waitcnt lgkmcnt(14)
	v_pk_fma_f32 v[128:129], v[100:101], v[200:201], v[128:129]
	v_pk_fma_f32 v[130:131], v[102:103], v[202:203], v[130:131]
	s_waitcnt lgkmcnt(13)
	v_pk_fma_f32 v[128:129], v[104:105], v[204:205], v[128:129]
	v_pk_fma_f32 v[130:131], v[106:107], v[206:207], v[130:131]
	s_waitcnt lgkmcnt(12)
	v_pk_fma_f32 v[128:129], v[108:109], v[208:209], v[128:129]
	v_pk_fma_f32 v[130:131], v[110:111], v[210:211], v[130:131]
	v_add_f32_e32 v128, v128, v129
	v_add_f32_e32 v130, v130, v131
	v_add_f32_e32 v213, v128, v130
	ds_read_b128 v[112:115], v194 offset:28288
	ds_read_b128 v[116:119], v194 offset:28544
	ds_read_b128 v[120:123], v194 offset:28800
	ds_read_b128 v[124:127], v194 offset:29056
	ds_read_b32 v156, v140 offset:35532
	ds_read_b32 v157, v190 offset:33600
	ds_read_b32 v154, v140 offset:35468
	ds_read_b128 v[96:99], v194 offset:20096
	ds_read_b128 v[100:103], v194 offset:20352
	ds_read_b128 v[104:107], v194 offset:20608
	ds_read_b128 v[108:111], v194 offset:20864
	s_waitcnt lgkmcnt(15)
	v_mul_f32_e32 v133, v134, v135
	v_pk_mul_f32 v[80:81], v[80:81], v[132:133] op_sel:[0,1] op_sel_hi:[1,1]
	v_add_f32_dpp v213, v213, v213 row_ror:8 row_mask:0xf bank_mask:0xf bound_ctrl:1
	v_pk_mul_f32 v[82:83], v[82:83], v[132:133] op_sel:[0,1] op_sel_hi:[1,1]
	v_pk_mul_f32 v[84:85], v[84:85], v[132:133] op_sel:[0,1] op_sel_hi:[1,1]
	v_add_f32_dpp v213, v213, v213 row_ror:4 row_mask:0xf bank_mask:0xf bound_ctrl:1
	v_pk_mul_f32 v[86:87], v[86:87], v[132:133] op_sel:[0,1] op_sel_hi:[1,1]
	v_pk_mul_f32 v[88:89], v[88:89], v[132:133] op_sel:[0,1] op_sel_hi:[1,1]
	v_add_f32_dpp v213, v213, v213 row_ror:2 row_mask:0xf bank_mask:0xf bound_ctrl:1
	v_pk_mul_f32 v[90:91], v[90:91], v[132:133] op_sel:[0,1] op_sel_hi:[1,1]
	v_pk_mul_f32 v[92:93], v[92:93], v[132:133] op_sel:[0,1] op_sel_hi:[1,1]
	v_add_f32_dpp v213, v213, v213 row_ror:1 row_mask:0xf bank_mask:0xf bound_ctrl:1
	v_pk_mul_f32 v[94:95], v[94:95], v[132:133] op_sel:[0,1] op_sel_hi:[1,1]
	v_pk_fma_f32 v[196:197], v[132:133], v[196:197], v[80:81] op_sel_hi:[0,1,1]
	s_and_saveexec_b64 s[8:9], s[44:45]
	ds_write_b32 v190, v213 offset:34624
	s_mov_b64 exec, s[8:9]
	v_pk_fma_f32 v[198:199], v[132:133], v[198:199], v[82:83] op_sel_hi:[0,1,1]
	v_pk_fma_f32 v[200:201], v[132:133], v[200:201], v[84:85] op_sel_hi:[0,1,1]
	v_pk_fma_f32 v[202:203], v[132:133], v[202:203], v[86:87] op_sel_hi:[0,1,1]
	v_pk_fma_f32 v[204:205], v[132:133], v[204:205], v[88:89] op_sel_hi:[0,1,1]
	v_pk_fma_f32 v[206:207], v[132:133], v[206:207], v[90:91] op_sel_hi:[0,1,1]
	v_pk_fma_f32 v[208:209], v[132:133], v[208:209], v[92:93] op_sel_hi:[0,1,1]
	v_pk_fma_f32 v[210:211], v[132:133], v[210:211], v[94:95] op_sel_hi:[0,1,1]
	s_waitcnt lgkmcnt(15)
	v_pk_fma_f32 v[128:129], v[64:65], v[196:197], v[214:215]
	v_pk_fma_f32 v[130:131], v[66:67], v[198:199], v[214:215]
	v_pk_fma_f32 v[128:129], v[68:69], v[200:201], v[128:129]
	v_pk_fma_f32 v[130:131], v[70:71], v[202:203], v[130:131]
	s_waitcnt lgkmcnt(14)
	v_pk_fma_f32 v[128:129], v[72:73], v[204:205], v[128:129]
	v_pk_fma_f32 v[130:131], v[74:75], v[206:207], v[130:131]
	s_waitcnt lgkmcnt(13)
	v_pk_fma_f32 v[128:129], v[76:77], v[208:209], v[128:129]
	v_pk_fma_f32 v[130:131], v[78:79], v[210:211], v[130:131]
	v_add_f32_e32 v128, v128, v129
	v_add_f32_e32 v130, v130, v131
	v_add_f32_e32 v212, v128, v130
	ds_read_b128 v[80:83], v194 offset:29312
	ds_read_b128 v[84:87], v194 offset:29568
	ds_read_b128 v[88:91], v194 offset:29824
	ds_read_b128 v[92:95], v194 offset:30080
	ds_read_b32 v134, v140 offset:35536
	ds_read_b32 v135, v190 offset:33664
	ds_read_b32 v132, v140 offset:35472
	ds_read_b128 v[64:67], v194 offset:21120
	ds_read_b128 v[68:71], v194 offset:21376
	ds_read_b128 v[72:75], v194 offset:21632
	ds_read_b128 v[76:79], v194 offset:21888
	s_waitcnt lgkmcnt(15)
	v_mul_f32_e32 v155, v156, v157
	v_pk_mul_f32 v[112:113], v[112:113], v[154:155] op_sel:[0,1] op_sel_hi:[1,1]
	v_add_f32_dpp v212, v212, v212 row_ror:8 row_mask:0xf bank_mask:0xf bound_ctrl:1
	v_pk_mul_f32 v[114:115], v[114:115], v[154:155] op_sel:[0,1] op_sel_hi:[1,1]
	v_pk_mul_f32 v[116:117], v[116:117], v[154:155] op_sel:[0,1] op_sel_hi:[1,1]
	v_add_f32_dpp v212, v212, v212 row_ror:4 row_mask:0xf bank_mask:0xf bound_ctrl:1
	v_pk_mul_f32 v[118:119], v[118:119], v[154:155] op_sel:[0,1] op_sel_hi:[1,1]
	v_pk_mul_f32 v[120:121], v[120:121], v[154:155] op_sel:[0,1] op_sel_hi:[1,1]
	v_add_f32_dpp v212, v212, v212 row_ror:2 row_mask:0xf bank_mask:0xf bound_ctrl:1
	v_pk_mul_f32 v[122:123], v[122:123], v[154:155] op_sel:[0,1] op_sel_hi:[1,1]
	v_pk_mul_f32 v[124:125], v[124:125], v[154:155] op_sel:[0,1] op_sel_hi:[1,1]
	v_add_f32_dpp v212, v212, v212 row_ror:1 row_mask:0xf bank_mask:0xf bound_ctrl:1
	v_pk_mul_f32 v[126:127], v[126:127], v[154:155] op_sel:[0,1] op_sel_hi:[1,1]
	v_pk_fma_f32 v[196:197], v[154:155], v[196:197], v[112:113] op_sel_hi:[0,1,1]
	s_and_saveexec_b64 s[8:9], s[44:45]
	ds_write_b32 v190, v212 offset:34688
	s_mov_b64 exec, s[8:9]
	v_pk_fma_f32 v[198:199], v[154:155], v[198:199], v[114:115] op_sel_hi:[0,1,1]
	v_pk_fma_f32 v[200:201], v[154:155], v[200:201], v[116:117] op_sel_hi:[0,1,1]
	v_pk_fma_f32 v[202:203], v[154:155], v[202:203], v[118:119] op_sel_hi:[0,1,1]
	v_pk_fma_f32 v[204:205], v[154:155], v[204:205], v[120:121] op_sel_hi:[0,1,1]
	v_pk_fma_f32 v[206:207], v[154:155], v[206:207], v[122:123] op_sel_hi:[0,1,1]
	v_pk_fma_f32 v[208:209], v[154:155], v[208:209], v[124:125] op_sel_hi:[0,1,1]
	v_pk_fma_f32 v[210:211], v[154:155], v[210:211], v[126:127] op_sel_hi:[0,1,1]
	s_waitcnt lgkmcnt(15)
	v_pk_fma_f32 v[128:129], v[96:97], v[196:197], v[214:215]
	v_pk_fma_f32 v[130:131], v[98:99], v[198:199], v[214:215]
	v_pk_fma_f32 v[128:129], v[100:101], v[200:201], v[128:129]
	v_pk_fma_f32 v[130:131], v[102:103], v[202:203], v[130:131]
	s_waitcnt lgkmcnt(14)
	v_pk_fma_f32 v[128:129], v[104:105], v[204:205], v[128:129]
	v_pk_fma_f32 v[130:131], v[106:107], v[206:207], v[130:131]
	s_waitcnt lgkmcnt(13)
	v_pk_fma_f32 v[128:129], v[108:109], v[208:209], v[128:129]
	v_pk_fma_f32 v[130:131], v[110:111], v[210:211], v[130:131]
	v_add_f32_e32 v128, v128, v129
	v_add_f32_e32 v130, v130, v131
	v_add_f32_e32 v213, v128, v130
	ds_read_b128 v[112:115], v194 offset:30336
	ds_read_b128 v[116:119], v194 offset:30592
	ds_read_b128 v[120:123], v194 offset:30848
	ds_read_b128 v[124:127], v194 offset:31104
	ds_read_b32 v156, v140 offset:35540
	ds_read_b32 v157, v190 offset:33728
	ds_read_b32 v154, v140 offset:35476
	ds_read_b128 v[96:99], v194 offset:22144
	ds_read_b128 v[100:103], v194 offset:22400
	ds_read_b128 v[104:107], v194 offset:22656
	ds_read_b128 v[108:111], v194 offset:22912
	s_waitcnt lgkmcnt(15)
	v_mul_f32_e32 v133, v134, v135
	v_pk_mul_f32 v[80:81], v[80:81], v[132:133] op_sel:[0,1] op_sel_hi:[1,1]
	v_add_f32_dpp v213, v213, v213 row_ror:8 row_mask:0xf bank_mask:0xf bound_ctrl:1
	v_pk_mul_f32 v[82:83], v[82:83], v[132:133] op_sel:[0,1] op_sel_hi:[1,1]
	v_pk_mul_f32 v[84:85], v[84:85], v[132:133] op_sel:[0,1] op_sel_hi:[1,1]
	v_add_f32_dpp v213, v213, v213 row_ror:4 row_mask:0xf bank_mask:0xf bound_ctrl:1
	v_pk_mul_f32 v[86:87], v[86:87], v[132:133] op_sel:[0,1] op_sel_hi:[1,1]
	v_pk_mul_f32 v[88:89], v[88:89], v[132:133] op_sel:[0,1] op_sel_hi:[1,1]
	v_add_f32_dpp v213, v213, v213 row_ror:2 row_mask:0xf bank_mask:0xf bound_ctrl:1
	v_pk_mul_f32 v[90:91], v[90:91], v[132:133] op_sel:[0,1] op_sel_hi:[1,1]
	v_pk_mul_f32 v[92:93], v[92:93], v[132:133] op_sel:[0,1] op_sel_hi:[1,1]
	v_add_f32_dpp v213, v213, v213 row_ror:1 row_mask:0xf bank_mask:0xf bound_ctrl:1
	v_pk_mul_f32 v[94:95], v[94:95], v[132:133] op_sel:[0,1] op_sel_hi:[1,1]
	v_pk_fma_f32 v[196:197], v[132:133], v[196:197], v[80:81] op_sel_hi:[0,1,1]
	s_and_saveexec_b64 s[8:9], s[44:45]
	ds_write_b32 v190, v213 offset:34752
	s_mov_b64 exec, s[8:9]
	v_pk_fma_f32 v[198:199], v[132:133], v[198:199], v[82:83] op_sel_hi:[0,1,1]
	v_pk_fma_f32 v[200:201], v[132:133], v[200:201], v[84:85] op_sel_hi:[0,1,1]
	v_pk_fma_f32 v[202:203], v[132:133], v[202:203], v[86:87] op_sel_hi:[0,1,1]
	v_pk_fma_f32 v[204:205], v[132:133], v[204:205], v[88:89] op_sel_hi:[0,1,1]
	v_pk_fma_f32 v[206:207], v[132:133], v[206:207], v[90:91] op_sel_hi:[0,1,1]
	v_pk_fma_f32 v[208:209], v[132:133], v[208:209], v[92:93] op_sel_hi:[0,1,1]
	v_pk_fma_f32 v[210:211], v[132:133], v[210:211], v[94:95] op_sel_hi:[0,1,1]
	s_waitcnt lgkmcnt(15)
	v_pk_fma_f32 v[128:129], v[64:65], v[196:197], v[214:215]
	v_pk_fma_f32 v[130:131], v[66:67], v[198:199], v[214:215]
	v_pk_fma_f32 v[128:129], v[68:69], v[200:201], v[128:129]
	v_pk_fma_f32 v[130:131], v[70:71], v[202:203], v[130:131]
	s_waitcnt lgkmcnt(14)
	v_pk_fma_f32 v[128:129], v[72:73], v[204:205], v[128:129]
	v_pk_fma_f32 v[130:131], v[74:75], v[206:207], v[130:131]
	s_waitcnt lgkmcnt(13)
	v_pk_fma_f32 v[128:129], v[76:77], v[208:209], v[128:129]
	v_pk_fma_f32 v[130:131], v[78:79], v[210:211], v[130:131]
	v_add_f32_e32 v128, v128, v129
	v_add_f32_e32 v130, v130, v131
	v_add_f32_e32 v212, v128, v130
	ds_read_b128 v[80:83], v194 offset:31360
	ds_read_b128 v[84:87], v194 offset:31616
	ds_read_b128 v[88:91], v194 offset:31872
	ds_read_b128 v[92:95], v194 offset:32128
	ds_read_b32 v134, v140 offset:35544
	ds_read_b32 v135, v190 offset:33792
	ds_read_b32 v132, v140 offset:35480
	ds_read_b128 v[64:67], v194 offset:23168
	ds_read_b128 v[68:71], v194 offset:23424
	ds_read_b128 v[72:75], v194 offset:23680
	ds_read_b128 v[76:79], v194 offset:23936
	s_waitcnt lgkmcnt(15)
	v_mul_f32_e32 v155, v156, v157
	v_pk_mul_f32 v[112:113], v[112:113], v[154:155] op_sel:[0,1] op_sel_hi:[1,1]
	v_add_f32_dpp v212, v212, v212 row_ror:8 row_mask:0xf bank_mask:0xf bound_ctrl:1
	v_pk_mul_f32 v[114:115], v[114:115], v[154:155] op_sel:[0,1] op_sel_hi:[1,1]
	v_pk_mul_f32 v[116:117], v[116:117], v[154:155] op_sel:[0,1] op_sel_hi:[1,1]
	v_add_f32_dpp v212, v212, v212 row_ror:4 row_mask:0xf bank_mask:0xf bound_ctrl:1
	v_pk_mul_f32 v[118:119], v[118:119], v[154:155] op_sel:[0,1] op_sel_hi:[1,1]
	v_pk_mul_f32 v[120:121], v[120:121], v[154:155] op_sel:[0,1] op_sel_hi:[1,1]
	v_add_f32_dpp v212, v212, v212 row_ror:2 row_mask:0xf bank_mask:0xf bound_ctrl:1
	v_pk_mul_f32 v[122:123], v[122:123], v[154:155] op_sel:[0,1] op_sel_hi:[1,1]
	v_pk_mul_f32 v[124:125], v[124:125], v[154:155] op_sel:[0,1] op_sel_hi:[1,1]
	v_add_f32_dpp v212, v212, v212 row_ror:1 row_mask:0xf bank_mask:0xf bound_ctrl:1
	v_pk_mul_f32 v[126:127], v[126:127], v[154:155] op_sel:[0,1] op_sel_hi:[1,1]
	v_pk_fma_f32 v[196:197], v[154:155], v[196:197], v[112:113] op_sel_hi:[0,1,1]
	s_and_saveexec_b64 s[8:9], s[44:45]
	ds_write_b32 v190, v212 offset:34816
	s_mov_b64 exec, s[8:9]
	v_pk_fma_f32 v[198:199], v[154:155], v[198:199], v[114:115] op_sel_hi:[0,1,1]
	v_pk_fma_f32 v[200:201], v[154:155], v[200:201], v[116:117] op_sel_hi:[0,1,1]
	v_pk_fma_f32 v[202:203], v[154:155], v[202:203], v[118:119] op_sel_hi:[0,1,1]
	v_pk_fma_f32 v[204:205], v[154:155], v[204:205], v[120:121] op_sel_hi:[0,1,1]
	v_pk_fma_f32 v[206:207], v[154:155], v[206:207], v[122:123] op_sel_hi:[0,1,1]
	v_pk_fma_f32 v[208:209], v[154:155], v[208:209], v[124:125] op_sel_hi:[0,1,1]
	v_pk_fma_f32 v[210:211], v[154:155], v[210:211], v[126:127] op_sel_hi:[0,1,1]
	s_waitcnt lgkmcnt(15)
	v_pk_fma_f32 v[128:129], v[96:97], v[196:197], v[214:215]
	v_pk_fma_f32 v[130:131], v[98:99], v[198:199], v[214:215]
	v_pk_fma_f32 v[128:129], v[100:101], v[200:201], v[128:129]
	v_pk_fma_f32 v[130:131], v[102:103], v[202:203], v[130:131]
	s_waitcnt lgkmcnt(14)
	v_pk_fma_f32 v[128:129], v[104:105], v[204:205], v[128:129]
	v_pk_fma_f32 v[130:131], v[106:107], v[206:207], v[130:131]
	s_waitcnt lgkmcnt(13)
	v_pk_fma_f32 v[128:129], v[108:109], v[208:209], v[128:129]
	v_pk_fma_f32 v[130:131], v[110:111], v[210:211], v[130:131]
	v_add_f32_e32 v128, v128, v129
	v_add_f32_e32 v130, v130, v131
	v_add_f32_e32 v213, v128, v130
	ds_read_b128 v[112:115], v194 offset:32384
	ds_read_b128 v[116:119], v194 offset:32640
	ds_read_b128 v[120:123], v194 offset:32896
	ds_read_b128 v[124:127], v194 offset:33152
	ds_read_b32 v156, v140 offset:35548
	ds_read_b32 v157, v190 offset:33856
	ds_read_b32 v154, v140 offset:35484
	ds_read_b128 v[96:99], v194 offset:24192
	ds_read_b128 v[100:103], v194 offset:24448
	ds_read_b128 v[104:107], v194 offset:24704
	ds_read_b128 v[108:111], v194 offset:24960
	s_waitcnt lgkmcnt(15)
	v_mul_f32_e32 v133, v134, v135
	v_pk_mul_f32 v[80:81], v[80:81], v[132:133] op_sel:[0,1] op_sel_hi:[1,1]
	v_add_f32_dpp v213, v213, v213 row_ror:8 row_mask:0xf bank_mask:0xf bound_ctrl:1
	v_pk_mul_f32 v[82:83], v[82:83], v[132:133] op_sel:[0,1] op_sel_hi:[1,1]
	v_pk_mul_f32 v[84:85], v[84:85], v[132:133] op_sel:[0,1] op_sel_hi:[1,1]
	v_add_f32_dpp v213, v213, v213 row_ror:4 row_mask:0xf bank_mask:0xf bound_ctrl:1
	v_pk_mul_f32 v[86:87], v[86:87], v[132:133] op_sel:[0,1] op_sel_hi:[1,1]
	v_pk_mul_f32 v[88:89], v[88:89], v[132:133] op_sel:[0,1] op_sel_hi:[1,1]
	v_add_f32_dpp v213, v213, v213 row_ror:2 row_mask:0xf bank_mask:0xf bound_ctrl:1
	v_pk_mul_f32 v[90:91], v[90:91], v[132:133] op_sel:[0,1] op_sel_hi:[1,1]
	v_pk_mul_f32 v[92:93], v[92:93], v[132:133] op_sel:[0,1] op_sel_hi:[1,1]
	v_add_f32_dpp v213, v213, v213 row_ror:1 row_mask:0xf bank_mask:0xf bound_ctrl:1
	v_pk_mul_f32 v[94:95], v[94:95], v[132:133] op_sel:[0,1] op_sel_hi:[1,1]
	v_pk_fma_f32 v[196:197], v[132:133], v[196:197], v[80:81] op_sel_hi:[0,1,1]
	s_and_saveexec_b64 s[8:9], s[44:45]
	ds_write_b32 v190, v213 offset:34880
	s_mov_b64 exec, s[8:9]
	v_pk_fma_f32 v[198:199], v[132:133], v[198:199], v[82:83] op_sel_hi:[0,1,1]
	v_pk_fma_f32 v[200:201], v[132:133], v[200:201], v[84:85] op_sel_hi:[0,1,1]
	v_pk_fma_f32 v[202:203], v[132:133], v[202:203], v[86:87] op_sel_hi:[0,1,1]
	v_pk_fma_f32 v[204:205], v[132:133], v[204:205], v[88:89] op_sel_hi:[0,1,1]
	v_pk_fma_f32 v[206:207], v[132:133], v[206:207], v[90:91] op_sel_hi:[0,1,1]
	v_pk_fma_f32 v[208:209], v[132:133], v[208:209], v[92:93] op_sel_hi:[0,1,1]
	v_pk_fma_f32 v[210:211], v[132:133], v[210:211], v[94:95] op_sel_hi:[0,1,1]
	s_waitcnt lgkmcnt(15)
	v_pk_fma_f32 v[128:129], v[64:65], v[196:197], v[214:215]
	v_pk_fma_f32 v[130:131], v[66:67], v[198:199], v[214:215]
	v_pk_fma_f32 v[128:129], v[68:69], v[200:201], v[128:129]
	v_pk_fma_f32 v[130:131], v[70:71], v[202:203], v[130:131]
	s_waitcnt lgkmcnt(14)
	v_pk_fma_f32 v[128:129], v[72:73], v[204:205], v[128:129]
	v_pk_fma_f32 v[130:131], v[74:75], v[206:207], v[130:131]
	s_waitcnt lgkmcnt(13)
	v_pk_fma_f32 v[128:129], v[76:77], v[208:209], v[128:129]
	v_pk_fma_f32 v[130:131], v[78:79], v[210:211], v[130:131]
	v_add_f32_e32 v128, v128, v129
	v_add_f32_e32 v130, v130, v131
	v_add_f32_e32 v212, v128, v130
	s_waitcnt lgkmcnt(6)
	v_mul_f32_e32 v155, v156, v157
	v_pk_mul_f32 v[112:113], v[112:113], v[154:155] op_sel:[0,1] op_sel_hi:[1,1]
	v_add_f32_dpp v212, v212, v212 row_ror:8 row_mask:0xf bank_mask:0xf bound_ctrl:1
	v_pk_mul_f32 v[114:115], v[114:115], v[154:155] op_sel:[0,1] op_sel_hi:[1,1]
	v_pk_mul_f32 v[116:117], v[116:117], v[154:155] op_sel:[0,1] op_sel_hi:[1,1]
	v_add_f32_dpp v212, v212, v212 row_ror:4 row_mask:0xf bank_mask:0xf bound_ctrl:1
	v_pk_mul_f32 v[118:119], v[118:119], v[154:155] op_sel:[0,1] op_sel_hi:[1,1]
	v_pk_mul_f32 v[120:121], v[120:121], v[154:155] op_sel:[0,1] op_sel_hi:[1,1]
	v_add_f32_dpp v212, v212, v212 row_ror:2 row_mask:0xf bank_mask:0xf bound_ctrl:1
	v_pk_mul_f32 v[122:123], v[122:123], v[154:155] op_sel:[0,1] op_sel_hi:[1,1]
	v_pk_mul_f32 v[124:125], v[124:125], v[154:155] op_sel:[0,1] op_sel_hi:[1,1]
	v_add_f32_dpp v212, v212, v212 row_ror:1 row_mask:0xf bank_mask:0xf bound_ctrl:1
	v_pk_mul_f32 v[126:127], v[126:127], v[154:155] op_sel:[0,1] op_sel_hi:[1,1]
	s_waitcnt lgkmcnt(5)
	v_pk_fma_f32 v[196:197], v[154:155], v[196:197], v[112:113] op_sel_hi:[0,1,1]
	s_and_saveexec_b64 s[8:9], s[44:45]
	ds_write_b32 v190, v212 offset:34944
	s_mov_b64 exec, s[8:9]
	v_pk_fma_f32 v[198:199], v[154:155], v[198:199], v[114:115] op_sel_hi:[0,1,1]
	v_pk_fma_f32 v[200:201], v[154:155], v[200:201], v[116:117] op_sel_hi:[0,1,1]
	v_pk_fma_f32 v[202:203], v[154:155], v[202:203], v[118:119] op_sel_hi:[0,1,1]
	v_pk_fma_f32 v[204:205], v[154:155], v[204:205], v[120:121] op_sel_hi:[0,1,1]
	v_pk_fma_f32 v[206:207], v[154:155], v[206:207], v[122:123] op_sel_hi:[0,1,1]
	v_pk_fma_f32 v[208:209], v[154:155], v[208:209], v[124:125] op_sel_hi:[0,1,1]
	v_pk_fma_f32 v[210:211], v[154:155], v[210:211], v[126:127] op_sel_hi:[0,1,1]
	s_waitcnt lgkmcnt(5)
	v_pk_fma_f32 v[128:129], v[96:97], v[196:197], v[214:215]
	v_pk_fma_f32 v[130:131], v[98:99], v[198:199], v[214:215]
	s_waitcnt lgkmcnt(4)
	v_pk_fma_f32 v[128:129], v[100:101], v[200:201], v[128:129]
	v_pk_fma_f32 v[130:131], v[102:103], v[202:203], v[130:131]
	s_waitcnt lgkmcnt(3)
	v_pk_fma_f32 v[128:129], v[104:105], v[204:205], v[128:129]
	v_pk_fma_f32 v[130:131], v[106:107], v[206:207], v[130:131]
	s_waitcnt lgkmcnt(2)
	v_pk_fma_f32 v[128:129], v[108:109], v[208:209], v[128:129]
	v_pk_fma_f32 v[130:131], v[110:111], v[210:211], v[130:131]
	v_add_f32_e32 v128, v128, v129
	v_add_f32_e32 v130, v130, v131
	v_add_f32_e32 v213, v128, v130
	s_nop 1
	v_add_f32_dpp v213, v213, v213 row_ror:8 row_mask:0xf bank_mask:0xf bound_ctrl:1
	s_nop 1
	v_add_f32_dpp v213, v213, v213 row_ror:4 row_mask:0xf bank_mask:0xf bound_ctrl:1
	s_nop 1
	v_add_f32_dpp v213, v213, v213 row_ror:2 row_mask:0xf bank_mask:0xf bound_ctrl:1
	s_nop 1
	v_add_f32_dpp v213, v213, v213 row_ror:1 row_mask:0xf bank_mask:0xf bound_ctrl:1
	s_and_saveexec_b64 s[8:9], s[44:45]
	ds_write_b32 v190, v213 offset:35008
	s_mov_b64 exec, s[8:9]
	s_waitcnt lgkmcnt(0)
	v_mov_b32_e32 v88, v196
	v_mov_b32_e32 v89, v197
	v_mov_b32_e32 v90, v198
	v_mov_b32_e32 v100, v199
	v_mov_b32_e32 v91, v200
	v_mov_b32_e32 v101, v201
	v_mov_b32_e32 v102, v202
	v_mov_b32_e32 v104, v203
	v_mov_b32_e32 v103, v204
	v_mov_b32_e32 v105, v205
	v_mov_b32_e32 v106, v206
	v_mov_b32_e32 v109, v207
	v_mov_b32_e32 v107, v208
	v_mov_b32_e32 v110, v209
	v_mov_b32_e32 v108, v210
	v_mov_b32_e32 v111, v211
	s_branch .LBB0_1138

.LBB0_1443:
	s_or_b64 exec, exec, s[8:9]
	s_and_saveexec_b64 s[8:9], s[46:47]
	s_cbranch_execz .LBB0_1452
	v_mov_b32_e32 v81, 0
	v_mov_b32_e32 v80, 0xf149f2ca
	s_and_saveexec_b64 s[64:65], s[40:41]
	v_add_u32_e32 v80, 0x4000, v144
	ds_read2_b32 v[80:81], v80 offset0:128 offset1:144
	s_or_b64 exec, exec, s[64:65]
	s_waitcnt lgkmcnt(0)
	v_add_f32_dpp v82, v80, v81 row_shr:1 row_mask:0xf bank_mask:0xf bound_ctrl:1
	v_max_f32_e32 v83, v80, v80
	v_max_f32_e32 v82, v82, v83
	v_cndmask_b32_e64 v82, v80, v82, s[48:49]
	v_add_f32_dpp v83, v81, v81 row_shr:1 row_mask:0xf bank_mask:0xf bound_ctrl:1
	v_cndmask_b32_e64 v83, v81, v83, s[48:49]
	v_max_f32_e32 v85, v82, v82
	s_nop 0
	v_add_f32_dpp v84, v82, v83 row_shr:2 row_mask:0xf bank_mask:0xf bound_ctrl:1
	v_max_f32_e32 v84, v84, v85
	v_add_f32_dpp v85, v83, v83 row_shr:2 row_mask:0xf bank_mask:0xf bound_ctrl:1
	v_cndmask_b32_e64 v82, v82, v84, s[50:51]
	v_cndmask_b32_e64 v83, v83, v85, s[50:51]
	v_max_f32_e32 v85, v82, v82
	s_nop 0
	v_add_f32_dpp v84, v82, v83 row_shr:4 row_mask:0xf bank_mask:0xf bound_ctrl:1
	v_max_f32_e32 v84, v84, v85
	v_cndmask_b32_e64 v82, v82, v84, s[52:53]
	ds_read_b32 v84, v140 offset:35328
	v_add_f32_dpp v85, v83, v83 row_shr:4 row_mask:0xf bank_mask:0xf bound_ctrl:1
	v_cndmask_b32_e64 v83, v83, v85, s[52:53]
	v_max_f32_e32 v82, v82, v82
	s_waitcnt lgkmcnt(0)
	v_add_f32_e32 v83, v84, v83
	v_max_f32_e32 v82, v83, v82
	v_mov_b32_e32 v83, 0
	v_sub_f32_e32 v80, v80, v82
	v_mul_f32_e32 v80, 0x3fb8aa3b, v80
	v_mov_b32_dpp v83, v82 row_shr:1 row_mask:0xf bank_mask:0xf
	v_cndmask_b32_e64 v83, v83, v84, s[38:39]
	v_add_f32_e32 v81, v81, v83
	v_sub_f32_e32 v81, v81, v82
	v_mul_f32_e32 v81, 0x3fb8aa3b, v81
	v_exp_f32_e32 v81, v81
	v_exp_f32_e32 v80, v80
	v_add_u32_e32 v83, 0x8800, v144
	ds_write2_b32 v83, v81, v80 offset0:64 offset1:80
	ds_write_b32 v144, v82 offset:35200
	s_and_b64 exec, exec, s[54:55]
	ds_write_b32 v140, v82 offset:35328

.LBB0_1447:
	s_cmp_lg_u32 s73, 0
	s_cselect_b64 s[8:9], -1, 0
	s_and_b64 s[22:23], s[56:57], s[8:9]
	s_and_saveexec_b64 s[8:9], s[22:23]
	s_cbranch_execz .LBB0_1454
	v_add3_u32 v80, v147, s73, -8
	ds_read_b32 v84, v183 offset:34560
	v_ashrrev_i32_e32 v81, 31, v80
	v_lshlrev_b64 v[80:81], 4, v[80:81]
	v_lshl_or_b32 v80, s70, 2, v80
	v_lshl_add_u64 v[82:83], s[34:35], 0, v[80:81]
	v_lshl_add_u64 v[80:81], s[96:97], 0, v[80:81]
	s_waitcnt lgkmcnt(0)
	global_store_dword v[80:81], v84, off
	ds_read_b32 v80, v144 offset:35264
	s_waitcnt lgkmcnt(0)
	global_store_dword v[82:83], v80, off
.LBB0_1454:
	s_or_b64 exec, exec, s[8:9]
	s_waitcnt lgkmcnt(0)
	v_mov_b32_e32 v196, v64
	v_mov_b32_e32 v197, v65
	v_mov_b32_e32 v198, v66
	v_mov_b32_e32 v199, v67
	v_mov_b32_e32 v200, v76
	v_mov_b32_e32 v201, v77
	v_mov_b32_e32 v202, v78
	v_mov_b32_e32 v203, v79
	v_mov_b32_e32 v204, v72
	v_mov_b32_e32 v205, v73
	v_mov_b32_e32 v206, v74
	v_mov_b32_e32 v207, v75
	v_mov_b32_e32 v208, v68
	v_mov_b32_e32 v209, v69
	v_mov_b32_e32 v210, v70
	v_mov_b32_e32 v211, v71
	v_mov_b32_e32 v192, 0
	v_mov_b32_e32 v193, 0
	ds_read_b128 v[80:83], v188 offset:8192
	ds_read_b128 v[84:87], v188 offset:8448
	ds_read_b128 v[88:91], v188 offset:8704
	ds_read_b128 v[92:95], v188 offset:8960
	ds_read_b32 v134, v140 offset:35136
	ds_read_b32 v135, v189 offset:16384
	ds_read_b32 v132, v140 offset:35072
	ds_read_b128 v[64:67], v188
	ds_read_b128 v[68:71], v188 offset:256
	ds_read_b128 v[72:75], v188 offset:512
	ds_read_b128 v[76:79], v188 offset:768
	ds_read_b128 v[112:115], v188 offset:9216
	ds_read_b128 v[116:119], v188 offset:9472
	ds_read_b128 v[120:123], v188 offset:9728
	ds_read_b128 v[124:127], v188 offset:9984
	ds_read_b32 v154, v140 offset:35140
	ds_read_b32 v155, v189 offset:16448
	ds_read_b32 v152, v140 offset:35076
	ds_read_b128 v[96:99], v188 offset:1024
	ds_read_b128 v[100:103], v188 offset:1280
	ds_read_b128 v[104:107], v188 offset:1536
	ds_read_b128 v[108:111], v188 offset:1792
	s_waitcnt lgkmcnt(15)
	v_mul_f32_e32 v133, v134, v135
	v_pk_mul_f32 v[80:81], v[80:81], v[132:133] op_sel:[0,1] op_sel_hi:[1,1]
	v_pk_mul_f32 v[82:83], v[82:83], v[132:133] op_sel:[0,1] op_sel_hi:[1,1]
	v_pk_mul_f32 v[84:85], v[84:85], v[132:133] op_sel:[0,1] op_sel_hi:[1,1]
	v_pk_mul_f32 v[86:87], v[86:87], v[132:133] op_sel:[0,1] op_sel_hi:[1,1]
	v_pk_mul_f32 v[88:89], v[88:89], v[132:133] op_sel:[0,1] op_sel_hi:[1,1]
	v_pk_mul_f32 v[90:91], v[90:91], v[132:133] op_sel:[0,1] op_sel_hi:[1,1]
	v_pk_mul_f32 v[92:93], v[92:93], v[132:133] op_sel:[0,1] op_sel_hi:[1,1]
	v_pk_mul_f32 v[94:95], v[94:95], v[132:133] op_sel:[0,1] op_sel_hi:[1,1]
	v_pk_fma_f32 v[196:197], v[132:133], v[196:197], v[80:81] op_sel_hi:[0,1,1]
	v_pk_fma_f32 v[198:199], v[132:133], v[198:199], v[82:83] op_sel_hi:[0,1,1]
	v_pk_fma_f32 v[200:201], v[132:133], v[200:201], v[84:85] op_sel_hi:[0,1,1]
	v_pk_fma_f32 v[202:203], v[132:133], v[202:203], v[86:87] op_sel_hi:[0,1,1]
	v_pk_fma_f32 v[204:205], v[132:133], v[204:205], v[88:89] op_sel_hi:[0,1,1]
	v_pk_fma_f32 v[206:207], v[132:133], v[206:207], v[90:91] op_sel_hi:[0,1,1]
	v_pk_fma_f32 v[208:209], v[132:133], v[208:209], v[92:93] op_sel_hi:[0,1,1]
	v_pk_fma_f32 v[210:211], v[132:133], v[210:211], v[94:95] op_sel_hi:[0,1,1]
	s_waitcnt lgkmcnt(14)
	v_pk_fma_f32 v[128:129], v[64:65], v[196:197], v[192:193]
	v_pk_fma_f32 v[130:131], v[66:67], v[198:199], v[192:193]
	s_waitcnt lgkmcnt(13)
	v_pk_fma_f32 v[128:129], v[68:69], v[200:201], v[128:129]
	v_pk_fma_f32 v[130:131], v[70:71], v[202:203], v[130:131]
	s_waitcnt lgkmcnt(12)
	v_pk_fma_f32 v[128:129], v[72:73], v[204:205], v[128:129]
	v_pk_fma_f32 v[130:131], v[74:75], v[206:207], v[130:131]
	s_waitcnt lgkmcnt(11)
	v_pk_fma_f32 v[128:129], v[76:77], v[208:209], v[128:129]
	v_pk_fma_f32 v[130:131], v[78:79], v[210:211], v[130:131]
	v_add_f32_e32 v128, v128, v129
	v_add_f32_e32 v130, v130, v131
	v_add_f32_e32 v190, v128, v130
	ds_read_b128 v[80:83], v188 offset:10240
	ds_read_b128 v[84:87], v188 offset:10496
	ds_read_b128 v[88:91], v188 offset:10752
	ds_read_b128 v[92:95], v188 offset:11008
	ds_read_b32 v134, v140 offset:35144
	ds_read_b32 v135, v189 offset:16512
	ds_read_b32 v132, v140 offset:35080
	ds_read_b128 v[64:67], v188 offset:2048
	ds_read_b128 v[68:71], v188 offset:2304
	ds_read_b128 v[72:75], v188 offset:2560
	ds_read_b128 v[76:79], v188 offset:2816
	s_waitcnt lgkmcnt(15)
	v_mul_f32_e32 v153, v154, v155
	v_pk_mul_f32 v[112:113], v[112:113], v[152:153] op_sel:[0,1] op_sel_hi:[1,1]
	v_add_f32_dpp v190, v190, v190 row_ror:8 row_mask:0xf bank_mask:0xf bound_ctrl:1
	v_pk_mul_f32 v[114:115], v[114:115], v[152:153] op_sel:[0,1] op_sel_hi:[1,1]
	v_pk_mul_f32 v[116:117], v[116:117], v[152:153] op_sel:[0,1] op_sel_hi:[1,1]
	v_add_f32_dpp v190, v190, v190 row_ror:4 row_mask:0xf bank_mask:0xf bound_ctrl:1
	v_pk_mul_f32 v[118:119], v[118:119], v[152:153] op_sel:[0,1] op_sel_hi:[1,1]
	v_pk_mul_f32 v[120:121], v[120:121], v[152:153] op_sel:[0,1] op_sel_hi:[1,1]
	v_add_f32_dpp v190, v190, v190 row_ror:2 row_mask:0xf bank_mask:0xf bound_ctrl:1
	v_pk_mul_f32 v[122:123], v[122:123], v[152:153] op_sel:[0,1] op_sel_hi:[1,1]
	v_pk_mul_f32 v[124:125], v[124:125], v[152:153] op_sel:[0,1] op_sel_hi:[1,1]
	v_add_f32_dpp v190, v190, v190 row_ror:1 row_mask:0xf bank_mask:0xf bound_ctrl:1
	v_pk_mul_f32 v[126:127], v[126:127], v[152:153] op_sel:[0,1] op_sel_hi:[1,1]
	v_pk_fma_f32 v[196:197], v[152:153], v[196:197], v[112:113] op_sel_hi:[0,1,1]
	s_and_saveexec_b64 s[8:9], s[44:45]
	ds_write_b32 v189, v190 offset:34048
	s_mov_b64 exec, s[8:9]
	v_pk_fma_f32 v[198:199], v[152:153], v[198:199], v[114:115] op_sel_hi:[0,1,1]
	v_pk_fma_f32 v[200:201], v[152:153], v[200:201], v[116:117] op_sel_hi:[0,1,1]
	v_pk_fma_f32 v[202:203], v[152:153], v[202:203], v[118:119] op_sel_hi:[0,1,1]
	v_pk_fma_f32 v[204:205], v[152:153], v[204:205], v[120:121] op_sel_hi:[0,1,1]
	v_pk_fma_f32 v[206:207], v[152:153], v[206:207], v[122:123] op_sel_hi:[0,1,1]
	v_pk_fma_f32 v[208:209], v[152:153], v[208:209], v[124:125] op_sel_hi:[0,1,1]
	v_pk_fma_f32 v[210:211], v[152:153], v[210:211], v[126:127] op_sel_hi:[0,1,1]
	s_waitcnt lgkmcnt(15)
	v_pk_fma_f32 v[128:129], v[96:97], v[196:197], v[192:193]
	v_pk_fma_f32 v[130:131], v[98:99], v[198:199], v[192:193]
	s_waitcnt lgkmcnt(14)
	v_pk_fma_f32 v[128:129], v[100:101], v[200:201], v[128:129]
	v_pk_fma_f32 v[130:131], v[102:103], v[202:203], v[130:131]
	s_waitcnt lgkmcnt(13)
	v_pk_fma_f32 v[128:129], v[104:105], v[204:205], v[128:129]
	v_pk_fma_f32 v[130:131], v[106:107], v[206:207], v[130:131]
	s_waitcnt lgkmcnt(12)
	v_pk_fma_f32 v[128:129], v[108:109], v[208:209], v[128:129]
	v_pk_fma_f32 v[130:131], v[110:111], v[210:211], v[130:131]
	v_add_f32_e32 v128, v128, v129
	v_add_f32_e32 v130, v130, v131
	v_add_f32_e32 v191, v128, v130
	ds_read_b128 v[112:115], v188 offset:11264
	ds_read_b128 v[116:119], v188 offset:11520
	ds_read_b128 v[120:123], v188 offset:11776
	ds_read_b128 v[124:127], v188 offset:12032
	ds_read_b32 v154, v140 offset:35148
	ds_read_b32 v155, v189 offset:16576
	ds_read_b32 v152, v140 offset:35084
	ds_read_b128 v[96:99], v188 offset:3072
	ds_read_b128 v[100:103], v188 offset:3328
	ds_read_b128 v[104:107], v188 offset:3584
	ds_read_b128 v[108:111], v188 offset:3840
	s_waitcnt lgkmcnt(15)
	v_mul_f32_e32 v133, v134, v135
	v_pk_mul_f32 v[80:81], v[80:81], v[132:133] op_sel:[0,1] op_sel_hi:[1,1]
	v_add_f32_dpp v191, v191, v191 row_ror:8 row_mask:0xf bank_mask:0xf bound_ctrl:1
	v_pk_mul_f32 v[82:83], v[82:83], v[132:133] op_sel:[0,1] op_sel_hi:[1,1]
	v_pk_mul_f32 v[84:85], v[84:85], v[132:133] op_sel:[0,1] op_sel_hi:[1,1]
	v_add_f32_dpp v191, v191, v191 row_ror:4 row_mask:0xf bank_mask:0xf bound_ctrl:1
	v_pk_mul_f32 v[86:87], v[86:87], v[132:133] op_sel:[0,1] op_sel_hi:[1,1]
	v_pk_mul_f32 v[88:89], v[88:89], v[132:133] op_sel:[0,1] op_sel_hi:[1,1]
	v_add_f32_dpp v191, v191, v191 row_ror:2 row_mask:0xf bank_mask:0xf bound_ctrl:1
	v_pk_mul_f32 v[90:91], v[90:91], v[132:133] op_sel:[0,1] op_sel_hi:[1,1]
	v_pk_mul_f32 v[92:93], v[92:93], v[132:133] op_sel:[0,1] op_sel_hi:[1,1]
	v_add_f32_dpp v191, v191, v191 row_ror:1 row_mask:0xf bank_mask:0xf bound_ctrl:1
	v_pk_mul_f32 v[94:95], v[94:95], v[132:133] op_sel:[0,1] op_sel_hi:[1,1]
	v_pk_fma_f32 v[196:197], v[132:133], v[196:197], v[80:81] op_sel_hi:[0,1,1]
	s_and_saveexec_b64 s[8:9], s[44:45]
	ds_write_b32 v189, v191 offset:34112
	s_mov_b64 exec, s[8:9]
	v_pk_fma_f32 v[198:199], v[132:133], v[198:199], v[82:83] op_sel_hi:[0,1,1]
	v_pk_fma_f32 v[200:201], v[132:133], v[200:201], v[84:85] op_sel_hi:[0,1,1]
	v_pk_fma_f32 v[202:203], v[132:133], v[202:203], v[86:87] op_sel_hi:[0,1,1]
	v_pk_fma_f32 v[204:205], v[132:133], v[204:205], v[88:89] op_sel_hi:[0,1,1]
	v_pk_fma_f32 v[206:207], v[132:133], v[206:207], v[90:91] op_sel_hi:[0,1,1]
	v_pk_fma_f32 v[208:209], v[132:133], v[208:209], v[92:93] op_sel_hi:[0,1,1]
	v_pk_fma_f32 v[210:211], v[132:133], v[210:211], v[94:95] op_sel_hi:[0,1,1]
	s_waitcnt lgkmcnt(15)
	v_pk_fma_f32 v[128:129], v[64:65], v[196:197], v[192:193]
	v_pk_fma_f32 v[130:131], v[66:67], v[198:199], v[192:193]
	v_pk_fma_f32 v[128:129], v[68:69], v[200:201], v[128:129]
	v_pk_fma_f32 v[130:131], v[70:71], v[202:203], v[130:131]
	s_waitcnt lgkmcnt(14)
	v_pk_fma_f32 v[128:129], v[72:73], v[204:205], v[128:129]
	v_pk_fma_f32 v[130:131], v[74:75], v[206:207], v[130:131]
	s_waitcnt lgkmcnt(13)
	v_pk_fma_f32 v[128:129], v[76:77], v[208:209], v[128:129]
	v_pk_fma_f32 v[130:131], v[78:79], v[210:211], v[130:131]
	v_add_f32_e32 v128, v128, v129
	v_add_f32_e32 v130, v130, v131
	v_add_f32_e32 v190, v128, v130
	ds_read_b128 v[80:83], v188 offset:12288
	ds_read_b128 v[84:87], v188 offset:12544
	ds_read_b128 v[88:91], v188 offset:12800
	ds_read_b128 v[92:95], v188 offset:13056
	ds_read_b32 v134, v140 offset:35152
	ds_read_b32 v135, v189 offset:16640
	ds_read_b32 v132, v140 offset:35088
	ds_read_b128 v[64:67], v188 offset:4096
	ds_read_b128 v[68:71], v188 offset:4352
	ds_read_b128 v[72:75], v188 offset:4608
	ds_read_b128 v[76:79], v188 offset:4864
	s_waitcnt lgkmcnt(15)
	v_mul_f32_e32 v153, v154, v155
	v_pk_mul_f32 v[112:113], v[112:113], v[152:153] op_sel:[0,1] op_sel_hi:[1,1]
	v_add_f32_dpp v190, v190, v190 row_ror:8 row_mask:0xf bank_mask:0xf bound_ctrl:1
	v_pk_mul_f32 v[114:115], v[114:115], v[152:153] op_sel:[0,1] op_sel_hi:[1,1]
	v_pk_mul_f32 v[116:117], v[116:117], v[152:153] op_sel:[0,1] op_sel_hi:[1,1]
	v_add_f32_dpp v190, v190, v190 row_ror:4 row_mask:0xf bank_mask:0xf bound_ctrl:1
	v_pk_mul_f32 v[118:119], v[118:119], v[152:153] op_sel:[0,1] op_sel_hi:[1,1]
	v_pk_mul_f32 v[120:121], v[120:121], v[152:153] op_sel:[0,1] op_sel_hi:[1,1]
	v_add_f32_dpp v190, v190, v190 row_ror:2 row_mask:0xf bank_mask:0xf bound_ctrl:1
	v_pk_mul_f32 v[122:123], v[122:123], v[152:153] op_sel:[0,1] op_sel_hi:[1,1]
	v_pk_mul_f32 v[124:125], v[124:125], v[152:153] op_sel:[0,1] op_sel_hi:[1,1]
	v_add_f32_dpp v190, v190, v190 row_ror:1 row_mask:0xf bank_mask:0xf bound_ctrl:1
	v_pk_mul_f32 v[126:127], v[126:127], v[152:153] op_sel:[0,1] op_sel_hi:[1,1]
	v_pk_fma_f32 v[196:197], v[152:153], v[196:197], v[112:113] op_sel_hi:[0,1,1]
	s_and_saveexec_b64 s[8:9], s[44:45]
	ds_write_b32 v189, v190 offset:34176
	s_mov_b64 exec, s[8:9]
	v_pk_fma_f32 v[198:199], v[152:153], v[198:199], v[114:115] op_sel_hi:[0,1,1]
	v_pk_fma_f32 v[200:201], v[152:153], v[200:201], v[116:117] op_sel_hi:[0,1,1]
	v_pk_fma_f32 v[202:203], v[152:153], v[202:203], v[118:119] op_sel_hi:[0,1,1]
	v_pk_fma_f32 v[204:205], v[152:153], v[204:205], v[120:121] op_sel_hi:[0,1,1]
	v_pk_fma_f32 v[206:207], v[152:153], v[206:207], v[122:123] op_sel_hi:[0,1,1]
	v_pk_fma_f32 v[208:209], v[152:153], v[208:209], v[124:125] op_sel_hi:[0,1,1]
	v_pk_fma_f32 v[210:211], v[152:153], v[210:211], v[126:127] op_sel_hi:[0,1,1]
	s_waitcnt lgkmcnt(15)
	v_pk_fma_f32 v[128:129], v[96:97], v[196:197], v[192:193]
	v_pk_fma_f32 v[130:131], v[98:99], v[198:199], v[192:193]
	v_pk_fma_f32 v[128:129], v[100:101], v[200:201], v[128:129]
	v_pk_fma_f32 v[130:131], v[102:103], v[202:203], v[130:131]
	s_waitcnt lgkmcnt(14)
	v_pk_fma_f32 v[128:129], v[104:105], v[204:205], v[128:129]
	v_pk_fma_f32 v[130:131], v[106:107], v[206:207], v[130:131]
	s_waitcnt lgkmcnt(13)
	v_pk_fma_f32 v[128:129], v[108:109], v[208:209], v[128:129]
	v_pk_fma_f32 v[130:131], v[110:111], v[210:211], v[130:131]
	v_add_f32_e32 v128, v128, v129
	v_add_f32_e32 v130, v130, v131
	v_add_f32_e32 v191, v128, v130
	ds_read_b128 v[112:115], v188 offset:13312
	ds_read_b128 v[116:119], v188 offset:13568
	ds_read_b128 v[120:123], v188 offset:13824
	ds_read_b128 v[124:127], v188 offset:14080
	ds_read_b32 v154, v140 offset:35156
	ds_read_b32 v155, v189 offset:16704
	ds_read_b32 v152, v140 offset:35092
	ds_read_b128 v[96:99], v188 offset:5120
	ds_read_b128 v[100:103], v188 offset:5376
	ds_read_b128 v[104:107], v188 offset:5632
	ds_read_b128 v[108:111], v188 offset:5888
	s_waitcnt lgkmcnt(15)
	v_mul_f32_e32 v133, v134, v135
	v_pk_mul_f32 v[80:81], v[80:81], v[132:133] op_sel:[0,1] op_sel_hi:[1,1]
	v_add_f32_dpp v191, v191, v191 row_ror:8 row_mask:0xf bank_mask:0xf bound_ctrl:1
	v_pk_mul_f32 v[82:83], v[82:83], v[132:133] op_sel:[0,1] op_sel_hi:[1,1]
	v_pk_mul_f32 v[84:85], v[84:85], v[132:133] op_sel:[0,1] op_sel_hi:[1,1]
	v_add_f32_dpp v191, v191, v191 row_ror:4 row_mask:0xf bank_mask:0xf bound_ctrl:1
	v_pk_mul_f32 v[86:87], v[86:87], v[132:133] op_sel:[0,1] op_sel_hi:[1,1]
	v_pk_mul_f32 v[88:89], v[88:89], v[132:133] op_sel:[0,1] op_sel_hi:[1,1]
	v_add_f32_dpp v191, v191, v191 row_ror:2 row_mask:0xf bank_mask:0xf bound_ctrl:1
	v_pk_mul_f32 v[90:91], v[90:91], v[132:133] op_sel:[0,1] op_sel_hi:[1,1]
	v_pk_mul_f32 v[92:93], v[92:93], v[132:133] op_sel:[0,1] op_sel_hi:[1,1]
	v_add_f32_dpp v191, v191, v191 row_ror:1 row_mask:0xf bank_mask:0xf bound_ctrl:1
	v_pk_mul_f32 v[94:95], v[94:95], v[132:133] op_sel:[0,1] op_sel_hi:[1,1]
	v_pk_fma_f32 v[196:197], v[132:133], v[196:197], v[80:81] op_sel_hi:[0,1,1]
	s_and_saveexec_b64 s[8:9], s[44:45]
	ds_write_b32 v189, v191 offset:34240
	s_mov_b64 exec, s[8:9]
	v_pk_fma_f32 v[198:199], v[132:133], v[198:199], v[82:83] op_sel_hi:[0,1,1]
	v_pk_fma_f32 v[200:201], v[132:133], v[200:201], v[84:85] op_sel_hi:[0,1,1]
	v_pk_fma_f32 v[202:203], v[132:133], v[202:203], v[86:87] op_sel_hi:[0,1,1]
	v_pk_fma_f32 v[204:205], v[132:133], v[204:205], v[88:89] op_sel_hi:[0,1,1]
	v_pk_fma_f32 v[206:207], v[132:133], v[206:207], v[90:91] op_sel_hi:[0,1,1]
	v_pk_fma_f32 v[208:209], v[132:133], v[208:209], v[92:93] op_sel_hi:[0,1,1]
	v_pk_fma_f32 v[210:211], v[132:133], v[210:211], v[94:95] op_sel_hi:[0,1,1]
	s_waitcnt lgkmcnt(15)
	v_pk_fma_f32 v[128:129], v[64:65], v[196:197], v[192:193]
	v_pk_fma_f32 v[130:131], v[66:67], v[198:199], v[192:193]
	v_pk_fma_f32 v[128:129], v[68:69], v[200:201], v[128:129]
	v_pk_fma_f32 v[130:131], v[70:71], v[202:203], v[130:131]
	s_waitcnt lgkmcnt(14)
	v_pk_fma_f32 v[128:129], v[72:73], v[204:205], v[128:129]
	v_pk_fma_f32 v[130:131], v[74:75], v[206:207], v[130:131]
	s_waitcnt lgkmcnt(13)
	v_pk_fma_f32 v[128:129], v[76:77], v[208:209], v[128:129]
	v_pk_fma_f32 v[130:131], v[78:79], v[210:211], v[130:131]
	v_add_f32_e32 v128, v128, v129
	v_add_f32_e32 v130, v130, v131
	v_add_f32_e32 v190, v128, v130
	ds_read_b128 v[80:83], v188 offset:14336
	ds_read_b128 v[84:87], v188 offset:14592
	ds_read_b128 v[88:91], v188 offset:14848
	ds_read_b128 v[92:95], v188 offset:15104
	ds_read_b32 v134, v140 offset:35160
	ds_read_b32 v135, v189 offset:16768
	ds_read_b32 v132, v140 offset:35096
	ds_read_b128 v[64:67], v188 offset:6144
	ds_read_b128 v[68:71], v188 offset:6400
	ds_read_b128 v[72:75], v188 offset:6656
	ds_read_b128 v[76:79], v188 offset:6912
	s_waitcnt lgkmcnt(15)
	v_mul_f32_e32 v153, v154, v155
	v_pk_mul_f32 v[112:113], v[112:113], v[152:153] op_sel:[0,1] op_sel_hi:[1,1]
	v_add_f32_dpp v190, v190, v190 row_ror:8 row_mask:0xf bank_mask:0xf bound_ctrl:1
	v_pk_mul_f32 v[114:115], v[114:115], v[152:153] op_sel:[0,1] op_sel_hi:[1,1]
	v_pk_mul_f32 v[116:117], v[116:117], v[152:153] op_sel:[0,1] op_sel_hi:[1,1]
	v_add_f32_dpp v190, v190, v190 row_ror:4 row_mask:0xf bank_mask:0xf bound_ctrl:1
	v_pk_mul_f32 v[118:119], v[118:119], v[152:153] op_sel:[0,1] op_sel_hi:[1,1]
	v_pk_mul_f32 v[120:121], v[120:121], v[152:153] op_sel:[0,1] op_sel_hi:[1,1]
	v_add_f32_dpp v190, v190, v190 row_ror:2 row_mask:0xf bank_mask:0xf bound_ctrl:1
	v_pk_mul_f32 v[122:123], v[122:123], v[152:153] op_sel:[0,1] op_sel_hi:[1,1]
	v_pk_mul_f32 v[124:125], v[124:125], v[152:153] op_sel:[0,1] op_sel_hi:[1,1]
	v_add_f32_dpp v190, v190, v190 row_ror:1 row_mask:0xf bank_mask:0xf bound_ctrl:1
	v_pk_mul_f32 v[126:127], v[126:127], v[152:153] op_sel:[0,1] op_sel_hi:[1,1]
	v_pk_fma_f32 v[196:197], v[152:153], v[196:197], v[112:113] op_sel_hi:[0,1,1]
	s_and_saveexec_b64 s[8:9], s[44:45]
	ds_write_b32 v189, v190 offset:34304
	s_mov_b64 exec, s[8:9]
	v_pk_fma_f32 v[198:199], v[152:153], v[198:199], v[114:115] op_sel_hi:[0,1,1]
	v_pk_fma_f32 v[200:201], v[152:153], v[200:201], v[116:117] op_sel_hi:[0,1,1]
	v_pk_fma_f32 v[202:203], v[152:153], v[202:203], v[118:119] op_sel_hi:[0,1,1]
	v_pk_fma_f32 v[204:205], v[152:153], v[204:205], v[120:121] op_sel_hi:[0,1,1]
	v_pk_fma_f32 v[206:207], v[152:153], v[206:207], v[122:123] op_sel_hi:[0,1,1]
	v_pk_fma_f32 v[208:209], v[152:153], v[208:209], v[124:125] op_sel_hi:[0,1,1]
	v_pk_fma_f32 v[210:211], v[152:153], v[210:211], v[126:127] op_sel_hi:[0,1,1]
	s_waitcnt lgkmcnt(15)
	v_pk_fma_f32 v[128:129], v[96:97], v[196:197], v[192:193]
	v_pk_fma_f32 v[130:131], v[98:99], v[198:199], v[192:193]
	v_pk_fma_f32 v[128:129], v[100:101], v[200:201], v[128:129]
	v_pk_fma_f32 v[130:131], v[102:103], v[202:203], v[130:131]
	s_waitcnt lgkmcnt(14)
	v_pk_fma_f32 v[128:129], v[104:105], v[204:205], v[128:129]
	v_pk_fma_f32 v[130:131], v[106:107], v[206:207], v[130:131]
	s_waitcnt lgkmcnt(13)
	v_pk_fma_f32 v[128:129], v[108:109], v[208:209], v[128:129]
	v_pk_fma_f32 v[130:131], v[110:111], v[210:211], v[130:131]
	v_add_f32_e32 v128, v128, v129
	v_add_f32_e32 v130, v130, v131
	v_add_f32_e32 v191, v128, v130
	ds_read_b128 v[112:115], v188 offset:15360
	ds_read_b128 v[116:119], v188 offset:15616
	ds_read_b128 v[120:123], v188 offset:15872
	ds_read_b128 v[124:127], v188 offset:16128
	ds_read_b32 v154, v140 offset:35164
	ds_read_b32 v155, v189 offset:16832
	ds_read_b32 v152, v140 offset:35100
	ds_read_b128 v[96:99], v188 offset:7168
	ds_read_b128 v[100:103], v188 offset:7424
	ds_read_b128 v[104:107], v188 offset:7680
	ds_read_b128 v[108:111], v188 offset:7936
	s_waitcnt lgkmcnt(15)
	v_mul_f32_e32 v133, v134, v135
	v_pk_mul_f32 v[80:81], v[80:81], v[132:133] op_sel:[0,1] op_sel_hi:[1,1]
	v_add_f32_dpp v191, v191, v191 row_ror:8 row_mask:0xf bank_mask:0xf bound_ctrl:1
	v_pk_mul_f32 v[82:83], v[82:83], v[132:133] op_sel:[0,1] op_sel_hi:[1,1]
	v_pk_mul_f32 v[84:85], v[84:85], v[132:133] op_sel:[0,1] op_sel_hi:[1,1]
	v_add_f32_dpp v191, v191, v191 row_ror:4 row_mask:0xf bank_mask:0xf bound_ctrl:1
	v_pk_mul_f32 v[86:87], v[86:87], v[132:133] op_sel:[0,1] op_sel_hi:[1,1]
	v_pk_mul_f32 v[88:89], v[88:89], v[132:133] op_sel:[0,1] op_sel_hi:[1,1]
	v_add_f32_dpp v191, v191, v191 row_ror:2 row_mask:0xf bank_mask:0xf bound_ctrl:1
	v_pk_mul_f32 v[90:91], v[90:91], v[132:133] op_sel:[0,1] op_sel_hi:[1,1]
	v_pk_mul_f32 v[92:93], v[92:93], v[132:133] op_sel:[0,1] op_sel_hi:[1,1]
	v_add_f32_dpp v191, v191, v191 row_ror:1 row_mask:0xf bank_mask:0xf bound_ctrl:1
	v_pk_mul_f32 v[94:95], v[94:95], v[132:133] op_sel:[0,1] op_sel_hi:[1,1]
	v_pk_fma_f32 v[196:197], v[132:133], v[196:197], v[80:81] op_sel_hi:[0,1,1]
	s_and_saveexec_b64 s[8:9], s[44:45]
	ds_write_b32 v189, v191 offset:34368
	s_mov_b64 exec, s[8:9]
	v_pk_fma_f32 v[198:199], v[132:133], v[198:199], v[82:83] op_sel_hi:[0,1,1]
	v_pk_fma_f32 v[200:201], v[132:133], v[200:201], v[84:85] op_sel_hi:[0,1,1]
	v_pk_fma_f32 v[202:203], v[132:133], v[202:203], v[86:87] op_sel_hi:[0,1,1]
	v_pk_fma_f32 v[204:205], v[132:133], v[204:205], v[88:89] op_sel_hi:[0,1,1]
	v_pk_fma_f32 v[206:207], v[132:133], v[206:207], v[90:91] op_sel_hi:[0,1,1]
	v_pk_fma_f32 v[208:209], v[132:133], v[208:209], v[92:93] op_sel_hi:[0,1,1]
	v_pk_fma_f32 v[210:211], v[132:133], v[210:211], v[94:95] op_sel_hi:[0,1,1]
	s_waitcnt lgkmcnt(15)
	v_pk_fma_f32 v[128:129], v[64:65], v[196:197], v[192:193]
	v_pk_fma_f32 v[130:131], v[66:67], v[198:199], v[192:193]
	v_pk_fma_f32 v[128:129], v[68:69], v[200:201], v[128:129]
	v_pk_fma_f32 v[130:131], v[70:71], v[202:203], v[130:131]
	s_waitcnt lgkmcnt(14)
	v_pk_fma_f32 v[128:129], v[72:73], v[204:205], v[128:129]
	v_pk_fma_f32 v[130:131], v[74:75], v[206:207], v[130:131]
	s_waitcnt lgkmcnt(13)
	v_pk_fma_f32 v[128:129], v[76:77], v[208:209], v[128:129]
	v_pk_fma_f32 v[130:131], v[78:79], v[210:211], v[130:131]
	v_add_f32_e32 v128, v128, v129
	v_add_f32_e32 v130, v130, v131
	v_add_f32_e32 v190, v128, v130
	s_waitcnt lgkmcnt(6)
	v_mul_f32_e32 v153, v154, v155
	v_pk_mul_f32 v[112:113], v[112:113], v[152:153] op_sel:[0,1] op_sel_hi:[1,1]
	v_add_f32_dpp v190, v190, v190 row_ror:8 row_mask:0xf bank_mask:0xf bound_ctrl:1
	v_pk_mul_f32 v[114:115], v[114:115], v[152:153] op_sel:[0,1] op_sel_hi:[1,1]
	v_pk_mul_f32 v[116:117], v[116:117], v[152:153] op_sel:[0,1] op_sel_hi:[1,1]
	v_add_f32_dpp v190, v190, v190 row_ror:4 row_mask:0xf bank_mask:0xf bound_ctrl:1
	v_pk_mul_f32 v[118:119], v[118:119], v[152:153] op_sel:[0,1] op_sel_hi:[1,1]
	v_pk_mul_f32 v[120:121], v[120:121], v[152:153] op_sel:[0,1] op_sel_hi:[1,1]
	v_add_f32_dpp v190, v190, v190 row_ror:2 row_mask:0xf bank_mask:0xf bound_ctrl:1
	v_pk_mul_f32 v[122:123], v[122:123], v[152:153] op_sel:[0,1] op_sel_hi:[1,1]
	v_pk_mul_f32 v[124:125], v[124:125], v[152:153] op_sel:[0,1] op_sel_hi:[1,1]
	v_add_f32_dpp v190, v190, v190 row_ror:1 row_mask:0xf bank_mask:0xf bound_ctrl:1
	v_pk_mul_f32 v[126:127], v[126:127], v[152:153] op_sel:[0,1] op_sel_hi:[1,1]
	s_waitcnt lgkmcnt(5)
	v_pk_fma_f32 v[196:197], v[152:153], v[196:197], v[112:113] op_sel_hi:[0,1,1]
	s_and_saveexec_b64 s[8:9], s[44:45]
	ds_write_b32 v189, v190 offset:34432
	s_mov_b64 exec, s[8:9]
	v_pk_fma_f32 v[198:199], v[152:153], v[198:199], v[114:115] op_sel_hi:[0,1,1]
	v_pk_fma_f32 v[200:201], v[152:153], v[200:201], v[116:117] op_sel_hi:[0,1,1]
	v_pk_fma_f32 v[202:203], v[152:153], v[202:203], v[118:119] op_sel_hi:[0,1,1]
	v_pk_fma_f32 v[204:205], v[152:153], v[204:205], v[120:121] op_sel_hi:[0,1,1]
	v_pk_fma_f32 v[206:207], v[152:153], v[206:207], v[122:123] op_sel_hi:[0,1,1]
	v_pk_fma_f32 v[208:209], v[152:153], v[208:209], v[124:125] op_sel_hi:[0,1,1]
	v_pk_fma_f32 v[210:211], v[152:153], v[210:211], v[126:127] op_sel_hi:[0,1,1]
	s_waitcnt lgkmcnt(5)
	v_pk_fma_f32 v[128:129], v[96:97], v[196:197], v[192:193]
	v_pk_fma_f32 v[130:131], v[98:99], v[198:199], v[192:193]
	s_waitcnt lgkmcnt(4)
	v_pk_fma_f32 v[128:129], v[100:101], v[200:201], v[128:129]
	v_pk_fma_f32 v[130:131], v[102:103], v[202:203], v[130:131]
	s_waitcnt lgkmcnt(3)
	v_pk_fma_f32 v[128:129], v[104:105], v[204:205], v[128:129]
	v_pk_fma_f32 v[130:131], v[106:107], v[206:207], v[130:131]
	s_waitcnt lgkmcnt(2)
	v_pk_fma_f32 v[128:129], v[108:109], v[208:209], v[128:129]
	v_pk_fma_f32 v[130:131], v[110:111], v[210:211], v[130:131]
	v_add_f32_e32 v128, v128, v129
	v_add_f32_e32 v130, v130, v131
	v_add_f32_e32 v191, v128, v130
	s_nop 1
	v_add_f32_dpp v191, v191, v191 row_ror:8 row_mask:0xf bank_mask:0xf bound_ctrl:1
	s_nop 1
	v_add_f32_dpp v191, v191, v191 row_ror:4 row_mask:0xf bank_mask:0xf bound_ctrl:1
	s_nop 1
	v_add_f32_dpp v191, v191, v191 row_ror:2 row_mask:0xf bank_mask:0xf bound_ctrl:1
	s_nop 1
	v_add_f32_dpp v191, v191, v191 row_ror:1 row_mask:0xf bank_mask:0xf bound_ctrl:1
	s_and_saveexec_b64 s[8:9], s[44:45]
	ds_write_b32 v189, v191 offset:34496
	s_mov_b64 exec, s[8:9]
	s_waitcnt vmcnt(11)
	ds_write_b128 v185, v[16:19] offset:17024
	s_waitcnt vmcnt(9)
	ds_write_b128 v186, v[24:27] offset:17024
	ds_write_b128 v185, v[20:23] offset:25216
	s_waitcnt vmcnt(8)
	ds_write_b128 v186, v[28:31] offset:25216
	s_and_saveexec_b64 s[8:9], s[42:43]
	ds_write_b32 v144, v184 offset:33408
	s_or_b64 exec, exec, s[8:9]
	s_and_saveexec_b64 s[8:9], s[40:41]
	s_cbranch_execz .LBB0_1474
	v_add_f32_e32 v64, v156, v157
	v_mul_f32_e64 v65, |v64|, s62
	v_exp_f32_e32 v65, v65
	v_min_f32_e32 v64, 0, v64
	v_add_f32_e32 v65, 1.0, v65
	v_cmp_gt_f32_e32 vcc, s5, v65
	s_nop 1
	v_cndmask_b32_e64 v66, 0, 32, vcc
	v_ldexp_f32 v65, v65, v66
	v_log_f32_e32 v65, v65
	v_cndmask_b32_e32 v67, 0, v171, vcc
	v_add_f32_e32 v66, v145, v179
	v_mul_f32_e32 v68, 0x3f317217, v65
	v_fma_f32 v68, v65, s76, -v68
	v_fmac_f32_e32 v68, 0x3377d1cf, v65
	v_fmac_f32_e32 v68, 0x3f317217, v65
	v_cmp_lt_f32_e64 vcc, |v65|, s77
	s_nop 1
	v_cndmask_b32_e32 v65, v65, v68, vcc
	v_sub_f32_e32 v65, v65, v67
	v_sub_f32_e32 v64, v64, v65
	v_add_u32_e32 v65, 0x8400, v144
	ds_write2_b32 v65, v66, v64 offset0:32 offset1:48
.LBB0_1474:
	s_or_b64 exec, exec, s[8:9]
	s_and_saveexec_b64 s[8:9], s[46:47]
	s_cbranch_execz .LBB0_1483
	v_mov_b32_e32 v65, 0
	v_mov_b32_e32 v64, 0xf149f2ca
	s_and_saveexec_b64 s[64:65], s[40:41]
	v_add_u32_e32 v64, 0x8400, v144
	ds_read2_b32 v[64:65], v64 offset0:32 offset1:48
	s_or_b64 exec, exec, s[64:65]
	s_waitcnt lgkmcnt(0)
	v_add_f32_dpp v66, v64, v65 row_shr:1 row_mask:0xf bank_mask:0xf bound_ctrl:1
	v_max_f32_e32 v67, v64, v64
	v_max_f32_e32 v66, v66, v67
	v_cndmask_b32_e64 v66, v64, v66, s[48:49]
	v_add_f32_dpp v67, v65, v65 row_shr:1 row_mask:0xf bank_mask:0xf bound_ctrl:1
	v_cndmask_b32_e64 v67, v65, v67, s[48:49]
	v_max_f32_e32 v69, v66, v66
	s_nop 0
	v_add_f32_dpp v68, v66, v67 row_shr:2 row_mask:0xf bank_mask:0xf bound_ctrl:1
	v_max_f32_e32 v68, v68, v69
	v_add_f32_dpp v69, v67, v67 row_shr:2 row_mask:0xf bank_mask:0xf bound_ctrl:1
	v_cndmask_b32_e64 v66, v66, v68, s[50:51]
	v_cndmask_b32_e64 v67, v67, v69, s[50:51]
	v_max_f32_e32 v69, v66, v66
	s_nop 0
	v_add_f32_dpp v68, v66, v67 row_shr:4 row_mask:0xf bank_mask:0xf bound_ctrl:1
	v_max_f32_e32 v68, v68, v69
	v_cndmask_b32_e64 v66, v66, v68, s[52:53]
	ds_read_b32 v68, v140 offset:35328
	v_add_f32_dpp v69, v67, v67 row_shr:4 row_mask:0xf bank_mask:0xf bound_ctrl:1
	v_cndmask_b32_e64 v67, v67, v69, s[52:53]
	v_max_f32_e32 v66, v66, v66
	s_waitcnt lgkmcnt(0)
	v_add_f32_e32 v67, v68, v67
	v_max_f32_e32 v66, v67, v66
	v_mov_b32_e32 v67, 0
	v_sub_f32_e32 v64, v64, v66
	v_mul_f32_e32 v64, 0x3fb8aa3b, v64
	v_mov_b32_dpp v67, v66 row_shr:1 row_mask:0xf bank_mask:0xf
	v_cndmask_b32_e64 v67, v67, v68, s[38:39]
	v_add_f32_e32 v65, v65, v67
	v_sub_f32_e32 v65, v65, v66
	v_mul_f32_e32 v65, 0x3fb8aa3b, v65
	v_exp_f32_e32 v65, v65
	v_exp_f32_e32 v64, v64
	v_add_u32_e32 v67, 0x8800, v144
	ds_write2_b32 v67, v65, v64 offset0:160 offset1:176
	ds_write_b32 v144, v66 offset:35264
	s_and_b64 exec, exec, s[54:55]
	ds_write_b32 v140, v66 offset:35328

.LBB0_1478:
	s_and_saveexec_b64 s[8:9], s[40:41]
	s_cbranch_execz .LBB0_1485
	v_add_u32_e32 v64, s73, v147
	ds_read_b32 v68, v183 offset:34048
	v_ashrrev_i32_e32 v65, 31, v64
	v_lshlrev_b64 v[64:65], 4, v[64:65]
	v_lshl_or_b32 v64, s70, 2, v64
	v_lshl_add_u64 v[66:67], s[96:97], 0, v[64:65]
	s_waitcnt lgkmcnt(0)
	global_store_dword v[66:67], v68, off
	ds_read_b32 v66, v144 offset:35200
	v_lshl_add_u64 v[64:65], s[34:35], 0, v[64:65]
	s_waitcnt lgkmcnt(0)
	global_store_dword v[64:65], v66, off
.LBB0_1485:
	s_or_b64 exec, exec, s[8:9]
	s_waitcnt lgkmcnt(0)
	v_mov_b32_e32 v192, 0
	v_mov_b32_e32 v193, 0
	ds_read_b128 v[80:83], v188 offset:25216
	ds_read_b128 v[84:87], v188 offset:25472
	ds_read_b128 v[88:91], v188 offset:25728
	ds_read_b128 v[92:95], v188 offset:25984
	ds_read_b32 v134, v140 offset:35520
	ds_read_b32 v135, v189 offset:33408
	ds_read_b32 v132, v140 offset:35456
	ds_read_b128 v[64:67], v188 offset:17024
	ds_read_b128 v[68:71], v188 offset:17280
	ds_read_b128 v[72:75], v188 offset:17536
	ds_read_b128 v[76:79], v188 offset:17792
	ds_read_b128 v[112:115], v188 offset:26240
	ds_read_b128 v[116:119], v188 offset:26496
	ds_read_b128 v[120:123], v188 offset:26752
	ds_read_b128 v[124:127], v188 offset:27008
	ds_read_b32 v154, v140 offset:35524
	ds_read_b32 v155, v189 offset:33472
	ds_read_b32 v152, v140 offset:35460
	ds_read_b128 v[96:99], v188 offset:18048
	ds_read_b128 v[100:103], v188 offset:18304
	ds_read_b128 v[104:107], v188 offset:18560
	ds_read_b128 v[108:111], v188 offset:18816
	s_waitcnt lgkmcnt(15)
	v_mul_f32_e32 v133, v134, v135
	v_pk_mul_f32 v[80:81], v[80:81], v[132:133] op_sel:[0,1] op_sel_hi:[1,1]
	v_pk_mul_f32 v[82:83], v[82:83], v[132:133] op_sel:[0,1] op_sel_hi:[1,1]
	v_pk_mul_f32 v[84:85], v[84:85], v[132:133] op_sel:[0,1] op_sel_hi:[1,1]
	v_pk_mul_f32 v[86:87], v[86:87], v[132:133] op_sel:[0,1] op_sel_hi:[1,1]
	v_pk_mul_f32 v[88:89], v[88:89], v[132:133] op_sel:[0,1] op_sel_hi:[1,1]
	v_pk_mul_f32 v[90:91], v[90:91], v[132:133] op_sel:[0,1] op_sel_hi:[1,1]
	v_pk_mul_f32 v[92:93], v[92:93], v[132:133] op_sel:[0,1] op_sel_hi:[1,1]
	v_pk_mul_f32 v[94:95], v[94:95], v[132:133] op_sel:[0,1] op_sel_hi:[1,1]
	v_pk_fma_f32 v[196:197], v[132:133], v[196:197], v[80:81] op_sel_hi:[0,1,1]
	v_pk_fma_f32 v[198:199], v[132:133], v[198:199], v[82:83] op_sel_hi:[0,1,1]
	v_pk_fma_f32 v[200:201], v[132:133], v[200:201], v[84:85] op_sel_hi:[0,1,1]
	v_pk_fma_f32 v[202:203], v[132:133], v[202:203], v[86:87] op_sel_hi:[0,1,1]
	v_pk_fma_f32 v[204:205], v[132:133], v[204:205], v[88:89] op_sel_hi:[0,1,1]
	v_pk_fma_f32 v[206:207], v[132:133], v[206:207], v[90:91] op_sel_hi:[0,1,1]
	v_pk_fma_f32 v[208:209], v[132:133], v[208:209], v[92:93] op_sel_hi:[0,1,1]
	v_pk_fma_f32 v[210:211], v[132:133], v[210:211], v[94:95] op_sel_hi:[0,1,1]
	s_waitcnt lgkmcnt(14)
	v_pk_fma_f32 v[128:129], v[64:65], v[196:197], v[192:193]
	v_pk_fma_f32 v[130:131], v[66:67], v[198:199], v[192:193]
	s_waitcnt lgkmcnt(13)
	v_pk_fma_f32 v[128:129], v[68:69], v[200:201], v[128:129]
	v_pk_fma_f32 v[130:131], v[70:71], v[202:203], v[130:131]
	s_waitcnt lgkmcnt(12)
	v_pk_fma_f32 v[128:129], v[72:73], v[204:205], v[128:129]
	v_pk_fma_f32 v[130:131], v[74:75], v[206:207], v[130:131]
	s_waitcnt lgkmcnt(11)
	v_pk_fma_f32 v[128:129], v[76:77], v[208:209], v[128:129]
	v_pk_fma_f32 v[130:131], v[78:79], v[210:211], v[130:131]
	v_add_f32_e32 v128, v128, v129
	v_add_f32_e32 v130, v130, v131
	v_add_f32_e32 v190, v128, v130
	ds_read_b128 v[80:83], v188 offset:27264
	ds_read_b128 v[84:87], v188 offset:27520
	ds_read_b128 v[88:91], v188 offset:27776
	ds_read_b128 v[92:95], v188 offset:28032
	ds_read_b32 v134, v140 offset:35528
	ds_read_b32 v135, v189 offset:33536
	ds_read_b32 v132, v140 offset:35464
	ds_read_b128 v[64:67], v188 offset:19072
	ds_read_b128 v[68:71], v188 offset:19328
	ds_read_b128 v[72:75], v188 offset:19584
	ds_read_b128 v[76:79], v188 offset:19840
	s_waitcnt lgkmcnt(15)
	v_mul_f32_e32 v153, v154, v155
	v_pk_mul_f32 v[112:113], v[112:113], v[152:153] op_sel:[0,1] op_sel_hi:[1,1]
	v_add_f32_dpp v190, v190, v190 row_ror:8 row_mask:0xf bank_mask:0xf bound_ctrl:1
	v_pk_mul_f32 v[114:115], v[114:115], v[152:153] op_sel:[0,1] op_sel_hi:[1,1]
	v_pk_mul_f32 v[116:117], v[116:117], v[152:153] op_sel:[0,1] op_sel_hi:[1,1]
	v_add_f32_dpp v190, v190, v190 row_ror:4 row_mask:0xf bank_mask:0xf bound_ctrl:1
	v_pk_mul_f32 v[118:119], v[118:119], v[152:153] op_sel:[0,1] op_sel_hi:[1,1]
	v_pk_mul_f32 v[120:121], v[120:121], v[152:153] op_sel:[0,1] op_sel_hi:[1,1]
	v_add_f32_dpp v190, v190, v190 row_ror:2 row_mask:0xf bank_mask:0xf bound_ctrl:1
	v_pk_mul_f32 v[122:123], v[122:123], v[152:153] op_sel:[0,1] op_sel_hi:[1,1]
	v_pk_mul_f32 v[124:125], v[124:125], v[152:153] op_sel:[0,1] op_sel_hi:[1,1]
	v_add_f32_dpp v190, v190, v190 row_ror:1 row_mask:0xf bank_mask:0xf bound_ctrl:1
	v_pk_mul_f32 v[126:127], v[126:127], v[152:153] op_sel:[0,1] op_sel_hi:[1,1]
	v_pk_fma_f32 v[196:197], v[152:153], v[196:197], v[112:113] op_sel_hi:[0,1,1]
	s_and_saveexec_b64 s[8:9], s[44:45]
	ds_write_b32 v189, v190 offset:34560
	s_mov_b64 exec, s[8:9]
	v_pk_fma_f32 v[198:199], v[152:153], v[198:199], v[114:115] op_sel_hi:[0,1,1]
	v_pk_fma_f32 v[200:201], v[152:153], v[200:201], v[116:117] op_sel_hi:[0,1,1]
	v_pk_fma_f32 v[202:203], v[152:153], v[202:203], v[118:119] op_sel_hi:[0,1,1]
	v_pk_fma_f32 v[204:205], v[152:153], v[204:205], v[120:121] op_sel_hi:[0,1,1]
	v_pk_fma_f32 v[206:207], v[152:153], v[206:207], v[122:123] op_sel_hi:[0,1,1]
	v_pk_fma_f32 v[208:209], v[152:153], v[208:209], v[124:125] op_sel_hi:[0,1,1]
	v_pk_fma_f32 v[210:211], v[152:153], v[210:211], v[126:127] op_sel_hi:[0,1,1]
	s_waitcnt lgkmcnt(15)
	v_pk_fma_f32 v[128:129], v[96:97], v[196:197], v[192:193]
	v_pk_fma_f32 v[130:131], v[98:99], v[198:199], v[192:193]
	s_waitcnt lgkmcnt(14)
	v_pk_fma_f32 v[128:129], v[100:101], v[200:201], v[128:129]
	v_pk_fma_f32 v[130:131], v[102:103], v[202:203], v[130:131]
	s_waitcnt lgkmcnt(13)
	v_pk_fma_f32 v[128:129], v[104:105], v[204:205], v[128:129]
	v_pk_fma_f32 v[130:131], v[106:107], v[206:207], v[130:131]
	s_waitcnt lgkmcnt(12)
	v_pk_fma_f32 v[128:129], v[108:109], v[208:209], v[128:129]
	v_pk_fma_f32 v[130:131], v[110:111], v[210:211], v[130:131]
	v_add_f32_e32 v128, v128, v129
	v_add_f32_e32 v130, v130, v131
	v_add_f32_e32 v191, v128, v130
	ds_read_b128 v[112:115], v188 offset:28288
	ds_read_b128 v[116:119], v188 offset:28544
	ds_read_b128 v[120:123], v188 offset:28800
	ds_read_b128 v[124:127], v188 offset:29056
	ds_read_b32 v154, v140 offset:35532
	ds_read_b32 v155, v189 offset:33600
	ds_read_b32 v152, v140 offset:35468
	ds_read_b128 v[96:99], v188 offset:20096
	ds_read_b128 v[100:103], v188 offset:20352
	ds_read_b128 v[104:107], v188 offset:20608
	ds_read_b128 v[108:111], v188 offset:20864
	s_waitcnt lgkmcnt(15)
	v_mul_f32_e32 v133, v134, v135
	v_pk_mul_f32 v[80:81], v[80:81], v[132:133] op_sel:[0,1] op_sel_hi:[1,1]
	v_add_f32_dpp v191, v191, v191 row_ror:8 row_mask:0xf bank_mask:0xf bound_ctrl:1
	v_pk_mul_f32 v[82:83], v[82:83], v[132:133] op_sel:[0,1] op_sel_hi:[1,1]
	v_pk_mul_f32 v[84:85], v[84:85], v[132:133] op_sel:[0,1] op_sel_hi:[1,1]
	v_add_f32_dpp v191, v191, v191 row_ror:4 row_mask:0xf bank_mask:0xf bound_ctrl:1
	v_pk_mul_f32 v[86:87], v[86:87], v[132:133] op_sel:[0,1] op_sel_hi:[1,1]
	v_pk_mul_f32 v[88:89], v[88:89], v[132:133] op_sel:[0,1] op_sel_hi:[1,1]
	v_add_f32_dpp v191, v191, v191 row_ror:2 row_mask:0xf bank_mask:0xf bound_ctrl:1
	v_pk_mul_f32 v[90:91], v[90:91], v[132:133] op_sel:[0,1] op_sel_hi:[1,1]
	v_pk_mul_f32 v[92:93], v[92:93], v[132:133] op_sel:[0,1] op_sel_hi:[1,1]
	v_add_f32_dpp v191, v191, v191 row_ror:1 row_mask:0xf bank_mask:0xf bound_ctrl:1
	v_pk_mul_f32 v[94:95], v[94:95], v[132:133] op_sel:[0,1] op_sel_hi:[1,1]
	v_pk_fma_f32 v[196:197], v[132:133], v[196:197], v[80:81] op_sel_hi:[0,1,1]
	s_and_saveexec_b64 s[8:9], s[44:45]
	ds_write_b32 v189, v191 offset:34624
	s_mov_b64 exec, s[8:9]
	v_pk_fma_f32 v[198:199], v[132:133], v[198:199], v[82:83] op_sel_hi:[0,1,1]
	v_pk_fma_f32 v[200:201], v[132:133], v[200:201], v[84:85] op_sel_hi:[0,1,1]
	v_pk_fma_f32 v[202:203], v[132:133], v[202:203], v[86:87] op_sel_hi:[0,1,1]
	v_pk_fma_f32 v[204:205], v[132:133], v[204:205], v[88:89] op_sel_hi:[0,1,1]
	v_pk_fma_f32 v[206:207], v[132:133], v[206:207], v[90:91] op_sel_hi:[0,1,1]
	v_pk_fma_f32 v[208:209], v[132:133], v[208:209], v[92:93] op_sel_hi:[0,1,1]
	v_pk_fma_f32 v[210:211], v[132:133], v[210:211], v[94:95] op_sel_hi:[0,1,1]
	s_waitcnt lgkmcnt(15)
	v_pk_fma_f32 v[128:129], v[64:65], v[196:197], v[192:193]
	v_pk_fma_f32 v[130:131], v[66:67], v[198:199], v[192:193]
	v_pk_fma_f32 v[128:129], v[68:69], v[200:201], v[128:129]
	v_pk_fma_f32 v[130:131], v[70:71], v[202:203], v[130:131]
	s_waitcnt lgkmcnt(14)
	v_pk_fma_f32 v[128:129], v[72:73], v[204:205], v[128:129]
	v_pk_fma_f32 v[130:131], v[74:75], v[206:207], v[130:131]
	s_waitcnt lgkmcnt(13)
	v_pk_fma_f32 v[128:129], v[76:77], v[208:209], v[128:129]
	v_pk_fma_f32 v[130:131], v[78:79], v[210:211], v[130:131]
	v_add_f32_e32 v128, v128, v129
	v_add_f32_e32 v130, v130, v131
	v_add_f32_e32 v190, v128, v130
	ds_read_b128 v[80:83], v188 offset:29312
	ds_read_b128 v[84:87], v188 offset:29568
	ds_read_b128 v[88:91], v188 offset:29824
	ds_read_b128 v[92:95], v188 offset:30080
	ds_read_b32 v134, v140 offset:35536
	ds_read_b32 v135, v189 offset:33664
	ds_read_b32 v132, v140 offset:35472
	ds_read_b128 v[64:67], v188 offset:21120
	ds_read_b128 v[68:71], v188 offset:21376
	ds_read_b128 v[72:75], v188 offset:21632
	ds_read_b128 v[76:79], v188 offset:21888
	s_waitcnt lgkmcnt(15)
	v_mul_f32_e32 v153, v154, v155
	v_pk_mul_f32 v[112:113], v[112:113], v[152:153] op_sel:[0,1] op_sel_hi:[1,1]
	v_add_f32_dpp v190, v190, v190 row_ror:8 row_mask:0xf bank_mask:0xf bound_ctrl:1
	v_pk_mul_f32 v[114:115], v[114:115], v[152:153] op_sel:[0,1] op_sel_hi:[1,1]
	v_pk_mul_f32 v[116:117], v[116:117], v[152:153] op_sel:[0,1] op_sel_hi:[1,1]
	v_add_f32_dpp v190, v190, v190 row_ror:4 row_mask:0xf bank_mask:0xf bound_ctrl:1
	v_pk_mul_f32 v[118:119], v[118:119], v[152:153] op_sel:[0,1] op_sel_hi:[1,1]
	v_pk_mul_f32 v[120:121], v[120:121], v[152:153] op_sel:[0,1] op_sel_hi:[1,1]
	v_add_f32_dpp v190, v190, v190 row_ror:2 row_mask:0xf bank_mask:0xf bound_ctrl:1
	v_pk_mul_f32 v[122:123], v[122:123], v[152:153] op_sel:[0,1] op_sel_hi:[1,1]
	v_pk_mul_f32 v[124:125], v[124:125], v[152:153] op_sel:[0,1] op_sel_hi:[1,1]
	v_add_f32_dpp v190, v190, v190 row_ror:1 row_mask:0xf bank_mask:0xf bound_ctrl:1
	v_pk_mul_f32 v[126:127], v[126:127], v[152:153] op_sel:[0,1] op_sel_hi:[1,1]
	v_pk_fma_f32 v[196:197], v[152:153], v[196:197], v[112:113] op_sel_hi:[0,1,1]
	s_and_saveexec_b64 s[8:9], s[44:45]
	ds_write_b32 v189, v190 offset:34688
	s_mov_b64 exec, s[8:9]
	v_pk_fma_f32 v[198:199], v[152:153], v[198:199], v[114:115] op_sel_hi:[0,1,1]
	v_pk_fma_f32 v[200:201], v[152:153], v[200:201], v[116:117] op_sel_hi:[0,1,1]
	v_pk_fma_f32 v[202:203], v[152:153], v[202:203], v[118:119] op_sel_hi:[0,1,1]
	v_pk_fma_f32 v[204:205], v[152:153], v[204:205], v[120:121] op_sel_hi:[0,1,1]
	v_pk_fma_f32 v[206:207], v[152:153], v[206:207], v[122:123] op_sel_hi:[0,1,1]
	v_pk_fma_f32 v[208:209], v[152:153], v[208:209], v[124:125] op_sel_hi:[0,1,1]
	v_pk_fma_f32 v[210:211], v[152:153], v[210:211], v[126:127] op_sel_hi:[0,1,1]
	s_waitcnt lgkmcnt(15)
	v_pk_fma_f32 v[128:129], v[96:97], v[196:197], v[192:193]
	v_pk_fma_f32 v[130:131], v[98:99], v[198:199], v[192:193]
	v_pk_fma_f32 v[128:129], v[100:101], v[200:201], v[128:129]
	v_pk_fma_f32 v[130:131], v[102:103], v[202:203], v[130:131]
	s_waitcnt lgkmcnt(14)
	v_pk_fma_f32 v[128:129], v[104:105], v[204:205], v[128:129]
	v_pk_fma_f32 v[130:131], v[106:107], v[206:207], v[130:131]
	s_waitcnt lgkmcnt(13)
	v_pk_fma_f32 v[128:129], v[108:109], v[208:209], v[128:129]
	v_pk_fma_f32 v[130:131], v[110:111], v[210:211], v[130:131]
	v_add_f32_e32 v128, v128, v129
	v_add_f32_e32 v130, v130, v131
	v_add_f32_e32 v191, v128, v130
	ds_read_b128 v[112:115], v188 offset:30336
	ds_read_b128 v[116:119], v188 offset:30592
	ds_read_b128 v[120:123], v188 offset:30848
	ds_read_b128 v[124:127], v188 offset:31104
	ds_read_b32 v154, v140 offset:35540
	ds_read_b32 v155, v189 offset:33728
	ds_read_b32 v152, v140 offset:35476
	ds_read_b128 v[96:99], v188 offset:22144
	ds_read_b128 v[100:103], v188 offset:22400
	ds_read_b128 v[104:107], v188 offset:22656
	ds_read_b128 v[108:111], v188 offset:22912
	s_waitcnt lgkmcnt(15)
	v_mul_f32_e32 v133, v134, v135
	v_pk_mul_f32 v[80:81], v[80:81], v[132:133] op_sel:[0,1] op_sel_hi:[1,1]
	v_add_f32_dpp v191, v191, v191 row_ror:8 row_mask:0xf bank_mask:0xf bound_ctrl:1
	v_pk_mul_f32 v[82:83], v[82:83], v[132:133] op_sel:[0,1] op_sel_hi:[1,1]
	v_pk_mul_f32 v[84:85], v[84:85], v[132:133] op_sel:[0,1] op_sel_hi:[1,1]
	v_add_f32_dpp v191, v191, v191 row_ror:4 row_mask:0xf bank_mask:0xf bound_ctrl:1
	v_pk_mul_f32 v[86:87], v[86:87], v[132:133] op_sel:[0,1] op_sel_hi:[1,1]
	v_pk_mul_f32 v[88:89], v[88:89], v[132:133] op_sel:[0,1] op_sel_hi:[1,1]
	v_add_f32_dpp v191, v191, v191 row_ror:2 row_mask:0xf bank_mask:0xf bound_ctrl:1
	v_pk_mul_f32 v[90:91], v[90:91], v[132:133] op_sel:[0,1] op_sel_hi:[1,1]
	v_pk_mul_f32 v[92:93], v[92:93], v[132:133] op_sel:[0,1] op_sel_hi:[1,1]
	v_add_f32_dpp v191, v191, v191 row_ror:1 row_mask:0xf bank_mask:0xf bound_ctrl:1
	v_pk_mul_f32 v[94:95], v[94:95], v[132:133] op_sel:[0,1] op_sel_hi:[1,1]
	v_pk_fma_f32 v[196:197], v[132:133], v[196:197], v[80:81] op_sel_hi:[0,1,1]
	s_and_saveexec_b64 s[8:9], s[44:45]
	ds_write_b32 v189, v191 offset:34752
	s_mov_b64 exec, s[8:9]
	v_pk_fma_f32 v[198:199], v[132:133], v[198:199], v[82:83] op_sel_hi:[0,1,1]
	v_pk_fma_f32 v[200:201], v[132:133], v[200:201], v[84:85] op_sel_hi:[0,1,1]
	v_pk_fma_f32 v[202:203], v[132:133], v[202:203], v[86:87] op_sel_hi:[0,1,1]
	v_pk_fma_f32 v[204:205], v[132:133], v[204:205], v[88:89] op_sel_hi:[0,1,1]
	v_pk_fma_f32 v[206:207], v[132:133], v[206:207], v[90:91] op_sel_hi:[0,1,1]
	v_pk_fma_f32 v[208:209], v[132:133], v[208:209], v[92:93] op_sel_hi:[0,1,1]
	v_pk_fma_f32 v[210:211], v[132:133], v[210:211], v[94:95] op_sel_hi:[0,1,1]
	s_waitcnt lgkmcnt(15)
	v_pk_fma_f32 v[128:129], v[64:65], v[196:197], v[192:193]
	v_pk_fma_f32 v[130:131], v[66:67], v[198:199], v[192:193]
	v_pk_fma_f32 v[128:129], v[68:69], v[200:201], v[128:129]
	v_pk_fma_f32 v[130:131], v[70:71], v[202:203], v[130:131]
	s_waitcnt lgkmcnt(14)
	v_pk_fma_f32 v[128:129], v[72:73], v[204:205], v[128:129]
	v_pk_fma_f32 v[130:131], v[74:75], v[206:207], v[130:131]
	s_waitcnt lgkmcnt(13)
	v_pk_fma_f32 v[128:129], v[76:77], v[208:209], v[128:129]
	v_pk_fma_f32 v[130:131], v[78:79], v[210:211], v[130:131]
	v_add_f32_e32 v128, v128, v129
	v_add_f32_e32 v130, v130, v131
	v_add_f32_e32 v190, v128, v130
	ds_read_b128 v[80:83], v188 offset:31360
	ds_read_b128 v[84:87], v188 offset:31616
	ds_read_b128 v[88:91], v188 offset:31872
	ds_read_b128 v[92:95], v188 offset:32128
	ds_read_b32 v134, v140 offset:35544
	ds_read_b32 v135, v189 offset:33792
	ds_read_b32 v132, v140 offset:35480
	ds_read_b128 v[64:67], v188 offset:23168
	ds_read_b128 v[68:71], v188 offset:23424
	ds_read_b128 v[72:75], v188 offset:23680
	ds_read_b128 v[76:79], v188 offset:23936
	s_waitcnt lgkmcnt(15)
	v_mul_f32_e32 v153, v154, v155
	v_pk_mul_f32 v[112:113], v[112:113], v[152:153] op_sel:[0,1] op_sel_hi:[1,1]
	v_add_f32_dpp v190, v190, v190 row_ror:8 row_mask:0xf bank_mask:0xf bound_ctrl:1
	v_pk_mul_f32 v[114:115], v[114:115], v[152:153] op_sel:[0,1] op_sel_hi:[1,1]
	v_pk_mul_f32 v[116:117], v[116:117], v[152:153] op_sel:[0,1] op_sel_hi:[1,1]
	v_add_f32_dpp v190, v190, v190 row_ror:4 row_mask:0xf bank_mask:0xf bound_ctrl:1
	v_pk_mul_f32 v[118:119], v[118:119], v[152:153] op_sel:[0,1] op_sel_hi:[1,1]
	v_pk_mul_f32 v[120:121], v[120:121], v[152:153] op_sel:[0,1] op_sel_hi:[1,1]
	v_add_f32_dpp v190, v190, v190 row_ror:2 row_mask:0xf bank_mask:0xf bound_ctrl:1
	v_pk_mul_f32 v[122:123], v[122:123], v[152:153] op_sel:[0,1] op_sel_hi:[1,1]
	v_pk_mul_f32 v[124:125], v[124:125], v[152:153] op_sel:[0,1] op_sel_hi:[1,1]
	v_add_f32_dpp v190, v190, v190 row_ror:1 row_mask:0xf bank_mask:0xf bound_ctrl:1
	v_pk_mul_f32 v[126:127], v[126:127], v[152:153] op_sel:[0,1] op_sel_hi:[1,1]
	v_pk_fma_f32 v[196:197], v[152:153], v[196:197], v[112:113] op_sel_hi:[0,1,1]
	s_and_saveexec_b64 s[8:9], s[44:45]
	ds_write_b32 v189, v190 offset:34816
	s_mov_b64 exec, s[8:9]
	v_pk_fma_f32 v[198:199], v[152:153], v[198:199], v[114:115] op_sel_hi:[0,1,1]
	v_pk_fma_f32 v[200:201], v[152:153], v[200:201], v[116:117] op_sel_hi:[0,1,1]
	v_pk_fma_f32 v[202:203], v[152:153], v[202:203], v[118:119] op_sel_hi:[0,1,1]
	v_pk_fma_f32 v[204:205], v[152:153], v[204:205], v[120:121] op_sel_hi:[0,1,1]
	v_pk_fma_f32 v[206:207], v[152:153], v[206:207], v[122:123] op_sel_hi:[0,1,1]
	v_pk_fma_f32 v[208:209], v[152:153], v[208:209], v[124:125] op_sel_hi:[0,1,1]
	v_pk_fma_f32 v[210:211], v[152:153], v[210:211], v[126:127] op_sel_hi:[0,1,1]
	s_waitcnt lgkmcnt(15)
	v_pk_fma_f32 v[128:129], v[96:97], v[196:197], v[192:193]
	v_pk_fma_f32 v[130:131], v[98:99], v[198:199], v[192:193]
	v_pk_fma_f32 v[128:129], v[100:101], v[200:201], v[128:129]
	v_pk_fma_f32 v[130:131], v[102:103], v[202:203], v[130:131]
	s_waitcnt lgkmcnt(14)
	v_pk_fma_f32 v[128:129], v[104:105], v[204:205], v[128:129]
	v_pk_fma_f32 v[130:131], v[106:107], v[206:207], v[130:131]
	s_waitcnt lgkmcnt(13)
	v_pk_fma_f32 v[128:129], v[108:109], v[208:209], v[128:129]
	v_pk_fma_f32 v[130:131], v[110:111], v[210:211], v[130:131]
	v_add_f32_e32 v128, v128, v129
	v_add_f32_e32 v130, v130, v131
	v_add_f32_e32 v191, v128, v130
	ds_read_b128 v[112:115], v188 offset:32384
	ds_read_b128 v[116:119], v188 offset:32640
	ds_read_b128 v[120:123], v188 offset:32896
	ds_read_b128 v[124:127], v188 offset:33152
	ds_read_b32 v154, v140 offset:35548
	ds_read_b32 v155, v189 offset:33856
	ds_read_b32 v152, v140 offset:35484
	ds_read_b128 v[96:99], v188 offset:24192
	ds_read_b128 v[100:103], v188 offset:24448
	ds_read_b128 v[104:107], v188 offset:24704
	ds_read_b128 v[108:111], v188 offset:24960
	s_waitcnt lgkmcnt(15)
	v_mul_f32_e32 v133, v134, v135
	v_pk_mul_f32 v[80:81], v[80:81], v[132:133] op_sel:[0,1] op_sel_hi:[1,1]
	v_add_f32_dpp v191, v191, v191 row_ror:8 row_mask:0xf bank_mask:0xf bound_ctrl:1
	v_pk_mul_f32 v[82:83], v[82:83], v[132:133] op_sel:[0,1] op_sel_hi:[1,1]
	v_pk_mul_f32 v[84:85], v[84:85], v[132:133] op_sel:[0,1] op_sel_hi:[1,1]
	v_add_f32_dpp v191, v191, v191 row_ror:4 row_mask:0xf bank_mask:0xf bound_ctrl:1
	v_pk_mul_f32 v[86:87], v[86:87], v[132:133] op_sel:[0,1] op_sel_hi:[1,1]
	v_pk_mul_f32 v[88:89], v[88:89], v[132:133] op_sel:[0,1] op_sel_hi:[1,1]
	v_add_f32_dpp v191, v191, v191 row_ror:2 row_mask:0xf bank_mask:0xf bound_ctrl:1
	v_pk_mul_f32 v[90:91], v[90:91], v[132:133] op_sel:[0,1] op_sel_hi:[1,1]
	v_pk_mul_f32 v[92:93], v[92:93], v[132:133] op_sel:[0,1] op_sel_hi:[1,1]
	v_add_f32_dpp v191, v191, v191 row_ror:1 row_mask:0xf bank_mask:0xf bound_ctrl:1
	v_pk_mul_f32 v[94:95], v[94:95], v[132:133] op_sel:[0,1] op_sel_hi:[1,1]
	v_pk_fma_f32 v[196:197], v[132:133], v[196:197], v[80:81] op_sel_hi:[0,1,1]
	s_and_saveexec_b64 s[8:9], s[44:45]
	ds_write_b32 v189, v191 offset:34880
	s_mov_b64 exec, s[8:9]
	v_pk_fma_f32 v[198:199], v[132:133], v[198:199], v[82:83] op_sel_hi:[0,1,1]
	v_pk_fma_f32 v[200:201], v[132:133], v[200:201], v[84:85] op_sel_hi:[0,1,1]
	v_pk_fma_f32 v[202:203], v[132:133], v[202:203], v[86:87] op_sel_hi:[0,1,1]
	v_pk_fma_f32 v[204:205], v[132:133], v[204:205], v[88:89] op_sel_hi:[0,1,1]
	v_pk_fma_f32 v[206:207], v[132:133], v[206:207], v[90:91] op_sel_hi:[0,1,1]
	v_pk_fma_f32 v[208:209], v[132:133], v[208:209], v[92:93] op_sel_hi:[0,1,1]
	v_pk_fma_f32 v[210:211], v[132:133], v[210:211], v[94:95] op_sel_hi:[0,1,1]
	s_waitcnt lgkmcnt(15)
	v_pk_fma_f32 v[128:129], v[64:65], v[196:197], v[192:193]
	v_pk_fma_f32 v[130:131], v[66:67], v[198:199], v[192:193]
	v_pk_fma_f32 v[128:129], v[68:69], v[200:201], v[128:129]
	v_pk_fma_f32 v[130:131], v[70:71], v[202:203], v[130:131]
	s_waitcnt lgkmcnt(14)
	v_pk_fma_f32 v[128:129], v[72:73], v[204:205], v[128:129]
	v_pk_fma_f32 v[130:131], v[74:75], v[206:207], v[130:131]
	s_waitcnt lgkmcnt(13)
	v_pk_fma_f32 v[128:129], v[76:77], v[208:209], v[128:129]
	v_pk_fma_f32 v[130:131], v[78:79], v[210:211], v[130:131]
	v_add_f32_e32 v128, v128, v129
	v_add_f32_e32 v130, v130, v131
	v_add_f32_e32 v190, v128, v130
	s_waitcnt lgkmcnt(6)
	v_mul_f32_e32 v153, v154, v155
	v_pk_mul_f32 v[112:113], v[112:113], v[152:153] op_sel:[0,1] op_sel_hi:[1,1]
	v_add_f32_dpp v190, v190, v190 row_ror:8 row_mask:0xf bank_mask:0xf bound_ctrl:1
	v_pk_mul_f32 v[114:115], v[114:115], v[152:153] op_sel:[0,1] op_sel_hi:[1,1]
	v_pk_mul_f32 v[116:117], v[116:117], v[152:153] op_sel:[0,1] op_sel_hi:[1,1]
	v_add_f32_dpp v190, v190, v190 row_ror:4 row_mask:0xf bank_mask:0xf bound_ctrl:1
	v_pk_mul_f32 v[118:119], v[118:119], v[152:153] op_sel:[0,1] op_sel_hi:[1,1]
	v_pk_mul_f32 v[120:121], v[120:121], v[152:153] op_sel:[0,1] op_sel_hi:[1,1]
	v_add_f32_dpp v190, v190, v190 row_ror:2 row_mask:0xf bank_mask:0xf bound_ctrl:1
	v_pk_mul_f32 v[122:123], v[122:123], v[152:153] op_sel:[0,1] op_sel_hi:[1,1]
	v_pk_mul_f32 v[124:125], v[124:125], v[152:153] op_sel:[0,1] op_sel_hi:[1,1]
	v_add_f32_dpp v190, v190, v190 row_ror:1 row_mask:0xf bank_mask:0xf bound_ctrl:1
	v_pk_mul_f32 v[126:127], v[126:127], v[152:153] op_sel:[0,1] op_sel_hi:[1,1]
	s_waitcnt lgkmcnt(5)
	v_pk_fma_f32 v[196:197], v[152:153], v[196:197], v[112:113] op_sel_hi:[0,1,1]
	s_and_saveexec_b64 s[8:9], s[44:45]
	ds_write_b32 v189, v190 offset:34944
	s_mov_b64 exec, s[8:9]
	v_pk_fma_f32 v[198:199], v[152:153], v[198:199], v[114:115] op_sel_hi:[0,1,1]
	v_pk_fma_f32 v[200:201], v[152:153], v[200:201], v[116:117] op_sel_hi:[0,1,1]
	v_pk_fma_f32 v[202:203], v[152:153], v[202:203], v[118:119] op_sel_hi:[0,1,1]
	v_pk_fma_f32 v[204:205], v[152:153], v[204:205], v[120:121] op_sel_hi:[0,1,1]
	v_pk_fma_f32 v[206:207], v[152:153], v[206:207], v[122:123] op_sel_hi:[0,1,1]
	v_pk_fma_f32 v[208:209], v[152:153], v[208:209], v[124:125] op_sel_hi:[0,1,1]
	v_pk_fma_f32 v[210:211], v[152:153], v[210:211], v[126:127] op_sel_hi:[0,1,1]
	s_waitcnt lgkmcnt(5)
	v_pk_fma_f32 v[128:129], v[96:97], v[196:197], v[192:193]
	v_pk_fma_f32 v[130:131], v[98:99], v[198:199], v[192:193]
	s_waitcnt lgkmcnt(4)
	v_pk_fma_f32 v[128:129], v[100:101], v[200:201], v[128:129]
	v_pk_fma_f32 v[130:131], v[102:103], v[202:203], v[130:131]
	s_waitcnt lgkmcnt(3)
	v_pk_fma_f32 v[128:129], v[104:105], v[204:205], v[128:129]
	v_pk_fma_f32 v[130:131], v[106:107], v[206:207], v[130:131]
	s_waitcnt lgkmcnt(2)
	v_pk_fma_f32 v[128:129], v[108:109], v[208:209], v[128:129]
	v_pk_fma_f32 v[130:131], v[110:111], v[210:211], v[130:131]
	v_add_f32_e32 v128, v128, v129
	v_add_f32_e32 v130, v130, v131
	v_add_f32_e32 v191, v128, v130
	s_nop 1
	v_add_f32_dpp v191, v191, v191 row_ror:8 row_mask:0xf bank_mask:0xf bound_ctrl:1
	s_nop 1
	v_add_f32_dpp v191, v191, v191 row_ror:4 row_mask:0xf bank_mask:0xf bound_ctrl:1
	s_nop 1
	v_add_f32_dpp v191, v191, v191 row_ror:2 row_mask:0xf bank_mask:0xf bound_ctrl:1
	s_nop 1
	v_add_f32_dpp v191, v191, v191 row_ror:1 row_mask:0xf bank_mask:0xf bound_ctrl:1
	s_and_saveexec_b64 s[8:9], s[44:45]
	ds_write_b32 v189, v191 offset:35008
	s_mov_b64 exec, s[8:9]
	s_waitcnt vmcnt(7)
	ds_write_b128 v185, v[32:35]
	s_waitcnt vmcnt(5)
	ds_write_b128 v186, v[40:43]
	ds_write_b128 v185, v[36:39] offset:8192
	s_waitcnt vmcnt(4)
	ds_write_b128 v186, v[44:47] offset:8192
	s_and_saveexec_b64 s[8:9], s[42:43]
	ds_write_b32 v144, v184 offset:16384
	s_or_b64 exec, exec, s[8:9]
	s_and_saveexec_b64 s[8:9], s[40:41]
	s_cbranch_execz .LBB0_1505
	v_add_f32_e32 v64, v156, v182
	v_mul_f32_e64 v65, |v64|, s62
	v_exp_f32_e32 v65, v65
	v_min_f32_e32 v64, 0, v64
	v_add_f32_e32 v65, 1.0, v65
	v_cmp_gt_f32_e32 vcc, s5, v65
	s_nop 1
	v_cndmask_b32_e64 v66, 0, 32, vcc
	v_ldexp_f32 v65, v65, v66
	v_log_f32_e32 v65, v65
	v_cndmask_b32_e32 v67, 0, v171, vcc
	v_add_f32_e32 v66, v145, v180
	v_mul_f32_e32 v68, 0x3f317217, v65
	v_fma_f32 v68, v65, s76, -v68
	v_fmac_f32_e32 v68, 0x3377d1cf, v65
	v_fmac_f32_e32 v68, 0x3f317217, v65
	v_cmp_lt_f32_e64 vcc, |v65|, s77
	s_nop 1
	v_cndmask_b32_e32 v65, v65, v68, vcc
	v_sub_f32_e32 v65, v65, v67
	v_sub_f32_e32 v64, v64, v65
	v_add_u32_e32 v65, 0x4000, v144
	ds_write2_b32 v65, v66, v64 offset0:128 offset1:144
.LBB0_1505:
	s_or_b64 exec, exec, s[8:9]
	s_and_saveexec_b64 s[8:9], s[46:47]
	s_cbranch_execz .LBB0_1514
	v_mov_b32_e32 v65, 0
	v_mov_b32_e32 v64, 0xf149f2ca
	s_and_saveexec_b64 s[64:65], s[40:41]
	v_add_u32_e32 v64, 0x4000, v144
	ds_read2_b32 v[64:65], v64 offset0:128 offset1:144
	s_or_b64 exec, exec, s[64:65]
	s_waitcnt lgkmcnt(0)
	v_add_f32_dpp v66, v64, v65 row_shr:1 row_mask:0xf bank_mask:0xf bound_ctrl:1
	v_max_f32_e32 v67, v64, v64
	v_max_f32_e32 v66, v66, v67
	v_cndmask_b32_e64 v66, v64, v66, s[48:49]
	v_add_f32_dpp v67, v65, v65 row_shr:1 row_mask:0xf bank_mask:0xf bound_ctrl:1
	v_cndmask_b32_e64 v67, v65, v67, s[48:49]
	v_max_f32_e32 v69, v66, v66
	s_nop 0
	v_add_f32_dpp v68, v66, v67 row_shr:2 row_mask:0xf bank_mask:0xf bound_ctrl:1
	v_max_f32_e32 v68, v68, v69
	v_add_f32_dpp v69, v67, v67 row_shr:2 row_mask:0xf bank_mask:0xf bound_ctrl:1
	v_cndmask_b32_e64 v66, v66, v68, s[50:51]
	v_cndmask_b32_e64 v67, v67, v69, s[50:51]
	v_max_f32_e32 v69, v66, v66
	s_nop 0
	v_add_f32_dpp v68, v66, v67 row_shr:4 row_mask:0xf bank_mask:0xf bound_ctrl:1
	v_max_f32_e32 v68, v68, v69
	v_cndmask_b32_e64 v66, v66, v68, s[52:53]
	ds_read_b32 v68, v140 offset:35328
	v_add_f32_dpp v69, v67, v67 row_shr:4 row_mask:0xf bank_mask:0xf bound_ctrl:1
	v_cndmask_b32_e64 v67, v67, v69, s[52:53]
	v_max_f32_e32 v66, v66, v66
	s_waitcnt lgkmcnt(0)
	v_add_f32_e32 v67, v68, v67
	v_max_f32_e32 v66, v67, v66
	v_mov_b32_e32 v67, 0
	v_sub_f32_e32 v64, v64, v66
	v_mul_f32_e32 v64, 0x3fb8aa3b, v64
	v_mov_b32_dpp v67, v66 row_shr:1 row_mask:0xf bank_mask:0xf
	v_cndmask_b32_e64 v67, v67, v68, s[38:39]
	v_add_f32_e32 v65, v65, v67
	v_sub_f32_e32 v65, v65, v66
	v_mul_f32_e32 v65, 0x3fb8aa3b, v65
	v_exp_f32_e32 v65, v65
	v_exp_f32_e32 v64, v64
	v_add_u32_e32 v67, 0x8800, v144
	ds_write2_b32 v67, v65, v64 offset0:64 offset1:80
	ds_write_b32 v144, v66 offset:35200
	s_and_b64 exec, exec, s[54:55]
	ds_write_b32 v140, v66 offset:35328

.LBB0_1509:
	s_and_saveexec_b64 s[8:9], s[40:41]
	s_cbranch_execz .LBB0_1516
	v_add3_u32 v64, v147, s73, 8
	ds_read_b32 v68, v183 offset:34560
	v_ashrrev_i32_e32 v65, 31, v64
	v_lshlrev_b64 v[64:65], 4, v[64:65]
	v_lshl_or_b32 v64, s70, 2, v64
	v_lshl_add_u64 v[66:67], s[96:97], 0, v[64:65]
	s_waitcnt lgkmcnt(0)
	global_store_dword v[66:67], v68, off
	ds_read_b32 v66, v144 offset:35264
	v_lshl_add_u64 v[64:65], s[34:35], 0, v[64:65]
	s_waitcnt lgkmcnt(0)
	global_store_dword v[64:65], v66, off
.LBB0_1516:
	s_or_b64 exec, exec, s[8:9]
	s_waitcnt lgkmcnt(0)
	v_mov_b32_e32 v192, 0
	v_mov_b32_e32 v193, 0
	ds_read_b128 v[80:83], v188 offset:8192
	ds_read_b128 v[84:87], v188 offset:8448
	ds_read_b128 v[88:91], v188 offset:8704
	ds_read_b128 v[92:95], v188 offset:8960
	ds_read_b32 v134, v140 offset:35136
	ds_read_b32 v135, v189 offset:16384
	ds_read_b32 v132, v140 offset:35072
	ds_read_b128 v[64:67], v188
	ds_read_b128 v[68:71], v188 offset:256
	ds_read_b128 v[72:75], v188 offset:512
	ds_read_b128 v[76:79], v188 offset:768
	ds_read_b128 v[112:115], v188 offset:9216
	ds_read_b128 v[116:119], v188 offset:9472
	ds_read_b128 v[120:123], v188 offset:9728
	ds_read_b128 v[124:127], v188 offset:9984
	ds_read_b32 v154, v140 offset:35140
	ds_read_b32 v155, v189 offset:16448
	ds_read_b32 v152, v140 offset:35076
	ds_read_b128 v[96:99], v188 offset:1024
	ds_read_b128 v[100:103], v188 offset:1280
	ds_read_b128 v[104:107], v188 offset:1536
	ds_read_b128 v[108:111], v188 offset:1792
	s_waitcnt lgkmcnt(15)
	v_mul_f32_e32 v133, v134, v135
	v_pk_mul_f32 v[80:81], v[80:81], v[132:133] op_sel:[0,1] op_sel_hi:[1,1]
	v_pk_mul_f32 v[82:83], v[82:83], v[132:133] op_sel:[0,1] op_sel_hi:[1,1]
	v_pk_mul_f32 v[84:85], v[84:85], v[132:133] op_sel:[0,1] op_sel_hi:[1,1]
	v_pk_mul_f32 v[86:87], v[86:87], v[132:133] op_sel:[0,1] op_sel_hi:[1,1]
	v_pk_mul_f32 v[88:89], v[88:89], v[132:133] op_sel:[0,1] op_sel_hi:[1,1]
	v_pk_mul_f32 v[90:91], v[90:91], v[132:133] op_sel:[0,1] op_sel_hi:[1,1]
	v_pk_mul_f32 v[92:93], v[92:93], v[132:133] op_sel:[0,1] op_sel_hi:[1,1]
	v_pk_mul_f32 v[94:95], v[94:95], v[132:133] op_sel:[0,1] op_sel_hi:[1,1]
	v_pk_fma_f32 v[196:197], v[132:133], v[196:197], v[80:81] op_sel_hi:[0,1,1]
	v_pk_fma_f32 v[198:199], v[132:133], v[198:199], v[82:83] op_sel_hi:[0,1,1]
	v_pk_fma_f32 v[200:201], v[132:133], v[200:201], v[84:85] op_sel_hi:[0,1,1]
	v_pk_fma_f32 v[202:203], v[132:133], v[202:203], v[86:87] op_sel_hi:[0,1,1]
	v_pk_fma_f32 v[204:205], v[132:133], v[204:205], v[88:89] op_sel_hi:[0,1,1]
	v_pk_fma_f32 v[206:207], v[132:133], v[206:207], v[90:91] op_sel_hi:[0,1,1]
	v_pk_fma_f32 v[208:209], v[132:133], v[208:209], v[92:93] op_sel_hi:[0,1,1]
	v_pk_fma_f32 v[210:211], v[132:133], v[210:211], v[94:95] op_sel_hi:[0,1,1]
	s_waitcnt lgkmcnt(14)
	v_pk_fma_f32 v[128:129], v[64:65], v[196:197], v[192:193]
	v_pk_fma_f32 v[130:131], v[66:67], v[198:199], v[192:193]
	s_waitcnt lgkmcnt(13)
	v_pk_fma_f32 v[128:129], v[68:69], v[200:201], v[128:129]
	v_pk_fma_f32 v[130:131], v[70:71], v[202:203], v[130:131]
	s_waitcnt lgkmcnt(12)
	v_pk_fma_f32 v[128:129], v[72:73], v[204:205], v[128:129]
	v_pk_fma_f32 v[130:131], v[74:75], v[206:207], v[130:131]
	s_waitcnt lgkmcnt(11)
	v_pk_fma_f32 v[128:129], v[76:77], v[208:209], v[128:129]
	v_pk_fma_f32 v[130:131], v[78:79], v[210:211], v[130:131]
	v_add_f32_e32 v128, v128, v129
	v_add_f32_e32 v130, v130, v131
	v_add_f32_e32 v190, v128, v130
	ds_read_b128 v[80:83], v188 offset:10240
	ds_read_b128 v[84:87], v188 offset:10496
	ds_read_b128 v[88:91], v188 offset:10752
	ds_read_b128 v[92:95], v188 offset:11008
	ds_read_b32 v134, v140 offset:35144
	ds_read_b32 v135, v189 offset:16512
	ds_read_b32 v132, v140 offset:35080
	ds_read_b128 v[64:67], v188 offset:2048
	ds_read_b128 v[68:71], v188 offset:2304
	ds_read_b128 v[72:75], v188 offset:2560
	ds_read_b128 v[76:79], v188 offset:2816
	s_waitcnt lgkmcnt(15)
	v_mul_f32_e32 v153, v154, v155
	v_pk_mul_f32 v[112:113], v[112:113], v[152:153] op_sel:[0,1] op_sel_hi:[1,1]
	v_add_f32_dpp v190, v190, v190 row_ror:8 row_mask:0xf bank_mask:0xf bound_ctrl:1
	v_pk_mul_f32 v[114:115], v[114:115], v[152:153] op_sel:[0,1] op_sel_hi:[1,1]
	v_pk_mul_f32 v[116:117], v[116:117], v[152:153] op_sel:[0,1] op_sel_hi:[1,1]
	v_add_f32_dpp v190, v190, v190 row_ror:4 row_mask:0xf bank_mask:0xf bound_ctrl:1
	v_pk_mul_f32 v[118:119], v[118:119], v[152:153] op_sel:[0,1] op_sel_hi:[1,1]
	v_pk_mul_f32 v[120:121], v[120:121], v[152:153] op_sel:[0,1] op_sel_hi:[1,1]
	v_add_f32_dpp v190, v190, v190 row_ror:2 row_mask:0xf bank_mask:0xf bound_ctrl:1
	v_pk_mul_f32 v[122:123], v[122:123], v[152:153] op_sel:[0,1] op_sel_hi:[1,1]
	v_pk_mul_f32 v[124:125], v[124:125], v[152:153] op_sel:[0,1] op_sel_hi:[1,1]
	v_add_f32_dpp v190, v190, v190 row_ror:1 row_mask:0xf bank_mask:0xf bound_ctrl:1
	v_pk_mul_f32 v[126:127], v[126:127], v[152:153] op_sel:[0,1] op_sel_hi:[1,1]
	v_pk_fma_f32 v[196:197], v[152:153], v[196:197], v[112:113] op_sel_hi:[0,1,1]
	s_and_saveexec_b64 s[8:9], s[44:45]
	ds_write_b32 v189, v190 offset:34048
	s_mov_b64 exec, s[8:9]
	v_pk_fma_f32 v[198:199], v[152:153], v[198:199], v[114:115] op_sel_hi:[0,1,1]
	v_pk_fma_f32 v[200:201], v[152:153], v[200:201], v[116:117] op_sel_hi:[0,1,1]
	v_pk_fma_f32 v[202:203], v[152:153], v[202:203], v[118:119] op_sel_hi:[0,1,1]
	v_pk_fma_f32 v[204:205], v[152:153], v[204:205], v[120:121] op_sel_hi:[0,1,1]
	v_pk_fma_f32 v[206:207], v[152:153], v[206:207], v[122:123] op_sel_hi:[0,1,1]
	v_pk_fma_f32 v[208:209], v[152:153], v[208:209], v[124:125] op_sel_hi:[0,1,1]
	v_pk_fma_f32 v[210:211], v[152:153], v[210:211], v[126:127] op_sel_hi:[0,1,1]
	s_waitcnt lgkmcnt(15)
	v_pk_fma_f32 v[128:129], v[96:97], v[196:197], v[192:193]
	v_pk_fma_f32 v[130:131], v[98:99], v[198:199], v[192:193]
	s_waitcnt lgkmcnt(14)
	v_pk_fma_f32 v[128:129], v[100:101], v[200:201], v[128:129]
	v_pk_fma_f32 v[130:131], v[102:103], v[202:203], v[130:131]
	s_waitcnt lgkmcnt(13)
	v_pk_fma_f32 v[128:129], v[104:105], v[204:205], v[128:129]
	v_pk_fma_f32 v[130:131], v[106:107], v[206:207], v[130:131]
	s_waitcnt lgkmcnt(12)
	v_pk_fma_f32 v[128:129], v[108:109], v[208:209], v[128:129]
	v_pk_fma_f32 v[130:131], v[110:111], v[210:211], v[130:131]
	v_add_f32_e32 v128, v128, v129
	v_add_f32_e32 v130, v130, v131
	v_add_f32_e32 v191, v128, v130
	ds_read_b128 v[112:115], v188 offset:11264
	ds_read_b128 v[116:119], v188 offset:11520
	ds_read_b128 v[120:123], v188 offset:11776
	ds_read_b128 v[124:127], v188 offset:12032
	ds_read_b32 v154, v140 offset:35148
	ds_read_b32 v155, v189 offset:16576
	ds_read_b32 v152, v140 offset:35084
	ds_read_b128 v[96:99], v188 offset:3072
	ds_read_b128 v[100:103], v188 offset:3328
	ds_read_b128 v[104:107], v188 offset:3584
	ds_read_b128 v[108:111], v188 offset:3840
	s_waitcnt lgkmcnt(15)
	v_mul_f32_e32 v133, v134, v135
	v_pk_mul_f32 v[80:81], v[80:81], v[132:133] op_sel:[0,1] op_sel_hi:[1,1]
	v_add_f32_dpp v191, v191, v191 row_ror:8 row_mask:0xf bank_mask:0xf bound_ctrl:1
	v_pk_mul_f32 v[82:83], v[82:83], v[132:133] op_sel:[0,1] op_sel_hi:[1,1]
	v_pk_mul_f32 v[84:85], v[84:85], v[132:133] op_sel:[0,1] op_sel_hi:[1,1]
	v_add_f32_dpp v191, v191, v191 row_ror:4 row_mask:0xf bank_mask:0xf bound_ctrl:1
	v_pk_mul_f32 v[86:87], v[86:87], v[132:133] op_sel:[0,1] op_sel_hi:[1,1]
	v_pk_mul_f32 v[88:89], v[88:89], v[132:133] op_sel:[0,1] op_sel_hi:[1,1]
	v_add_f32_dpp v191, v191, v191 row_ror:2 row_mask:0xf bank_mask:0xf bound_ctrl:1
	v_pk_mul_f32 v[90:91], v[90:91], v[132:133] op_sel:[0,1] op_sel_hi:[1,1]
	v_pk_mul_f32 v[92:93], v[92:93], v[132:133] op_sel:[0,1] op_sel_hi:[1,1]
	v_add_f32_dpp v191, v191, v191 row_ror:1 row_mask:0xf bank_mask:0xf bound_ctrl:1
	v_pk_mul_f32 v[94:95], v[94:95], v[132:133] op_sel:[0,1] op_sel_hi:[1,1]
	v_pk_fma_f32 v[196:197], v[132:133], v[196:197], v[80:81] op_sel_hi:[0,1,1]
	s_and_saveexec_b64 s[8:9], s[44:45]
	ds_write_b32 v189, v191 offset:34112
	s_mov_b64 exec, s[8:9]
	v_pk_fma_f32 v[198:199], v[132:133], v[198:199], v[82:83] op_sel_hi:[0,1,1]
	v_pk_fma_f32 v[200:201], v[132:133], v[200:201], v[84:85] op_sel_hi:[0,1,1]
	v_pk_fma_f32 v[202:203], v[132:133], v[202:203], v[86:87] op_sel_hi:[0,1,1]
	v_pk_fma_f32 v[204:205], v[132:133], v[204:205], v[88:89] op_sel_hi:[0,1,1]
	v_pk_fma_f32 v[206:207], v[132:133], v[206:207], v[90:91] op_sel_hi:[0,1,1]
	v_pk_fma_f32 v[208:209], v[132:133], v[208:209], v[92:93] op_sel_hi:[0,1,1]
	v_pk_fma_f32 v[210:211], v[132:133], v[210:211], v[94:95] op_sel_hi:[0,1,1]
	s_waitcnt lgkmcnt(15)
	v_pk_fma_f32 v[128:129], v[64:65], v[196:197], v[192:193]
	v_pk_fma_f32 v[130:131], v[66:67], v[198:199], v[192:193]
	v_pk_fma_f32 v[128:129], v[68:69], v[200:201], v[128:129]
	v_pk_fma_f32 v[130:131], v[70:71], v[202:203], v[130:131]
	s_waitcnt lgkmcnt(14)
	v_pk_fma_f32 v[128:129], v[72:73], v[204:205], v[128:129]
	v_pk_fma_f32 v[130:131], v[74:75], v[206:207], v[130:131]
	s_waitcnt lgkmcnt(13)
	v_pk_fma_f32 v[128:129], v[76:77], v[208:209], v[128:129]
	v_pk_fma_f32 v[130:131], v[78:79], v[210:211], v[130:131]
	v_add_f32_e32 v128, v128, v129
	v_add_f32_e32 v130, v130, v131
	v_add_f32_e32 v190, v128, v130
	ds_read_b128 v[80:83], v188 offset:12288
	ds_read_b128 v[84:87], v188 offset:12544
	ds_read_b128 v[88:91], v188 offset:12800
	ds_read_b128 v[92:95], v188 offset:13056
	ds_read_b32 v134, v140 offset:35152
	ds_read_b32 v135, v189 offset:16640
	ds_read_b32 v132, v140 offset:35088
	ds_read_b128 v[64:67], v188 offset:4096
	ds_read_b128 v[68:71], v188 offset:4352
	ds_read_b128 v[72:75], v188 offset:4608
	ds_read_b128 v[76:79], v188 offset:4864
	s_waitcnt lgkmcnt(15)
	v_mul_f32_e32 v153, v154, v155
	v_pk_mul_f32 v[112:113], v[112:113], v[152:153] op_sel:[0,1] op_sel_hi:[1,1]
	v_add_f32_dpp v190, v190, v190 row_ror:8 row_mask:0xf bank_mask:0xf bound_ctrl:1
	v_pk_mul_f32 v[114:115], v[114:115], v[152:153] op_sel:[0,1] op_sel_hi:[1,1]
	v_pk_mul_f32 v[116:117], v[116:117], v[152:153] op_sel:[0,1] op_sel_hi:[1,1]
	v_add_f32_dpp v190, v190, v190 row_ror:4 row_mask:0xf bank_mask:0xf bound_ctrl:1
	v_pk_mul_f32 v[118:119], v[118:119], v[152:153] op_sel:[0,1] op_sel_hi:[1,1]
	v_pk_mul_f32 v[120:121], v[120:121], v[152:153] op_sel:[0,1] op_sel_hi:[1,1]
	v_add_f32_dpp v190, v190, v190 row_ror:2 row_mask:0xf bank_mask:0xf bound_ctrl:1
	v_pk_mul_f32 v[122:123], v[122:123], v[152:153] op_sel:[0,1] op_sel_hi:[1,1]
	v_pk_mul_f32 v[124:125], v[124:125], v[152:153] op_sel:[0,1] op_sel_hi:[1,1]
	v_add_f32_dpp v190, v190, v190 row_ror:1 row_mask:0xf bank_mask:0xf bound_ctrl:1
	v_pk_mul_f32 v[126:127], v[126:127], v[152:153] op_sel:[0,1] op_sel_hi:[1,1]
	v_pk_fma_f32 v[196:197], v[152:153], v[196:197], v[112:113] op_sel_hi:[0,1,1]
	s_and_saveexec_b64 s[8:9], s[44:45]
	ds_write_b32 v189, v190 offset:34176
	s_mov_b64 exec, s[8:9]
	v_pk_fma_f32 v[198:199], v[152:153], v[198:199], v[114:115] op_sel_hi:[0,1,1]
	v_pk_fma_f32 v[200:201], v[152:153], v[200:201], v[116:117] op_sel_hi:[0,1,1]
	v_pk_fma_f32 v[202:203], v[152:153], v[202:203], v[118:119] op_sel_hi:[0,1,1]
	v_pk_fma_f32 v[204:205], v[152:153], v[204:205], v[120:121] op_sel_hi:[0,1,1]
	v_pk_fma_f32 v[206:207], v[152:153], v[206:207], v[122:123] op_sel_hi:[0,1,1]
	v_pk_fma_f32 v[208:209], v[152:153], v[208:209], v[124:125] op_sel_hi:[0,1,1]
	v_pk_fma_f32 v[210:211], v[152:153], v[210:211], v[126:127] op_sel_hi:[0,1,1]
	s_waitcnt lgkmcnt(15)
	v_pk_fma_f32 v[128:129], v[96:97], v[196:197], v[192:193]
	v_pk_fma_f32 v[130:131], v[98:99], v[198:199], v[192:193]
	v_pk_fma_f32 v[128:129], v[100:101], v[200:201], v[128:129]
	v_pk_fma_f32 v[130:131], v[102:103], v[202:203], v[130:131]
	s_waitcnt lgkmcnt(14)
	v_pk_fma_f32 v[128:129], v[104:105], v[204:205], v[128:129]
	v_pk_fma_f32 v[130:131], v[106:107], v[206:207], v[130:131]
	s_waitcnt lgkmcnt(13)
	v_pk_fma_f32 v[128:129], v[108:109], v[208:209], v[128:129]
	v_pk_fma_f32 v[130:131], v[110:111], v[210:211], v[130:131]
	v_add_f32_e32 v128, v128, v129
	v_add_f32_e32 v130, v130, v131
	v_add_f32_e32 v191, v128, v130
	ds_read_b128 v[112:115], v188 offset:13312
	ds_read_b128 v[116:119], v188 offset:13568
	ds_read_b128 v[120:123], v188 offset:13824
	ds_read_b128 v[124:127], v188 offset:14080
	ds_read_b32 v154, v140 offset:35156
	ds_read_b32 v155, v189 offset:16704
	ds_read_b32 v152, v140 offset:35092
	ds_read_b128 v[96:99], v188 offset:5120
	ds_read_b128 v[100:103], v188 offset:5376
	ds_read_b128 v[104:107], v188 offset:5632
	ds_read_b128 v[108:111], v188 offset:5888
	s_waitcnt lgkmcnt(15)
	v_mul_f32_e32 v133, v134, v135
	v_pk_mul_f32 v[80:81], v[80:81], v[132:133] op_sel:[0,1] op_sel_hi:[1,1]
	v_add_f32_dpp v191, v191, v191 row_ror:8 row_mask:0xf bank_mask:0xf bound_ctrl:1
	v_pk_mul_f32 v[82:83], v[82:83], v[132:133] op_sel:[0,1] op_sel_hi:[1,1]
	v_pk_mul_f32 v[84:85], v[84:85], v[132:133] op_sel:[0,1] op_sel_hi:[1,1]
	v_add_f32_dpp v191, v191, v191 row_ror:4 row_mask:0xf bank_mask:0xf bound_ctrl:1
	v_pk_mul_f32 v[86:87], v[86:87], v[132:133] op_sel:[0,1] op_sel_hi:[1,1]
	v_pk_mul_f32 v[88:89], v[88:89], v[132:133] op_sel:[0,1] op_sel_hi:[1,1]
	v_add_f32_dpp v191, v191, v191 row_ror:2 row_mask:0xf bank_mask:0xf bound_ctrl:1
	v_pk_mul_f32 v[90:91], v[90:91], v[132:133] op_sel:[0,1] op_sel_hi:[1,1]
	v_pk_mul_f32 v[92:93], v[92:93], v[132:133] op_sel:[0,1] op_sel_hi:[1,1]
	v_add_f32_dpp v191, v191, v191 row_ror:1 row_mask:0xf bank_mask:0xf bound_ctrl:1
	v_pk_mul_f32 v[94:95], v[94:95], v[132:133] op_sel:[0,1] op_sel_hi:[1,1]
	v_pk_fma_f32 v[196:197], v[132:133], v[196:197], v[80:81] op_sel_hi:[0,1,1]
	s_and_saveexec_b64 s[8:9], s[44:45]
	ds_write_b32 v189, v191 offset:34240
	s_mov_b64 exec, s[8:9]
	v_pk_fma_f32 v[198:199], v[132:133], v[198:199], v[82:83] op_sel_hi:[0,1,1]
	v_pk_fma_f32 v[200:201], v[132:133], v[200:201], v[84:85] op_sel_hi:[0,1,1]
	v_pk_fma_f32 v[202:203], v[132:133], v[202:203], v[86:87] op_sel_hi:[0,1,1]
	v_pk_fma_f32 v[204:205], v[132:133], v[204:205], v[88:89] op_sel_hi:[0,1,1]
	v_pk_fma_f32 v[206:207], v[132:133], v[206:207], v[90:91] op_sel_hi:[0,1,1]
	v_pk_fma_f32 v[208:209], v[132:133], v[208:209], v[92:93] op_sel_hi:[0,1,1]
	v_pk_fma_f32 v[210:211], v[132:133], v[210:211], v[94:95] op_sel_hi:[0,1,1]
	s_waitcnt lgkmcnt(15)
	v_pk_fma_f32 v[128:129], v[64:65], v[196:197], v[192:193]
	v_pk_fma_f32 v[130:131], v[66:67], v[198:199], v[192:193]
	v_pk_fma_f32 v[128:129], v[68:69], v[200:201], v[128:129]
	v_pk_fma_f32 v[130:131], v[70:71], v[202:203], v[130:131]
	s_waitcnt lgkmcnt(14)
	v_pk_fma_f32 v[128:129], v[72:73], v[204:205], v[128:129]
	v_pk_fma_f32 v[130:131], v[74:75], v[206:207], v[130:131]
	s_waitcnt lgkmcnt(13)
	v_pk_fma_f32 v[128:129], v[76:77], v[208:209], v[128:129]
	v_pk_fma_f32 v[130:131], v[78:79], v[210:211], v[130:131]
	v_add_f32_e32 v128, v128, v129
	v_add_f32_e32 v130, v130, v131
	v_add_f32_e32 v190, v128, v130
	ds_read_b128 v[80:83], v188 offset:14336
	ds_read_b128 v[84:87], v188 offset:14592
	ds_read_b128 v[88:91], v188 offset:14848
	ds_read_b128 v[92:95], v188 offset:15104
	ds_read_b32 v134, v140 offset:35160
	ds_read_b32 v135, v189 offset:16768
	ds_read_b32 v132, v140 offset:35096
	ds_read_b128 v[64:67], v188 offset:6144
	ds_read_b128 v[68:71], v188 offset:6400
	ds_read_b128 v[72:75], v188 offset:6656
	ds_read_b128 v[76:79], v188 offset:6912
	s_waitcnt lgkmcnt(15)
	v_mul_f32_e32 v153, v154, v155
	v_pk_mul_f32 v[112:113], v[112:113], v[152:153] op_sel:[0,1] op_sel_hi:[1,1]
	v_add_f32_dpp v190, v190, v190 row_ror:8 row_mask:0xf bank_mask:0xf bound_ctrl:1
	v_pk_mul_f32 v[114:115], v[114:115], v[152:153] op_sel:[0,1] op_sel_hi:[1,1]
	v_pk_mul_f32 v[116:117], v[116:117], v[152:153] op_sel:[0,1] op_sel_hi:[1,1]
	v_add_f32_dpp v190, v190, v190 row_ror:4 row_mask:0xf bank_mask:0xf bound_ctrl:1
	v_pk_mul_f32 v[118:119], v[118:119], v[152:153] op_sel:[0,1] op_sel_hi:[1,1]
	v_pk_mul_f32 v[120:121], v[120:121], v[152:153] op_sel:[0,1] op_sel_hi:[1,1]
	v_add_f32_dpp v190, v190, v190 row_ror:2 row_mask:0xf bank_mask:0xf bound_ctrl:1
	v_pk_mul_f32 v[122:123], v[122:123], v[152:153] op_sel:[0,1] op_sel_hi:[1,1]
	v_pk_mul_f32 v[124:125], v[124:125], v[152:153] op_sel:[0,1] op_sel_hi:[1,1]
	v_add_f32_dpp v190, v190, v190 row_ror:1 row_mask:0xf bank_mask:0xf bound_ctrl:1
	v_pk_mul_f32 v[126:127], v[126:127], v[152:153] op_sel:[0,1] op_sel_hi:[1,1]
	v_pk_fma_f32 v[196:197], v[152:153], v[196:197], v[112:113] op_sel_hi:[0,1,1]
	s_and_saveexec_b64 s[8:9], s[44:45]
	ds_write_b32 v189, v190 offset:34304
	s_mov_b64 exec, s[8:9]
	v_pk_fma_f32 v[198:199], v[152:153], v[198:199], v[114:115] op_sel_hi:[0,1,1]
	v_pk_fma_f32 v[200:201], v[152:153], v[200:201], v[116:117] op_sel_hi:[0,1,1]
	v_pk_fma_f32 v[202:203], v[152:153], v[202:203], v[118:119] op_sel_hi:[0,1,1]
	v_pk_fma_f32 v[204:205], v[152:153], v[204:205], v[120:121] op_sel_hi:[0,1,1]
	v_pk_fma_f32 v[206:207], v[152:153], v[206:207], v[122:123] op_sel_hi:[0,1,1]
	v_pk_fma_f32 v[208:209], v[152:153], v[208:209], v[124:125] op_sel_hi:[0,1,1]
	v_pk_fma_f32 v[210:211], v[152:153], v[210:211], v[126:127] op_sel_hi:[0,1,1]
	s_waitcnt lgkmcnt(15)
	v_pk_fma_f32 v[128:129], v[96:97], v[196:197], v[192:193]
	v_pk_fma_f32 v[130:131], v[98:99], v[198:199], v[192:193]
	v_pk_fma_f32 v[128:129], v[100:101], v[200:201], v[128:129]
	v_pk_fma_f32 v[130:131], v[102:103], v[202:203], v[130:131]
	s_waitcnt lgkmcnt(14)
	v_pk_fma_f32 v[128:129], v[104:105], v[204:205], v[128:129]
	v_pk_fma_f32 v[130:131], v[106:107], v[206:207], v[130:131]
	s_waitcnt lgkmcnt(13)
	v_pk_fma_f32 v[128:129], v[108:109], v[208:209], v[128:129]
	v_pk_fma_f32 v[130:131], v[110:111], v[210:211], v[130:131]
	v_add_f32_e32 v128, v128, v129
	v_add_f32_e32 v130, v130, v131
	v_add_f32_e32 v191, v128, v130
	ds_read_b128 v[112:115], v188 offset:15360
	ds_read_b128 v[116:119], v188 offset:15616
	ds_read_b128 v[120:123], v188 offset:15872
	ds_read_b128 v[124:127], v188 offset:16128
	ds_read_b32 v154, v140 offset:35164
	ds_read_b32 v155, v189 offset:16832
	ds_read_b32 v152, v140 offset:35100
	ds_read_b128 v[96:99], v188 offset:7168
	ds_read_b128 v[100:103], v188 offset:7424
	ds_read_b128 v[104:107], v188 offset:7680
	ds_read_b128 v[108:111], v188 offset:7936
	s_waitcnt lgkmcnt(15)
	v_mul_f32_e32 v133, v134, v135
	v_pk_mul_f32 v[80:81], v[80:81], v[132:133] op_sel:[0,1] op_sel_hi:[1,1]
	v_add_f32_dpp v191, v191, v191 row_ror:8 row_mask:0xf bank_mask:0xf bound_ctrl:1
	v_pk_mul_f32 v[82:83], v[82:83], v[132:133] op_sel:[0,1] op_sel_hi:[1,1]
	v_pk_mul_f32 v[84:85], v[84:85], v[132:133] op_sel:[0,1] op_sel_hi:[1,1]
	v_add_f32_dpp v191, v191, v191 row_ror:4 row_mask:0xf bank_mask:0xf bound_ctrl:1
	v_pk_mul_f32 v[86:87], v[86:87], v[132:133] op_sel:[0,1] op_sel_hi:[1,1]
	v_pk_mul_f32 v[88:89], v[88:89], v[132:133] op_sel:[0,1] op_sel_hi:[1,1]
	v_add_f32_dpp v191, v191, v191 row_ror:2 row_mask:0xf bank_mask:0xf bound_ctrl:1
	v_pk_mul_f32 v[90:91], v[90:91], v[132:133] op_sel:[0,1] op_sel_hi:[1,1]
	v_pk_mul_f32 v[92:93], v[92:93], v[132:133] op_sel:[0,1] op_sel_hi:[1,1]
	v_add_f32_dpp v191, v191, v191 row_ror:1 row_mask:0xf bank_mask:0xf bound_ctrl:1
	v_pk_mul_f32 v[94:95], v[94:95], v[132:133] op_sel:[0,1] op_sel_hi:[1,1]
	v_pk_fma_f32 v[196:197], v[132:133], v[196:197], v[80:81] op_sel_hi:[0,1,1]
	s_and_saveexec_b64 s[8:9], s[44:45]
	ds_write_b32 v189, v191 offset:34368
	s_mov_b64 exec, s[8:9]
	v_pk_fma_f32 v[198:199], v[132:133], v[198:199], v[82:83] op_sel_hi:[0,1,1]
	v_pk_fma_f32 v[200:201], v[132:133], v[200:201], v[84:85] op_sel_hi:[0,1,1]
	v_pk_fma_f32 v[202:203], v[132:133], v[202:203], v[86:87] op_sel_hi:[0,1,1]
	v_pk_fma_f32 v[204:205], v[132:133], v[204:205], v[88:89] op_sel_hi:[0,1,1]
	v_pk_fma_f32 v[206:207], v[132:133], v[206:207], v[90:91] op_sel_hi:[0,1,1]
	v_pk_fma_f32 v[208:209], v[132:133], v[208:209], v[92:93] op_sel_hi:[0,1,1]
	v_pk_fma_f32 v[210:211], v[132:133], v[210:211], v[94:95] op_sel_hi:[0,1,1]
	s_waitcnt lgkmcnt(15)
	v_pk_fma_f32 v[128:129], v[64:65], v[196:197], v[192:193]
	v_pk_fma_f32 v[130:131], v[66:67], v[198:199], v[192:193]
	v_pk_fma_f32 v[128:129], v[68:69], v[200:201], v[128:129]
	v_pk_fma_f32 v[130:131], v[70:71], v[202:203], v[130:131]
	s_waitcnt lgkmcnt(14)
	v_pk_fma_f32 v[128:129], v[72:73], v[204:205], v[128:129]
	v_pk_fma_f32 v[130:131], v[74:75], v[206:207], v[130:131]
	s_waitcnt lgkmcnt(13)
	v_pk_fma_f32 v[128:129], v[76:77], v[208:209], v[128:129]
	v_pk_fma_f32 v[130:131], v[78:79], v[210:211], v[130:131]
	v_add_f32_e32 v128, v128, v129
	v_add_f32_e32 v130, v130, v131
	v_add_f32_e32 v190, v128, v130
	s_waitcnt lgkmcnt(6)
	v_mul_f32_e32 v153, v154, v155
	v_pk_mul_f32 v[112:113], v[112:113], v[152:153] op_sel:[0,1] op_sel_hi:[1,1]
	v_add_f32_dpp v190, v190, v190 row_ror:8 row_mask:0xf bank_mask:0xf bound_ctrl:1
	v_pk_mul_f32 v[114:115], v[114:115], v[152:153] op_sel:[0,1] op_sel_hi:[1,1]
	v_pk_mul_f32 v[116:117], v[116:117], v[152:153] op_sel:[0,1] op_sel_hi:[1,1]
	v_add_f32_dpp v190, v190, v190 row_ror:4 row_mask:0xf bank_mask:0xf bound_ctrl:1
	v_pk_mul_f32 v[118:119], v[118:119], v[152:153] op_sel:[0,1] op_sel_hi:[1,1]
	v_pk_mul_f32 v[120:121], v[120:121], v[152:153] op_sel:[0,1] op_sel_hi:[1,1]
	v_add_f32_dpp v190, v190, v190 row_ror:2 row_mask:0xf bank_mask:0xf bound_ctrl:1
	v_pk_mul_f32 v[122:123], v[122:123], v[152:153] op_sel:[0,1] op_sel_hi:[1,1]
	v_pk_mul_f32 v[124:125], v[124:125], v[152:153] op_sel:[0,1] op_sel_hi:[1,1]
	v_add_f32_dpp v190, v190, v190 row_ror:1 row_mask:0xf bank_mask:0xf bound_ctrl:1
	v_pk_mul_f32 v[126:127], v[126:127], v[152:153] op_sel:[0,1] op_sel_hi:[1,1]
	s_waitcnt lgkmcnt(5)
	v_pk_fma_f32 v[196:197], v[152:153], v[196:197], v[112:113] op_sel_hi:[0,1,1]
	s_and_saveexec_b64 s[8:9], s[44:45]
	ds_write_b32 v189, v190 offset:34432
	s_mov_b64 exec, s[8:9]
	v_pk_fma_f32 v[198:199], v[152:153], v[198:199], v[114:115] op_sel_hi:[0,1,1]
	v_pk_fma_f32 v[200:201], v[152:153], v[200:201], v[116:117] op_sel_hi:[0,1,1]
	v_pk_fma_f32 v[202:203], v[152:153], v[202:203], v[118:119] op_sel_hi:[0,1,1]
	v_pk_fma_f32 v[204:205], v[152:153], v[204:205], v[120:121] op_sel_hi:[0,1,1]
	v_pk_fma_f32 v[206:207], v[152:153], v[206:207], v[122:123] op_sel_hi:[0,1,1]
	v_pk_fma_f32 v[208:209], v[152:153], v[208:209], v[124:125] op_sel_hi:[0,1,1]
	v_pk_fma_f32 v[210:211], v[152:153], v[210:211], v[126:127] op_sel_hi:[0,1,1]
	s_waitcnt lgkmcnt(5)
	v_pk_fma_f32 v[128:129], v[96:97], v[196:197], v[192:193]
	v_pk_fma_f32 v[130:131], v[98:99], v[198:199], v[192:193]
	s_waitcnt lgkmcnt(4)
	v_pk_fma_f32 v[128:129], v[100:101], v[200:201], v[128:129]
	v_pk_fma_f32 v[130:131], v[102:103], v[202:203], v[130:131]
	s_waitcnt lgkmcnt(3)
	v_pk_fma_f32 v[128:129], v[104:105], v[204:205], v[128:129]
	v_pk_fma_f32 v[130:131], v[106:107], v[206:207], v[130:131]
	s_waitcnt lgkmcnt(2)
	v_pk_fma_f32 v[128:129], v[108:109], v[208:209], v[128:129]
	v_pk_fma_f32 v[130:131], v[110:111], v[210:211], v[130:131]
	v_add_f32_e32 v128, v128, v129
	v_add_f32_e32 v130, v130, v131
	v_add_f32_e32 v191, v128, v130
	s_nop 1
	v_add_f32_dpp v191, v191, v191 row_ror:8 row_mask:0xf bank_mask:0xf bound_ctrl:1
	s_nop 1
	v_add_f32_dpp v191, v191, v191 row_ror:4 row_mask:0xf bank_mask:0xf bound_ctrl:1
	s_nop 1
	v_add_f32_dpp v191, v191, v191 row_ror:2 row_mask:0xf bank_mask:0xf bound_ctrl:1
	s_nop 1
	v_add_f32_dpp v191, v191, v191 row_ror:1 row_mask:0xf bank_mask:0xf bound_ctrl:1
	s_and_saveexec_b64 s[8:9], s[44:45]
	ds_write_b32 v189, v191 offset:34496
	s_mov_b64 exec, s[8:9]
	s_waitcnt vmcnt(3)
	ds_write_b128 v185, v[48:51] offset:17024
	s_waitcnt vmcnt(1)
	ds_write_b128 v186, v[56:59] offset:17024
	ds_write_b128 v185, v[52:55] offset:25216
	s_waitcnt vmcnt(0)
	ds_write_b128 v186, v[60:63] offset:25216
	s_and_saveexec_b64 s[8:9], s[42:43]
	ds_write_b32 v144, v184 offset:33408
	s_or_b64 exec, exec, s[8:9]
	s_and_saveexec_b64 s[8:9], s[40:41]
	s_cbranch_execz .LBB0_1536
	v_add_f32_e32 v64, v156, v181
	v_mul_f32_e64 v65, |v64|, s62
	v_exp_f32_e32 v65, v65
	v_min_f32_e32 v64, 0, v64
	v_add_f32_e32 v65, 1.0, v65
	v_cmp_gt_f32_e32 vcc, s5, v65
	s_nop 1
	v_cndmask_b32_e64 v66, 0, 32, vcc
	v_ldexp_f32 v65, v65, v66
	v_log_f32_e32 v65, v65
	v_cndmask_b32_e32 v67, 0, v171, vcc
	v_add_f32_e32 v66, v145, v187
	v_mul_f32_e32 v68, 0x3f317217, v65
	v_fma_f32 v68, v65, s76, -v68
	v_fmac_f32_e32 v68, 0x3377d1cf, v65
	v_fmac_f32_e32 v68, 0x3f317217, v65
	v_cmp_lt_f32_e64 vcc, |v65|, s77
	s_nop 1
	v_cndmask_b32_e32 v65, v65, v68, vcc
	v_sub_f32_e32 v65, v65, v67
	v_sub_f32_e32 v64, v64, v65
	v_add_u32_e32 v65, 0x8400, v144
	ds_write2_b32 v65, v66, v64 offset0:32 offset1:48
.LBB0_1536:
	s_or_b64 exec, exec, s[8:9]
	s_and_saveexec_b64 s[8:9], s[46:47]
	s_cbranch_execz .LBB0_1545
	v_mov_b32_e32 v64, 0xf149f2ca
	v_mov_b32_e32 v65, 0
	s_and_saveexec_b64 s[64:65], s[40:41]
	v_add_u32_e32 v64, 0x8400, v144
	ds_read2_b32 v[64:65], v64 offset0:32 offset1:48
	s_or_b64 exec, exec, s[64:65]
	s_waitcnt lgkmcnt(0)
	v_add_f32_dpp v66, v64, v65 row_shr:1 row_mask:0xf bank_mask:0xf bound_ctrl:1
	v_max_f32_e32 v67, v64, v64
	v_max_f32_e32 v66, v66, v67
	v_cndmask_b32_e64 v66, v64, v66, s[48:49]
	v_add_f32_dpp v67, v65, v65 row_shr:1 row_mask:0xf bank_mask:0xf bound_ctrl:1
	v_cndmask_b32_e64 v67, v65, v67, s[48:49]
	v_max_f32_e32 v69, v66, v66
	s_nop 0
	v_add_f32_dpp v68, v66, v67 row_shr:2 row_mask:0xf bank_mask:0xf bound_ctrl:1
	v_max_f32_e32 v68, v68, v69
	v_add_f32_dpp v69, v67, v67 row_shr:2 row_mask:0xf bank_mask:0xf bound_ctrl:1
	v_cndmask_b32_e64 v67, v67, v69, s[50:51]
	v_cndmask_b32_e64 v66, v66, v68, s[50:51]
	v_max_f32_e32 v69, v66, v66
	s_nop 0
	v_add_f32_dpp v68, v66, v67 row_shr:4 row_mask:0xf bank_mask:0xf bound_ctrl:1
	v_max_f32_e32 v68, v68, v69
	v_cndmask_b32_e64 v66, v66, v68, s[52:53]
	ds_read_b32 v68, v140 offset:35328
	v_add_f32_dpp v69, v67, v67 row_shr:4 row_mask:0xf bank_mask:0xf bound_ctrl:1
	v_cndmask_b32_e64 v67, v67, v69, s[52:53]
	v_max_f32_e32 v66, v66, v66
	s_waitcnt lgkmcnt(0)
	v_add_f32_e32 v67, v68, v67
	v_max_f32_e32 v66, v67, v66
	v_mov_b32_e32 v67, 0
	v_sub_f32_e32 v64, v64, v66
	v_mul_f32_e32 v64, 0x3fb8aa3b, v64
	v_mov_b32_dpp v67, v66 row_shr:1 row_mask:0xf bank_mask:0xf
	v_cndmask_b32_e64 v67, v67, v68, s[38:39]
	v_add_f32_e32 v65, v65, v67
	v_sub_f32_e32 v65, v65, v66
	v_mul_f32_e32 v65, 0x3fb8aa3b, v65
	v_exp_f32_e32 v65, v65
	v_exp_f32_e32 v64, v64
	v_add_u32_e32 v67, 0x8800, v144
	ds_write2_b32 v67, v65, v64 offset0:160 offset1:176
	ds_write_b32 v144, v66 offset:35264
	s_and_b64 exec, exec, s[54:55]
	ds_write_b32 v140, v66 offset:35328

.LBB0_1540:
	s_and_saveexec_b64 s[8:9], s[40:41]
	s_cbranch_execz .LBB0_1547
	v_add3_u32 v64, v147, s73, 16
	ds_read_b32 v68, v183 offset:34048
	v_ashrrev_i32_e32 v65, 31, v64
	v_lshlrev_b64 v[64:65], 4, v[64:65]
	v_lshl_or_b32 v64, s70, 2, v64
	v_lshl_add_u64 v[66:67], s[96:97], 0, v[64:65]
	s_waitcnt lgkmcnt(0)
	global_store_dword v[66:67], v68, off
	ds_read_b32 v66, v144 offset:35200
	v_lshl_add_u64 v[64:65], s[34:35], 0, v[64:65]
	s_waitcnt lgkmcnt(0)
	global_store_dword v[64:65], v66, off
.LBB0_1547:
	s_or_b64 exec, exec, s[8:9]
	s_waitcnt lgkmcnt(0)
	v_mov_b32_e32 v192, 0
	v_mov_b32_e32 v193, 0
	ds_read_b128 v[80:83], v188 offset:25216
	ds_read_b128 v[84:87], v188 offset:25472
	ds_read_b128 v[88:91], v188 offset:25728
	ds_read_b128 v[92:95], v188 offset:25984
	ds_read_b32 v134, v140 offset:35520
	ds_read_b32 v135, v189 offset:33408
	ds_read_b32 v132, v140 offset:35456
	ds_read_b128 v[64:67], v188 offset:17024
	ds_read_b128 v[68:71], v188 offset:17280
	ds_read_b128 v[72:75], v188 offset:17536
	ds_read_b128 v[76:79], v188 offset:17792
	ds_read_b128 v[112:115], v188 offset:26240
	ds_read_b128 v[116:119], v188 offset:26496
	ds_read_b128 v[120:123], v188 offset:26752
	ds_read_b128 v[124:127], v188 offset:27008
	ds_read_b32 v154, v140 offset:35524
	ds_read_b32 v155, v189 offset:33472
	ds_read_b32 v152, v140 offset:35460
	ds_read_b128 v[96:99], v188 offset:18048
	ds_read_b128 v[100:103], v188 offset:18304
	ds_read_b128 v[104:107], v188 offset:18560
	ds_read_b128 v[108:111], v188 offset:18816
	s_waitcnt lgkmcnt(15)
	v_mul_f32_e32 v133, v134, v135
	v_pk_mul_f32 v[80:81], v[80:81], v[132:133] op_sel:[0,1] op_sel_hi:[1,1]
	v_pk_mul_f32 v[82:83], v[82:83], v[132:133] op_sel:[0,1] op_sel_hi:[1,1]
	v_pk_mul_f32 v[84:85], v[84:85], v[132:133] op_sel:[0,1] op_sel_hi:[1,1]
	v_pk_mul_f32 v[86:87], v[86:87], v[132:133] op_sel:[0,1] op_sel_hi:[1,1]
	v_pk_mul_f32 v[88:89], v[88:89], v[132:133] op_sel:[0,1] op_sel_hi:[1,1]
	v_pk_mul_f32 v[90:91], v[90:91], v[132:133] op_sel:[0,1] op_sel_hi:[1,1]
	v_pk_mul_f32 v[92:93], v[92:93], v[132:133] op_sel:[0,1] op_sel_hi:[1,1]
	v_pk_mul_f32 v[94:95], v[94:95], v[132:133] op_sel:[0,1] op_sel_hi:[1,1]
	v_pk_fma_f32 v[196:197], v[132:133], v[196:197], v[80:81] op_sel_hi:[0,1,1]
	v_pk_fma_f32 v[198:199], v[132:133], v[198:199], v[82:83] op_sel_hi:[0,1,1]
	v_pk_fma_f32 v[200:201], v[132:133], v[200:201], v[84:85] op_sel_hi:[0,1,1]
	v_pk_fma_f32 v[202:203], v[132:133], v[202:203], v[86:87] op_sel_hi:[0,1,1]
	v_pk_fma_f32 v[204:205], v[132:133], v[204:205], v[88:89] op_sel_hi:[0,1,1]
	v_pk_fma_f32 v[206:207], v[132:133], v[206:207], v[90:91] op_sel_hi:[0,1,1]
	v_pk_fma_f32 v[208:209], v[132:133], v[208:209], v[92:93] op_sel_hi:[0,1,1]
	v_pk_fma_f32 v[210:211], v[132:133], v[210:211], v[94:95] op_sel_hi:[0,1,1]
	s_waitcnt lgkmcnt(14)
	v_pk_fma_f32 v[128:129], v[64:65], v[196:197], v[192:193]
	v_pk_fma_f32 v[130:131], v[66:67], v[198:199], v[192:193]
	s_waitcnt lgkmcnt(13)
	v_pk_fma_f32 v[128:129], v[68:69], v[200:201], v[128:129]
	v_pk_fma_f32 v[130:131], v[70:71], v[202:203], v[130:131]
	s_waitcnt lgkmcnt(12)
	v_pk_fma_f32 v[128:129], v[72:73], v[204:205], v[128:129]
	v_pk_fma_f32 v[130:131], v[74:75], v[206:207], v[130:131]
	s_waitcnt lgkmcnt(11)
	v_pk_fma_f32 v[128:129], v[76:77], v[208:209], v[128:129]
	v_pk_fma_f32 v[130:131], v[78:79], v[210:211], v[130:131]
	v_add_f32_e32 v128, v128, v129
	v_add_f32_e32 v130, v130, v131
	v_add_f32_e32 v190, v128, v130
	ds_read_b128 v[80:83], v188 offset:27264
	ds_read_b128 v[84:87], v188 offset:27520
	ds_read_b128 v[88:91], v188 offset:27776
	ds_read_b128 v[92:95], v188 offset:28032
	ds_read_b32 v134, v140 offset:35528
	ds_read_b32 v135, v189 offset:33536
	ds_read_b32 v132, v140 offset:35464
	ds_read_b128 v[64:67], v188 offset:19072
	ds_read_b128 v[68:71], v188 offset:19328
	ds_read_b128 v[72:75], v188 offset:19584
	ds_read_b128 v[76:79], v188 offset:19840
	s_waitcnt lgkmcnt(15)
	v_mul_f32_e32 v153, v154, v155
	v_pk_mul_f32 v[112:113], v[112:113], v[152:153] op_sel:[0,1] op_sel_hi:[1,1]
	v_add_f32_dpp v190, v190, v190 row_ror:8 row_mask:0xf bank_mask:0xf bound_ctrl:1
	v_pk_mul_f32 v[114:115], v[114:115], v[152:153] op_sel:[0,1] op_sel_hi:[1,1]
	v_pk_mul_f32 v[116:117], v[116:117], v[152:153] op_sel:[0,1] op_sel_hi:[1,1]
	v_add_f32_dpp v190, v190, v190 row_ror:4 row_mask:0xf bank_mask:0xf bound_ctrl:1
	v_pk_mul_f32 v[118:119], v[118:119], v[152:153] op_sel:[0,1] op_sel_hi:[1,1]
	v_pk_mul_f32 v[120:121], v[120:121], v[152:153] op_sel:[0,1] op_sel_hi:[1,1]
	v_add_f32_dpp v190, v190, v190 row_ror:2 row_mask:0xf bank_mask:0xf bound_ctrl:1
	v_pk_mul_f32 v[122:123], v[122:123], v[152:153] op_sel:[0,1] op_sel_hi:[1,1]
	v_pk_mul_f32 v[124:125], v[124:125], v[152:153] op_sel:[0,1] op_sel_hi:[1,1]
	v_add_f32_dpp v190, v190, v190 row_ror:1 row_mask:0xf bank_mask:0xf bound_ctrl:1
	v_pk_mul_f32 v[126:127], v[126:127], v[152:153] op_sel:[0,1] op_sel_hi:[1,1]
	v_pk_fma_f32 v[196:197], v[152:153], v[196:197], v[112:113] op_sel_hi:[0,1,1]
	s_and_saveexec_b64 s[8:9], s[44:45]
	ds_write_b32 v189, v190 offset:34560
	s_mov_b64 exec, s[8:9]
	v_pk_fma_f32 v[198:199], v[152:153], v[198:199], v[114:115] op_sel_hi:[0,1,1]
	v_pk_fma_f32 v[200:201], v[152:153], v[200:201], v[116:117] op_sel_hi:[0,1,1]
	v_pk_fma_f32 v[202:203], v[152:153], v[202:203], v[118:119] op_sel_hi:[0,1,1]
	v_pk_fma_f32 v[204:205], v[152:153], v[204:205], v[120:121] op_sel_hi:[0,1,1]
	v_pk_fma_f32 v[206:207], v[152:153], v[206:207], v[122:123] op_sel_hi:[0,1,1]
	v_pk_fma_f32 v[208:209], v[152:153], v[208:209], v[124:125] op_sel_hi:[0,1,1]
	v_pk_fma_f32 v[210:211], v[152:153], v[210:211], v[126:127] op_sel_hi:[0,1,1]
	s_waitcnt lgkmcnt(15)
	v_pk_fma_f32 v[128:129], v[96:97], v[196:197], v[192:193]
	v_pk_fma_f32 v[130:131], v[98:99], v[198:199], v[192:193]
	s_waitcnt lgkmcnt(14)
	v_pk_fma_f32 v[128:129], v[100:101], v[200:201], v[128:129]
	v_pk_fma_f32 v[130:131], v[102:103], v[202:203], v[130:131]
	s_waitcnt lgkmcnt(13)
	v_pk_fma_f32 v[128:129], v[104:105], v[204:205], v[128:129]
	v_pk_fma_f32 v[130:131], v[106:107], v[206:207], v[130:131]
	s_waitcnt lgkmcnt(12)
	v_pk_fma_f32 v[128:129], v[108:109], v[208:209], v[128:129]
	v_pk_fma_f32 v[130:131], v[110:111], v[210:211], v[130:131]
	v_add_f32_e32 v128, v128, v129
	v_add_f32_e32 v130, v130, v131
	v_add_f32_e32 v191, v128, v130
	ds_read_b128 v[112:115], v188 offset:28288
	ds_read_b128 v[116:119], v188 offset:28544
	ds_read_b128 v[120:123], v188 offset:28800
	ds_read_b128 v[124:127], v188 offset:29056
	ds_read_b32 v154, v140 offset:35532
	ds_read_b32 v155, v189 offset:33600
	ds_read_b32 v152, v140 offset:35468
	ds_read_b128 v[96:99], v188 offset:20096
	ds_read_b128 v[100:103], v188 offset:20352
	ds_read_b128 v[104:107], v188 offset:20608
	ds_read_b128 v[108:111], v188 offset:20864
	s_waitcnt lgkmcnt(15)
	v_mul_f32_e32 v133, v134, v135
	v_pk_mul_f32 v[80:81], v[80:81], v[132:133] op_sel:[0,1] op_sel_hi:[1,1]
	v_add_f32_dpp v191, v191, v191 row_ror:8 row_mask:0xf bank_mask:0xf bound_ctrl:1
	v_pk_mul_f32 v[82:83], v[82:83], v[132:133] op_sel:[0,1] op_sel_hi:[1,1]
	v_pk_mul_f32 v[84:85], v[84:85], v[132:133] op_sel:[0,1] op_sel_hi:[1,1]
	v_add_f32_dpp v191, v191, v191 row_ror:4 row_mask:0xf bank_mask:0xf bound_ctrl:1
	v_pk_mul_f32 v[86:87], v[86:87], v[132:133] op_sel:[0,1] op_sel_hi:[1,1]
	v_pk_mul_f32 v[88:89], v[88:89], v[132:133] op_sel:[0,1] op_sel_hi:[1,1]
	v_add_f32_dpp v191, v191, v191 row_ror:2 row_mask:0xf bank_mask:0xf bound_ctrl:1
	v_pk_mul_f32 v[90:91], v[90:91], v[132:133] op_sel:[0,1] op_sel_hi:[1,1]
	v_pk_mul_f32 v[92:93], v[92:93], v[132:133] op_sel:[0,1] op_sel_hi:[1,1]
	v_add_f32_dpp v191, v191, v191 row_ror:1 row_mask:0xf bank_mask:0xf bound_ctrl:1
	v_pk_mul_f32 v[94:95], v[94:95], v[132:133] op_sel:[0,1] op_sel_hi:[1,1]
	v_pk_fma_f32 v[196:197], v[132:133], v[196:197], v[80:81] op_sel_hi:[0,1,1]
	s_and_saveexec_b64 s[8:9], s[44:45]
	ds_write_b32 v189, v191 offset:34624
	s_mov_b64 exec, s[8:9]
	v_pk_fma_f32 v[198:199], v[132:133], v[198:199], v[82:83] op_sel_hi:[0,1,1]
	v_pk_fma_f32 v[200:201], v[132:133], v[200:201], v[84:85] op_sel_hi:[0,1,1]
	v_pk_fma_f32 v[202:203], v[132:133], v[202:203], v[86:87] op_sel_hi:[0,1,1]
	v_pk_fma_f32 v[204:205], v[132:133], v[204:205], v[88:89] op_sel_hi:[0,1,1]
	v_pk_fma_f32 v[206:207], v[132:133], v[206:207], v[90:91] op_sel_hi:[0,1,1]
	v_pk_fma_f32 v[208:209], v[132:133], v[208:209], v[92:93] op_sel_hi:[0,1,1]
	v_pk_fma_f32 v[210:211], v[132:133], v[210:211], v[94:95] op_sel_hi:[0,1,1]
	s_waitcnt lgkmcnt(15)
	v_pk_fma_f32 v[128:129], v[64:65], v[196:197], v[192:193]
	v_pk_fma_f32 v[130:131], v[66:67], v[198:199], v[192:193]
	v_pk_fma_f32 v[128:129], v[68:69], v[200:201], v[128:129]
	v_pk_fma_f32 v[130:131], v[70:71], v[202:203], v[130:131]
	s_waitcnt lgkmcnt(14)
	v_pk_fma_f32 v[128:129], v[72:73], v[204:205], v[128:129]
	v_pk_fma_f32 v[130:131], v[74:75], v[206:207], v[130:131]
	s_waitcnt lgkmcnt(13)
	v_pk_fma_f32 v[128:129], v[76:77], v[208:209], v[128:129]
	v_pk_fma_f32 v[130:131], v[78:79], v[210:211], v[130:131]
	v_add_f32_e32 v128, v128, v129
	v_add_f32_e32 v130, v130, v131
	v_add_f32_e32 v190, v128, v130
	ds_read_b128 v[80:83], v188 offset:29312
	ds_read_b128 v[84:87], v188 offset:29568
	ds_read_b128 v[88:91], v188 offset:29824
	ds_read_b128 v[92:95], v188 offset:30080
	ds_read_b32 v134, v140 offset:35536
	ds_read_b32 v135, v189 offset:33664
	ds_read_b32 v132, v140 offset:35472
	ds_read_b128 v[64:67], v188 offset:21120
	ds_read_b128 v[68:71], v188 offset:21376
	ds_read_b128 v[72:75], v188 offset:21632
	ds_read_b128 v[76:79], v188 offset:21888
	s_waitcnt lgkmcnt(15)
	v_mul_f32_e32 v153, v154, v155
	v_pk_mul_f32 v[112:113], v[112:113], v[152:153] op_sel:[0,1] op_sel_hi:[1,1]
	v_add_f32_dpp v190, v190, v190 row_ror:8 row_mask:0xf bank_mask:0xf bound_ctrl:1
	v_pk_mul_f32 v[114:115], v[114:115], v[152:153] op_sel:[0,1] op_sel_hi:[1,1]
	v_pk_mul_f32 v[116:117], v[116:117], v[152:153] op_sel:[0,1] op_sel_hi:[1,1]
	v_add_f32_dpp v190, v190, v190 row_ror:4 row_mask:0xf bank_mask:0xf bound_ctrl:1
	v_pk_mul_f32 v[118:119], v[118:119], v[152:153] op_sel:[0,1] op_sel_hi:[1,1]
	v_pk_mul_f32 v[120:121], v[120:121], v[152:153] op_sel:[0,1] op_sel_hi:[1,1]
	v_add_f32_dpp v190, v190, v190 row_ror:2 row_mask:0xf bank_mask:0xf bound_ctrl:1
	v_pk_mul_f32 v[122:123], v[122:123], v[152:153] op_sel:[0,1] op_sel_hi:[1,1]
	v_pk_mul_f32 v[124:125], v[124:125], v[152:153] op_sel:[0,1] op_sel_hi:[1,1]
	v_add_f32_dpp v190, v190, v190 row_ror:1 row_mask:0xf bank_mask:0xf bound_ctrl:1
	v_pk_mul_f32 v[126:127], v[126:127], v[152:153] op_sel:[0,1] op_sel_hi:[1,1]
	v_pk_fma_f32 v[196:197], v[152:153], v[196:197], v[112:113] op_sel_hi:[0,1,1]
	s_and_saveexec_b64 s[8:9], s[44:45]
	ds_write_b32 v189, v190 offset:34688
	s_mov_b64 exec, s[8:9]
	v_pk_fma_f32 v[198:199], v[152:153], v[198:199], v[114:115] op_sel_hi:[0,1,1]
	v_pk_fma_f32 v[200:201], v[152:153], v[200:201], v[116:117] op_sel_hi:[0,1,1]
	v_pk_fma_f32 v[202:203], v[152:153], v[202:203], v[118:119] op_sel_hi:[0,1,1]
	v_pk_fma_f32 v[204:205], v[152:153], v[204:205], v[120:121] op_sel_hi:[0,1,1]
	v_pk_fma_f32 v[206:207], v[152:153], v[206:207], v[122:123] op_sel_hi:[0,1,1]
	v_pk_fma_f32 v[208:209], v[152:153], v[208:209], v[124:125] op_sel_hi:[0,1,1]
	v_pk_fma_f32 v[210:211], v[152:153], v[210:211], v[126:127] op_sel_hi:[0,1,1]
	s_waitcnt lgkmcnt(15)
	v_pk_fma_f32 v[128:129], v[96:97], v[196:197], v[192:193]
	v_pk_fma_f32 v[130:131], v[98:99], v[198:199], v[192:193]
	v_pk_fma_f32 v[128:129], v[100:101], v[200:201], v[128:129]
	v_pk_fma_f32 v[130:131], v[102:103], v[202:203], v[130:131]
	s_waitcnt lgkmcnt(14)
	v_pk_fma_f32 v[128:129], v[104:105], v[204:205], v[128:129]
	v_pk_fma_f32 v[130:131], v[106:107], v[206:207], v[130:131]
	s_waitcnt lgkmcnt(13)
	v_pk_fma_f32 v[128:129], v[108:109], v[208:209], v[128:129]
	v_pk_fma_f32 v[130:131], v[110:111], v[210:211], v[130:131]
	v_add_f32_e32 v128, v128, v129
	v_add_f32_e32 v130, v130, v131
	v_add_f32_e32 v191, v128, v130
	ds_read_b128 v[112:115], v188 offset:30336
	ds_read_b128 v[116:119], v188 offset:30592
	ds_read_b128 v[120:123], v188 offset:30848
	ds_read_b128 v[124:127], v188 offset:31104
	ds_read_b32 v154, v140 offset:35540
	ds_read_b32 v155, v189 offset:33728
	ds_read_b32 v152, v140 offset:35476
	ds_read_b128 v[96:99], v188 offset:22144
	ds_read_b128 v[100:103], v188 offset:22400
	ds_read_b128 v[104:107], v188 offset:22656
	ds_read_b128 v[108:111], v188 offset:22912
	s_waitcnt lgkmcnt(15)
	v_mul_f32_e32 v133, v134, v135
	v_pk_mul_f32 v[80:81], v[80:81], v[132:133] op_sel:[0,1] op_sel_hi:[1,1]
	v_add_f32_dpp v191, v191, v191 row_ror:8 row_mask:0xf bank_mask:0xf bound_ctrl:1
	v_pk_mul_f32 v[82:83], v[82:83], v[132:133] op_sel:[0,1] op_sel_hi:[1,1]
	v_pk_mul_f32 v[84:85], v[84:85], v[132:133] op_sel:[0,1] op_sel_hi:[1,1]
	v_add_f32_dpp v191, v191, v191 row_ror:4 row_mask:0xf bank_mask:0xf bound_ctrl:1
	v_pk_mul_f32 v[86:87], v[86:87], v[132:133] op_sel:[0,1] op_sel_hi:[1,1]
	v_pk_mul_f32 v[88:89], v[88:89], v[132:133] op_sel:[0,1] op_sel_hi:[1,1]
	v_add_f32_dpp v191, v191, v191 row_ror:2 row_mask:0xf bank_mask:0xf bound_ctrl:1
	v_pk_mul_f32 v[90:91], v[90:91], v[132:133] op_sel:[0,1] op_sel_hi:[1,1]
	v_pk_mul_f32 v[92:93], v[92:93], v[132:133] op_sel:[0,1] op_sel_hi:[1,1]
	v_add_f32_dpp v191, v191, v191 row_ror:1 row_mask:0xf bank_mask:0xf bound_ctrl:1
	v_pk_mul_f32 v[94:95], v[94:95], v[132:133] op_sel:[0,1] op_sel_hi:[1,1]
	v_pk_fma_f32 v[196:197], v[132:133], v[196:197], v[80:81] op_sel_hi:[0,1,1]
	s_and_saveexec_b64 s[8:9], s[44:45]
	ds_write_b32 v189, v191 offset:34752
	s_mov_b64 exec, s[8:9]
	v_pk_fma_f32 v[198:199], v[132:133], v[198:199], v[82:83] op_sel_hi:[0,1,1]
	v_pk_fma_f32 v[200:201], v[132:133], v[200:201], v[84:85] op_sel_hi:[0,1,1]
	v_pk_fma_f32 v[202:203], v[132:133], v[202:203], v[86:87] op_sel_hi:[0,1,1]
	v_pk_fma_f32 v[204:205], v[132:133], v[204:205], v[88:89] op_sel_hi:[0,1,1]
	v_pk_fma_f32 v[206:207], v[132:133], v[206:207], v[90:91] op_sel_hi:[0,1,1]
	v_pk_fma_f32 v[208:209], v[132:133], v[208:209], v[92:93] op_sel_hi:[0,1,1]
	v_pk_fma_f32 v[210:211], v[132:133], v[210:211], v[94:95] op_sel_hi:[0,1,1]
	s_waitcnt lgkmcnt(15)
	v_pk_fma_f32 v[128:129], v[64:65], v[196:197], v[192:193]
	v_pk_fma_f32 v[130:131], v[66:67], v[198:199], v[192:193]
	v_pk_fma_f32 v[128:129], v[68:69], v[200:201], v[128:129]
	v_pk_fma_f32 v[130:131], v[70:71], v[202:203], v[130:131]
	s_waitcnt lgkmcnt(14)
	v_pk_fma_f32 v[128:129], v[72:73], v[204:205], v[128:129]
	v_pk_fma_f32 v[130:131], v[74:75], v[206:207], v[130:131]
	s_waitcnt lgkmcnt(13)
	v_pk_fma_f32 v[128:129], v[76:77], v[208:209], v[128:129]
	v_pk_fma_f32 v[130:131], v[78:79], v[210:211], v[130:131]
	v_add_f32_e32 v128, v128, v129
	v_add_f32_e32 v130, v130, v131
	v_add_f32_e32 v190, v128, v130
	ds_read_b128 v[80:83], v188 offset:31360
	ds_read_b128 v[84:87], v188 offset:31616
	ds_read_b128 v[88:91], v188 offset:31872
	ds_read_b128 v[92:95], v188 offset:32128
	ds_read_b32 v134, v140 offset:35544
	ds_read_b32 v135, v189 offset:33792
	ds_read_b32 v132, v140 offset:35480
	ds_read_b128 v[64:67], v188 offset:23168
	ds_read_b128 v[68:71], v188 offset:23424
	ds_read_b128 v[72:75], v188 offset:23680
	ds_read_b128 v[76:79], v188 offset:23936
	s_waitcnt lgkmcnt(15)
	v_mul_f32_e32 v153, v154, v155
	v_pk_mul_f32 v[112:113], v[112:113], v[152:153] op_sel:[0,1] op_sel_hi:[1,1]
	v_add_f32_dpp v190, v190, v190 row_ror:8 row_mask:0xf bank_mask:0xf bound_ctrl:1
	v_pk_mul_f32 v[114:115], v[114:115], v[152:153] op_sel:[0,1] op_sel_hi:[1,1]
	v_pk_mul_f32 v[116:117], v[116:117], v[152:153] op_sel:[0,1] op_sel_hi:[1,1]
	v_add_f32_dpp v190, v190, v190 row_ror:4 row_mask:0xf bank_mask:0xf bound_ctrl:1
	v_pk_mul_f32 v[118:119], v[118:119], v[152:153] op_sel:[0,1] op_sel_hi:[1,1]
	v_pk_mul_f32 v[120:121], v[120:121], v[152:153] op_sel:[0,1] op_sel_hi:[1,1]
	v_add_f32_dpp v190, v190, v190 row_ror:2 row_mask:0xf bank_mask:0xf bound_ctrl:1
	v_pk_mul_f32 v[122:123], v[122:123], v[152:153] op_sel:[0,1] op_sel_hi:[1,1]
	v_pk_mul_f32 v[124:125], v[124:125], v[152:153] op_sel:[0,1] op_sel_hi:[1,1]
	v_add_f32_dpp v190, v190, v190 row_ror:1 row_mask:0xf bank_mask:0xf bound_ctrl:1
	v_pk_mul_f32 v[126:127], v[126:127], v[152:153] op_sel:[0,1] op_sel_hi:[1,1]
	v_pk_fma_f32 v[196:197], v[152:153], v[196:197], v[112:113] op_sel_hi:[0,1,1]
	s_and_saveexec_b64 s[8:9], s[44:45]
	ds_write_b32 v189, v190 offset:34816
	s_mov_b64 exec, s[8:9]
	v_pk_fma_f32 v[198:199], v[152:153], v[198:199], v[114:115] op_sel_hi:[0,1,1]
	v_pk_fma_f32 v[200:201], v[152:153], v[200:201], v[116:117] op_sel_hi:[0,1,1]
	v_pk_fma_f32 v[202:203], v[152:153], v[202:203], v[118:119] op_sel_hi:[0,1,1]
	v_pk_fma_f32 v[204:205], v[152:153], v[204:205], v[120:121] op_sel_hi:[0,1,1]
	v_pk_fma_f32 v[206:207], v[152:153], v[206:207], v[122:123] op_sel_hi:[0,1,1]
	v_pk_fma_f32 v[208:209], v[152:153], v[208:209], v[124:125] op_sel_hi:[0,1,1]
	v_pk_fma_f32 v[210:211], v[152:153], v[210:211], v[126:127] op_sel_hi:[0,1,1]
	s_waitcnt lgkmcnt(15)
	v_pk_fma_f32 v[128:129], v[96:97], v[196:197], v[192:193]
	v_pk_fma_f32 v[130:131], v[98:99], v[198:199], v[192:193]
	v_pk_fma_f32 v[128:129], v[100:101], v[200:201], v[128:129]
	v_pk_fma_f32 v[130:131], v[102:103], v[202:203], v[130:131]
	s_waitcnt lgkmcnt(14)
	v_pk_fma_f32 v[128:129], v[104:105], v[204:205], v[128:129]
	v_pk_fma_f32 v[130:131], v[106:107], v[206:207], v[130:131]
	s_waitcnt lgkmcnt(13)
	v_pk_fma_f32 v[128:129], v[108:109], v[208:209], v[128:129]
	v_pk_fma_f32 v[130:131], v[110:111], v[210:211], v[130:131]
	v_add_f32_e32 v128, v128, v129
	v_add_f32_e32 v130, v130, v131
	v_add_f32_e32 v191, v128, v130
	ds_read_b128 v[112:115], v188 offset:32384
	ds_read_b128 v[116:119], v188 offset:32640
	ds_read_b128 v[120:123], v188 offset:32896
	ds_read_b128 v[124:127], v188 offset:33152
	ds_read_b32 v154, v140 offset:35548
	ds_read_b32 v155, v189 offset:33856
	ds_read_b32 v152, v140 offset:35484
	ds_read_b128 v[96:99], v188 offset:24192
	ds_read_b128 v[100:103], v188 offset:24448
	ds_read_b128 v[104:107], v188 offset:24704
	ds_read_b128 v[108:111], v188 offset:24960
	s_waitcnt lgkmcnt(15)
	v_mul_f32_e32 v133, v134, v135
	v_pk_mul_f32 v[80:81], v[80:81], v[132:133] op_sel:[0,1] op_sel_hi:[1,1]
	v_add_f32_dpp v191, v191, v191 row_ror:8 row_mask:0xf bank_mask:0xf bound_ctrl:1
	v_pk_mul_f32 v[82:83], v[82:83], v[132:133] op_sel:[0,1] op_sel_hi:[1,1]
	v_pk_mul_f32 v[84:85], v[84:85], v[132:133] op_sel:[0,1] op_sel_hi:[1,1]
	v_add_f32_dpp v191, v191, v191 row_ror:4 row_mask:0xf bank_mask:0xf bound_ctrl:1
	v_pk_mul_f32 v[86:87], v[86:87], v[132:133] op_sel:[0,1] op_sel_hi:[1,1]
	v_pk_mul_f32 v[88:89], v[88:89], v[132:133] op_sel:[0,1] op_sel_hi:[1,1]
	v_add_f32_dpp v191, v191, v191 row_ror:2 row_mask:0xf bank_mask:0xf bound_ctrl:1
	v_pk_mul_f32 v[90:91], v[90:91], v[132:133] op_sel:[0,1] op_sel_hi:[1,1]
	v_pk_mul_f32 v[92:93], v[92:93], v[132:133] op_sel:[0,1] op_sel_hi:[1,1]
	v_add_f32_dpp v191, v191, v191 row_ror:1 row_mask:0xf bank_mask:0xf bound_ctrl:1
	v_pk_mul_f32 v[94:95], v[94:95], v[132:133] op_sel:[0,1] op_sel_hi:[1,1]
	v_pk_fma_f32 v[196:197], v[132:133], v[196:197], v[80:81] op_sel_hi:[0,1,1]
	s_and_saveexec_b64 s[8:9], s[44:45]
	ds_write_b32 v189, v191 offset:34880
	s_mov_b64 exec, s[8:9]
	v_pk_fma_f32 v[198:199], v[132:133], v[198:199], v[82:83] op_sel_hi:[0,1,1]
	v_pk_fma_f32 v[200:201], v[132:133], v[200:201], v[84:85] op_sel_hi:[0,1,1]
	v_pk_fma_f32 v[202:203], v[132:133], v[202:203], v[86:87] op_sel_hi:[0,1,1]
	v_pk_fma_f32 v[204:205], v[132:133], v[204:205], v[88:89] op_sel_hi:[0,1,1]
	v_pk_fma_f32 v[206:207], v[132:133], v[206:207], v[90:91] op_sel_hi:[0,1,1]
	v_pk_fma_f32 v[208:209], v[132:133], v[208:209], v[92:93] op_sel_hi:[0,1,1]
	v_pk_fma_f32 v[210:211], v[132:133], v[210:211], v[94:95] op_sel_hi:[0,1,1]
	s_waitcnt lgkmcnt(15)
	v_pk_fma_f32 v[128:129], v[64:65], v[196:197], v[192:193]
	v_pk_fma_f32 v[130:131], v[66:67], v[198:199], v[192:193]
	v_pk_fma_f32 v[128:129], v[68:69], v[200:201], v[128:129]
	v_pk_fma_f32 v[130:131], v[70:71], v[202:203], v[130:131]
	s_waitcnt lgkmcnt(14)
	v_pk_fma_f32 v[128:129], v[72:73], v[204:205], v[128:129]
	v_pk_fma_f32 v[130:131], v[74:75], v[206:207], v[130:131]
	s_waitcnt lgkmcnt(13)
	v_pk_fma_f32 v[128:129], v[76:77], v[208:209], v[128:129]
	v_pk_fma_f32 v[130:131], v[78:79], v[210:211], v[130:131]
	v_add_f32_e32 v128, v128, v129
	v_add_f32_e32 v130, v130, v131
	v_add_f32_e32 v190, v128, v130
	s_waitcnt lgkmcnt(6)
	v_mul_f32_e32 v153, v154, v155
	v_pk_mul_f32 v[112:113], v[112:113], v[152:153] op_sel:[0,1] op_sel_hi:[1,1]
	v_add_f32_dpp v190, v190, v190 row_ror:8 row_mask:0xf bank_mask:0xf bound_ctrl:1
	v_pk_mul_f32 v[114:115], v[114:115], v[152:153] op_sel:[0,1] op_sel_hi:[1,1]
	v_pk_mul_f32 v[116:117], v[116:117], v[152:153] op_sel:[0,1] op_sel_hi:[1,1]
	v_add_f32_dpp v190, v190, v190 row_ror:4 row_mask:0xf bank_mask:0xf bound_ctrl:1
	v_pk_mul_f32 v[118:119], v[118:119], v[152:153] op_sel:[0,1] op_sel_hi:[1,1]
	v_pk_mul_f32 v[120:121], v[120:121], v[152:153] op_sel:[0,1] op_sel_hi:[1,1]
	v_add_f32_dpp v190, v190, v190 row_ror:2 row_mask:0xf bank_mask:0xf bound_ctrl:1
	v_pk_mul_f32 v[122:123], v[122:123], v[152:153] op_sel:[0,1] op_sel_hi:[1,1]
	v_pk_mul_f32 v[124:125], v[124:125], v[152:153] op_sel:[0,1] op_sel_hi:[1,1]
	v_add_f32_dpp v190, v190, v190 row_ror:1 row_mask:0xf bank_mask:0xf bound_ctrl:1
	v_pk_mul_f32 v[126:127], v[126:127], v[152:153] op_sel:[0,1] op_sel_hi:[1,1]
	s_waitcnt lgkmcnt(5)
	v_pk_fma_f32 v[196:197], v[152:153], v[196:197], v[112:113] op_sel_hi:[0,1,1]
	s_and_saveexec_b64 s[8:9], s[44:45]
	ds_write_b32 v189, v190 offset:34944
	s_mov_b64 exec, s[8:9]
	v_pk_fma_f32 v[198:199], v[152:153], v[198:199], v[114:115] op_sel_hi:[0,1,1]
	v_pk_fma_f32 v[200:201], v[152:153], v[200:201], v[116:117] op_sel_hi:[0,1,1]
	v_pk_fma_f32 v[202:203], v[152:153], v[202:203], v[118:119] op_sel_hi:[0,1,1]
	v_pk_fma_f32 v[204:205], v[152:153], v[204:205], v[120:121] op_sel_hi:[0,1,1]
	v_pk_fma_f32 v[206:207], v[152:153], v[206:207], v[122:123] op_sel_hi:[0,1,1]
	v_pk_fma_f32 v[208:209], v[152:153], v[208:209], v[124:125] op_sel_hi:[0,1,1]
	v_pk_fma_f32 v[210:211], v[152:153], v[210:211], v[126:127] op_sel_hi:[0,1,1]
	s_waitcnt lgkmcnt(5)
	v_pk_fma_f32 v[128:129], v[96:97], v[196:197], v[192:193]
	v_pk_fma_f32 v[130:131], v[98:99], v[198:199], v[192:193]
	s_waitcnt lgkmcnt(4)
	v_pk_fma_f32 v[128:129], v[100:101], v[200:201], v[128:129]
	v_pk_fma_f32 v[130:131], v[102:103], v[202:203], v[130:131]
	s_waitcnt lgkmcnt(3)
	v_pk_fma_f32 v[128:129], v[104:105], v[204:205], v[128:129]
	v_pk_fma_f32 v[130:131], v[106:107], v[206:207], v[130:131]
	s_waitcnt lgkmcnt(2)
	v_pk_fma_f32 v[128:129], v[108:109], v[208:209], v[128:129]
	v_pk_fma_f32 v[130:131], v[110:111], v[210:211], v[130:131]
	v_add_f32_e32 v128, v128, v129
	v_add_f32_e32 v130, v130, v131
	v_add_f32_e32 v191, v128, v130
	s_nop 1
	v_add_f32_dpp v191, v191, v191 row_ror:8 row_mask:0xf bank_mask:0xf bound_ctrl:1
	s_nop 1
	v_add_f32_dpp v191, v191, v191 row_ror:4 row_mask:0xf bank_mask:0xf bound_ctrl:1
	s_nop 1
	v_add_f32_dpp v191, v191, v191 row_ror:2 row_mask:0xf bank_mask:0xf bound_ctrl:1
	s_nop 1
	v_add_f32_dpp v191, v191, v191 row_ror:1 row_mask:0xf bank_mask:0xf bound_ctrl:1
	s_and_saveexec_b64 s[8:9], s[44:45]
	ds_write_b32 v189, v191 offset:35008
	s_mov_b64 exec, s[8:9]
	s_waitcnt lgkmcnt(0)
	v_mov_b32_e32 v64, v196
	v_mov_b32_e32 v65, v197
	v_mov_b32_e32 v66, v198
	v_mov_b32_e32 v67, v199
	v_mov_b32_e32 v76, v200
	v_mov_b32_e32 v77, v201
	v_mov_b32_e32 v78, v202
	v_mov_b32_e32 v79, v203
	v_mov_b32_e32 v72, v204
	v_mov_b32_e32 v73, v205
	v_mov_b32_e32 v74, v206
	v_mov_b32_e32 v75, v207
	v_mov_b32_e32 v68, v208
	v_mov_b32_e32 v69, v209
	v_mov_b32_e32 v70, v210
	v_mov_b32_e32 v71, v211
	s_branch .LBB0_1438
